# M0NOP: 64 s_nop wait states between M0 writes and LDS-DMA loads in the GEMM main loops replaced by reordering the address computation behind the M0 write; on top of NOPRIO
# speedup vs baseline: 1.0043x; 1.0034x over previous
; #define PG8_STAGE(bufoff, gbase, voff) do { _Pragma("unroll") for (int _i = 0; _i < 2; ++_i) \
;         __builtin_amdgcn_global_load_lds((const unsigned*)((const char*)(gbase) + (voff)[_i]), (PG8_LAS unsigned*)(lds + (bufoff) + ldsw + _i * 8192), 16, 0, 0); } while (0)
; #define PG8_LDA(dst, b, h) do { _Pragma("unroll") for (int m = 0; m < 4; ++m) _Pragma("unroll") for (int k = 0; k < 2; ++k) dst[m][k] = *(const PG8_LAS bf16x8*)(lds + PG8_SA(b, h) + aoff + m * 2048 + k * 1024); } while (0)
; #define PG8_LDB(dst, b, h) do { _Pragma("unroll") for (int n = 0; n < 2; ++n) _Pragma("unroll") for (int k = 0; k < 2; ++k) dst[n][k] = *(const PG8_LAS bf16x8*)(lds + PG8_SB(b, h) + boff + n * 2048 + k * 1024); } while (0)
; #define PG8_MMA(ai, bj, At, Bt) do { __builtin_amdgcn_s_setprio(1); _Pragma("unroll") for (int m = 0; m < 4; ++m) _Pragma("unroll") for (int n = 0; n < 2; ++n) _Pragma("unroll") for (int k = 0; k < 2; ++k) \
;         acc[ai][bj][m][n] = __builtin_amdgcn_mfma_f32_16x16x32_bf16(Bt[n][k], At[m][k], acc[ai][bj][m][n], 0, 0, 0); __builtin_amdgcn_s_setprio(0); } while (0)
; #define PG8_WAIT_L(n) asm volatile("s_waitcnt lgkmcnt(" #n ")" ::: "memory")
; #define PG8_BAR __builtin_amdgcn_s_barrier()
; #define PG8_SCHED __builtin_amdgcn_sched_barrier(0)
; template <class Epi, class Sched>
; __device__ __forceinline__ void gemm_phase(PG8_LAS unsigned char* lds, const Gemm g, const Sched& S, const Epi& E, int tid_in) {
;     ...
;         for (int t = 0; t < nt; t += 2) {
;             const bool last = (t == nt - 2);
;             const char* a1 = cA + (size_t)(t + 1) * kstep;
;             const char* a2 = last ? nA : cA + (size_t)(t + 2) * kstep; const char* b2 = last ? nB : cB + (size_t)(t + 2) * kstep;
;             const char* a3 = a2 + kstep; const char* b3 = b2 + kstep;
;             if (last && has_next) S.a_ready(nxt);
;             PG8_LDB(B0, 0, 0); PG8_SCHED; PG8_LDA(At, 0, 0); PG8_STAGE(PG8_SA(1, 1), a1 + hstep, voffA);
;             PG8_WAIT_L(8); PG8_BAR; PG8_WAIT_L(0); PG8_MMA(0, 0, At, B0); PG8_BAR; PG8_SCHED;
;             PG8_LDB(B1, 0, 1); PG8_STAGE(PG8_SB(0, 0), b2, voffB);
;             PG8_BAR; PG8_WAIT_L(0); PG8_MMA(0, 1, At, B1); PG8_BAR;
;             PG8_LDA(At, 0, 1); PG8_STAGE(PG8_SA(0, 0), a2, voffA);
;             PG8_BAR; PG8_WAIT_L(0); PG8_MMA(1, 0, At, B0); PG8_BAR; PG8_SCHED;
.LBB0_266:
	s_add_u32 s28, s4, 0x100
	s_addc_u32 s29, s5, 0
	s_add_i32 s58, 0, 0x10000
	v_add_u32_e32 v136, s58, v151
	ds_read_b128 v[128:131], v136
	ds_read_b128 v[132:135], v136 offset:1024
	ds_read_b128 v[144:147], v136 offset:2048
	ds_read_b128 v[154:157], v136 offset:3072
	s_cmp_eq_u32 s56, 60
	s_cselect_b32 s79, s15, s29
	s_cselect_b32 s78, s52, s28
	s_cselect_b32 s31, s13, s55
	s_cselect_b32 s30, s53, s54
	v_lshl_add_u64 v[136:137], s[4:5], 0, v[140:141]
	s_add_i32 m0, s27, 0xc000
	ds_read_b128 v[158:161], v153
	ds_read_b128 v[162:165], v153 offset:1024
	ds_read_b128 v[166:169], v153 offset:2048
	ds_read_b128 v[170:173], v153 offset:3072
	ds_read_b128 v[174:177], v153 offset:4096
	ds_read_b128 v[178:181], v153 offset:5120
	ds_read_b128 v[182:185], v153 offset:6144
	ds_read_b128 v[186:189], v153 offset:7168
	global_load_lds_dwordx4 v[136:137], off
	s_add_i32 m0, s27, 0xe000
	v_lshl_add_u64 v[136:137], s[4:5], 0, v[142:143]
	global_load_lds_dwordx4 v[136:137], off
	s_waitcnt lgkmcnt(8)
	s_barrier
	s_waitcnt lgkmcnt(0)
	s_waitcnt lgkmcnt(0)
	v_mfma_f32_16x16x32_bf16 v[124:127], v[128:131], v[158:161], v[124:127]
	v_mfma_f32_16x16x32_bf16 v[96:99], v[144:147], v[158:161], v[96:99]
	v_mfma_f32_16x16x32_bf16 v[120:123], v[128:131], v[166:169], v[120:123]
	v_mfma_f32_16x16x32_bf16 v[88:91], v[144:147], v[166:169], v[88:91]
	v_mfma_f32_16x16x32_bf16 v[116:119], v[128:131], v[174:177], v[116:119]
	v_mfma_f32_16x16x32_bf16 v[84:87], v[144:147], v[174:177], v[84:87]
	v_mfma_f32_16x16x32_bf16 v[112:115], v[128:131], v[182:185], v[112:115]
	v_mfma_f32_16x16x32_bf16 v[80:83], v[144:147], v[182:185], v[80:83]
	v_mfma_f32_16x16x32_bf16 v[124:127], v[132:135], v[162:165], v[124:127]
	v_mfma_f32_16x16x32_bf16 v[96:99], v[154:157], v[162:165], v[96:99]
	v_mfma_f32_16x16x32_bf16 v[120:123], v[132:135], v[170:173], v[120:123]
	v_mfma_f32_16x16x32_bf16 v[88:91], v[154:157], v[170:173], v[88:91]
	v_mfma_f32_16x16x32_bf16 v[116:119], v[132:135], v[178:181], v[116:119]
	v_mfma_f32_16x16x32_bf16 v[84:87], v[154:157], v[178:181], v[84:87]
	v_mfma_f32_16x16x32_bf16 v[112:115], v[132:135], v[186:189], v[112:115]
	v_mfma_f32_16x16x32_bf16 v[80:83], v[154:157], v[186:189], v[80:83]
	s_barrier
	s_add_i32 s59, 0, 0x14000
	v_add_u32_e32 v136, s59, v151
	s_add_i32 s4, s58, s33
	ds_read_b128 v[194:197], v136
	ds_read_b128 v[200:203], v136 offset:1024
	ds_read_b128 v[204:207], v136 offset:2048
	ds_read_b128 v[208:211], v136 offset:3072
	v_lshl_add_u64 v[136:137], s[30:31], 0, v[192:193]
	s_mov_b32 m0, s4
	v_lshl_add_u64 v[148:149], s[30:31], 0, v[138:139]
	global_load_lds_dwordx4 v[136:137], off
	s_add_i32 m0, s4, 0x2000
	s_nop 0
	global_load_lds_dwordx4 v[148:149], off
	s_barrier
	s_waitcnt lgkmcnt(0)
	s_waitcnt lgkmcnt(0)
	v_mfma_f32_16x16x32_bf16 v[64:67], v[194:197], v[158:161], v[64:67]
	v_mfma_f32_16x16x32_bf16 v[36:39], v[204:207], v[158:161], v[36:39]
	v_mfma_f32_16x16x32_bf16 v[56:59], v[194:197], v[166:169], v[56:59]
	v_mfma_f32_16x16x32_bf16 v[28:31], v[204:207], v[166:169], v[28:31]
	v_mfma_f32_16x16x32_bf16 v[52:55], v[194:197], v[174:177], v[52:55]
	v_mfma_f32_16x16x32_bf16 v[20:23], v[204:207], v[174:177], v[20:23]
	v_mfma_f32_16x16x32_bf16 v[48:51], v[194:197], v[182:185], v[48:51]
	v_mfma_f32_16x16x32_bf16 v[16:19], v[204:207], v[182:185], v[16:19]
	v_mfma_f32_16x16x32_bf16 v[64:67], v[200:203], v[162:165], v[64:67]
	v_mfma_f32_16x16x32_bf16 v[36:39], v[208:211], v[162:165], v[36:39]
	v_mfma_f32_16x16x32_bf16 v[56:59], v[200:203], v[170:173], v[56:59]
	v_mfma_f32_16x16x32_bf16 v[28:31], v[208:211], v[170:173], v[28:31]
	v_mfma_f32_16x16x32_bf16 v[52:55], v[200:203], v[178:181], v[52:55]
	v_mfma_f32_16x16x32_bf16 v[20:23], v[208:211], v[178:181], v[20:23]
	v_mfma_f32_16x16x32_bf16 v[48:51], v[200:203], v[186:189], v[48:51]
	v_mfma_f32_16x16x32_bf16 v[16:19], v[208:211], v[186:189], v[16:19]
	s_mov_b32 m0, s27
	v_lshl_add_u64 v[190:191], s[78:79], 0, v[192:193]
	s_barrier
	ds_read_b128 v[158:161], v153 offset:16384
	ds_read_b128 v[162:165], v153 offset:17408
	ds_read_b128 v[166:169], v153 offset:18432
	ds_read_b128 v[170:173], v153 offset:19456
	ds_read_b128 v[174:177], v153 offset:20480
	ds_read_b128 v[178:181], v153 offset:21504
	ds_read_b128 v[182:185], v153 offset:22528
	ds_read_b128 v[186:189], v153 offset:23552
	global_load_lds_dwordx4 v[190:191], off
	s_mov_b32 m0, s42
	v_lshl_add_u64 v[212:213], s[78:79], 0, v[138:139]
	global_load_lds_dwordx4 v[212:213], off
	s_barrier
	s_waitcnt lgkmcnt(0)
	s_waitcnt lgkmcnt(0)
	v_mfma_f32_16x16x32_bf16 v[108:111], v[128:131], v[158:161], v[108:111]
	v_mfma_f32_16x16x32_bf16 v[76:79], v[144:147], v[158:161], v[76:79]
	v_mfma_f32_16x16x32_bf16 v[104:107], v[128:131], v[166:169], v[104:107]
	v_mfma_f32_16x16x32_bf16 v[72:75], v[144:147], v[166:169], v[72:75]
	v_mfma_f32_16x16x32_bf16 v[100:103], v[128:131], v[174:177], v[100:103]
	v_mfma_f32_16x16x32_bf16 v[68:71], v[144:147], v[174:177], v[68:71]
	v_mfma_f32_16x16x32_bf16 v[92:95], v[128:131], v[182:185], v[92:95]
	v_mfma_f32_16x16x32_bf16 v[60:63], v[144:147], v[182:185], v[60:63]
	v_mfma_f32_16x16x32_bf16 v[108:111], v[132:135], v[162:165], v[108:111]
	v_mfma_f32_16x16x32_bf16 v[76:79], v[154:157], v[162:165], v[76:79]
	v_mfma_f32_16x16x32_bf16 v[104:107], v[132:135], v[170:173], v[104:107]
	v_mfma_f32_16x16x32_bf16 v[72:75], v[154:157], v[170:173], v[72:75]
	v_mfma_f32_16x16x32_bf16 v[100:103], v[132:135], v[178:181], v[100:103]
	v_mfma_f32_16x16x32_bf16 v[68:71], v[154:157], v[178:181], v[68:71]
	v_mfma_f32_16x16x32_bf16 v[92:95], v[132:135], v[186:189], v[92:95]
	v_mfma_f32_16x16x32_bf16 v[60:63], v[154:157], v[186:189], v[60:63]
	s_barrier
; #define PG8_STAGE(bufoff, gbase, voff) do { _Pragma("unroll") for (int _i = 0; _i < 2; ++_i) \
;         __builtin_amdgcn_global_load_lds((const unsigned*)((const char*)(gbase) + (voff)[_i]), (PG8_LAS unsigned*)(lds + (bufoff) + ldsw + _i * 8192), 16, 0, 0); } while (0)
; #define PG8_LDA(dst, b, h) do { _Pragma("unroll") for (int m = 0; m < 4; ++m) _Pragma("unroll") for (int k = 0; k < 2; ++k) dst[m][k] = *(const PG8_LAS bf16x8*)(lds + PG8_SA(b, h) + aoff + m * 2048 + k * 1024); } while (0)
; #define PG8_LDB(dst, b, h) do { _Pragma("unroll") for (int n = 0; n < 2; ++n) _Pragma("unroll") for (int k = 0; k < 2; ++k) dst[n][k] = *(const PG8_LAS bf16x8*)(lds + PG8_SB(b, h) + boff + n * 2048 + k * 1024); } while (0)
; #define PG8_MMA(ai, bj, At, Bt) do { __builtin_amdgcn_s_setprio(1); _Pragma("unroll") for (int m = 0; m < 4; ++m) _Pragma("unroll") for (int n = 0; n < 2; ++n) _Pragma("unroll") for (int k = 0; k < 2; ++k) \
;         acc[ai][bj][m][n] = __builtin_amdgcn_mfma_f32_16x16x32_bf16(Bt[n][k], At[m][k], acc[ai][bj][m][n], 0, 0, 0); __builtin_amdgcn_s_setprio(0); } while (0)
; #define PG8_WAIT_V(n) asm volatile("s_waitcnt vmcnt(" #n ")" ::: "memory")
; #define PG8_WAIT_L(n) asm volatile("s_waitcnt lgkmcnt(" #n ")" ::: "memory")
; #define PG8_BAR __builtin_amdgcn_s_barrier()
; #define PG8_SCHED __builtin_amdgcn_sched_barrier(0)
; template <class Epi, class Sched>
; __device__ __forceinline__ void gemm_phase(PG8_LAS unsigned char* lds, const Gemm g, const Sched& S, const Epi& E, int tid_in) {
;     ...
;             PG8_STAGE(PG8_SB(0, 1), b2 + hstep, voffB);
;             PG8_WAIT_V(6); PG8_BAR; PG8_MMA(1, 1, At, B1); PG8_BAR;
;             PG8_LDB(B0, 1, 0); PG8_SCHED; PG8_LDA(At, 1, 0); PG8_STAGE(PG8_SA(0, 1), a2 + hstep, voffA);
;             PG8_WAIT_L(8); PG8_BAR; PG8_WAIT_L(0); PG8_MMA(0, 0, At, B0); PG8_BAR; PG8_SCHED;
;             PG8_LDB(B1, 1, 1); PG8_STAGE(PG8_SB(1, 0), b3, voffB);
;             PG8_BAR; PG8_WAIT_L(0); PG8_MMA(0, 1, At, B1); PG8_BAR;
;             PG8_LDA(At, 1, 1); PG8_STAGE(PG8_SA(1, 0), a3, voffA);
	s_add_u32 s4, s30, 0x100000
	s_addc_u32 s5, s31, 0
	s_add_i32 s58, s59, s33
	s_mov_b32 m0, s58
	v_lshl_add_u64 v[128:129], s[4:5], 0, v[192:193]
	global_load_lds_dwordx4 v[128:129], off
	s_add_i32 m0, s58, 0x2000
	v_lshl_add_u64 v[128:129], s[4:5], 0, v[138:139]
	global_load_lds_dwordx4 v[128:129], off
	s_waitcnt vmcnt(6)
	s_barrier
	v_mfma_f32_16x16x32_bf16 v[44:47], v[194:197], v[158:161], v[44:47]
	v_mfma_f32_16x16x32_bf16 v[12:15], v[204:207], v[158:161], v[12:15]
	v_mfma_f32_16x16x32_bf16 v[40:43], v[194:197], v[166:169], v[40:43]
	v_mfma_f32_16x16x32_bf16 v[8:11], v[204:207], v[166:169], v[8:11]
	v_mfma_f32_16x16x32_bf16 v[32:35], v[194:197], v[174:177], v[32:35]
	v_mfma_f32_16x16x32_bf16 v[4:7], v[204:207], v[174:177], v[4:7]
	v_mfma_f32_16x16x32_bf16 v[24:27], v[194:197], v[182:185], v[24:27]
	v_mfma_f32_16x16x32_bf16 v[0:3], v[204:207], v[182:185], v[0:3]
	v_mfma_f32_16x16x32_bf16 v[44:47], v[200:203], v[162:165], v[44:47]
	v_mfma_f32_16x16x32_bf16 v[12:15], v[208:211], v[162:165], v[12:15]
	v_mfma_f32_16x16x32_bf16 v[40:43], v[200:203], v[170:173], v[40:43]
	v_mfma_f32_16x16x32_bf16 v[8:11], v[208:211], v[170:173], v[8:11]
	v_mfma_f32_16x16x32_bf16 v[32:35], v[200:203], v[178:181], v[32:35]
	v_mfma_f32_16x16x32_bf16 v[4:7], v[208:211], v[178:181], v[4:7]
	v_mfma_f32_16x16x32_bf16 v[24:27], v[200:203], v[186:189], v[24:27]
	v_mfma_f32_16x16x32_bf16 v[0:3], v[208:211], v[186:189], v[0:3]
	s_add_i32 s58, 0, 0x18000
	v_add_u32_e32 v154, s58, v151
	s_barrier
	ds_read_b128 v[128:131], v154
	ds_read_b128 v[132:135], v154 offset:1024
	ds_read_b128 v[144:147], v154 offset:2048
	ds_read_b128 v[154:157], v154 offset:3072
	s_add_u32 s4, s78, 0x100000
	s_addc_u32 s5, s79, 0
	s_mov_b32 m0, s43
	v_lshl_add_u64 v[194:195], s[4:5], 0, v[192:193]
	ds_read_b128 v[158:161], v153 offset:32768
	ds_read_b128 v[162:165], v153 offset:33792
	ds_read_b128 v[166:169], v153 offset:34816
	ds_read_b128 v[170:173], v153 offset:35840
	ds_read_b128 v[174:177], v153 offset:36864
	ds_read_b128 v[178:181], v153 offset:37888
	ds_read_b128 v[182:185], v153 offset:38912
	ds_read_b128 v[186:189], v153 offset:39936
	global_load_lds_dwordx4 v[194:195], off
	s_mov_b32 m0, s44
	v_lshl_add_u64 v[194:195], s[4:5], 0, v[138:139]
	global_load_lds_dwordx4 v[194:195], off
	s_waitcnt lgkmcnt(8)
	s_barrier
	s_waitcnt lgkmcnt(0)
	s_waitcnt lgkmcnt(0)
	v_mfma_f32_16x16x32_bf16 v[124:127], v[128:131], v[158:161], v[124:127]
	v_mfma_f32_16x16x32_bf16 v[96:99], v[144:147], v[158:161], v[96:99]
	v_mfma_f32_16x16x32_bf16 v[120:123], v[128:131], v[166:169], v[120:123]
	v_mfma_f32_16x16x32_bf16 v[88:91], v[144:147], v[166:169], v[88:91]
	v_mfma_f32_16x16x32_bf16 v[116:119], v[128:131], v[174:177], v[116:119]
	v_mfma_f32_16x16x32_bf16 v[84:87], v[144:147], v[174:177], v[84:87]
	v_mfma_f32_16x16x32_bf16 v[112:115], v[128:131], v[182:185], v[112:115]
	v_mfma_f32_16x16x32_bf16 v[80:83], v[144:147], v[182:185], v[80:83]
	v_mfma_f32_16x16x32_bf16 v[124:127], v[132:135], v[162:165], v[124:127]
	v_mfma_f32_16x16x32_bf16 v[96:99], v[154:157], v[162:165], v[96:99]
	v_mfma_f32_16x16x32_bf16 v[120:123], v[132:135], v[170:173], v[120:123]
	v_mfma_f32_16x16x32_bf16 v[88:91], v[154:157], v[170:173], v[88:91]
	v_mfma_f32_16x16x32_bf16 v[116:119], v[132:135], v[178:181], v[116:119]
	v_mfma_f32_16x16x32_bf16 v[84:87], v[154:157], v[178:181], v[84:87]
	v_mfma_f32_16x16x32_bf16 v[112:115], v[132:135], v[186:189], v[112:115]
	v_mfma_f32_16x16x32_bf16 v[80:83], v[154:157], v[186:189], v[80:83]
	s_barrier
	s_add_i32 s59, 0, 0x1c000
	s_add_i32 s4, s58, s33
	v_add_u32_e32 v199, s59, v151
	v_lshl_add_u64 v[136:137], v[136:137], 0, s[74:75]
	s_mov_b32 m0, s4
	ds_read_b128 v[194:197], v199
	ds_read_b128 v[200:203], v199 offset:1024
	ds_read_b128 v[204:207], v199 offset:2048
	ds_read_b128 v[208:211], v199 offset:3072
	global_load_lds_dwordx4 v[136:137], off
	s_add_i32 m0, s4, 0x2000
	v_lshl_add_u64 v[136:137], v[148:149], 0, s[74:75]
	global_load_lds_dwordx4 v[136:137], off
	s_barrier
	s_waitcnt lgkmcnt(0)
	s_waitcnt lgkmcnt(0)
	v_mfma_f32_16x16x32_bf16 v[64:67], v[194:197], v[158:161], v[64:67]
	v_mfma_f32_16x16x32_bf16 v[36:39], v[204:207], v[158:161], v[36:39]
	v_mfma_f32_16x16x32_bf16 v[56:59], v[194:197], v[166:169], v[56:59]
	v_mfma_f32_16x16x32_bf16 v[28:31], v[204:207], v[166:169], v[28:31]
	v_mfma_f32_16x16x32_bf16 v[52:55], v[194:197], v[174:177], v[52:55]
	v_mfma_f32_16x16x32_bf16 v[20:23], v[204:207], v[174:177], v[20:23]
	v_mfma_f32_16x16x32_bf16 v[48:51], v[194:197], v[182:185], v[48:51]
	v_mfma_f32_16x16x32_bf16 v[16:19], v[204:207], v[182:185], v[16:19]
	v_mfma_f32_16x16x32_bf16 v[64:67], v[200:203], v[162:165], v[64:67]
	v_mfma_f32_16x16x32_bf16 v[36:39], v[208:211], v[162:165], v[36:39]
	v_mfma_f32_16x16x32_bf16 v[56:59], v[200:203], v[170:173], v[56:59]
	v_mfma_f32_16x16x32_bf16 v[28:31], v[208:211], v[170:173], v[28:31]
	v_mfma_f32_16x16x32_bf16 v[52:55], v[200:203], v[178:181], v[52:55]
	v_mfma_f32_16x16x32_bf16 v[20:23], v[208:211], v[178:181], v[20:23]
	v_mfma_f32_16x16x32_bf16 v[48:51], v[200:203], v[186:189], v[48:51]
	v_mfma_f32_16x16x32_bf16 v[16:19], v[208:211], v[186:189], v[16:19]
	s_mov_b32 m0, s48
	v_lshl_add_u64 v[136:137], v[190:191], 0, s[74:75]
	s_barrier
; #define PG8_STAGE(bufoff, gbase, voff) do { _Pragma("unroll") for (int _i = 0; _i < 2; ++_i) \
;         __builtin_amdgcn_global_load_lds((const unsigned*)((const char*)(gbase) + (voff)[_i]), (PG8_LAS unsigned*)(lds + (bufoff) + ldsw + _i * 8192), 16, 0, 0); } while (0)
; #define PG8_LDA(dst, b, h) do { _Pragma("unroll") for (int m = 0; m < 4; ++m) _Pragma("unroll") for (int k = 0; k < 2; ++k) dst[m][k] = *(const PG8_LAS bf16x8*)(lds + PG8_SA(b, h) + aoff + m * 2048 + k * 1024); } while (0)
; #define PG8_MMA(ai, bj, At, Bt) do { __builtin_amdgcn_s_setprio(1); _Pragma("unroll") for (int m = 0; m < 4; ++m) _Pragma("unroll") for (int n = 0; n < 2; ++n) _Pragma("unroll") for (int k = 0; k < 2; ++k) \
;         acc[ai][bj][m][n] = __builtin_amdgcn_mfma_f32_16x16x32_bf16(Bt[n][k], At[m][k], acc[ai][bj][m][n], 0, 0, 0); __builtin_amdgcn_s_setprio(0); } while (0)
; #define PG8_WAIT_V(n) asm volatile("s_waitcnt vmcnt(" #n ")" ::: "memory")
; #define PG8_WAIT_L(n) asm volatile("s_waitcnt lgkmcnt(" #n ")" ::: "memory")
; #define PG8_BAR __builtin_amdgcn_s_barrier()
; #define PG8_SCHED __builtin_amdgcn_sched_barrier(0)
; template <class Epi, class Sched>
; __device__ __forceinline__ void gemm_phase(PG8_LAS unsigned char* lds, const Gemm g, const Sched& S, const Epi& E, int tid_in) {
;     ...
;             PG8_LDA(At, 1, 1); PG8_STAGE(PG8_SA(1, 0), a3, voffA);
;             PG8_BAR; PG8_WAIT_L(0); PG8_MMA(1, 0, At, B0); PG8_BAR; PG8_SCHED;
;             PG8_STAGE(PG8_SB(1, 1), b3 + hstep, voffB);
;             PG8_WAIT_V(6); PG8_BAR; PG8_MMA(1, 1, At, B1); PG8_BAR;
;         }
;     __device__ __forceinline__ void operator()(f32x4 (&acc)[2][2][4][2], const Unit& u, int wr, int wc, int fr, int fq) const {
;         const int row0 = u.pm * 256 + wr * 64 + fr, col0 = u.pn * 256 + wc * 32 + 4 * fq;
;         const float* gr = gate + (size_t)(bbase + (u.pm * 256) / SEQ) * MODW;
; #pragma unroll
;         for (int bj = 0; bj < 2; ++bj)
; #pragma unroll
;             for (int n = 0; n < 2; ++n) { const int col = col0 + bj * 128 + n * 16; const f32x4 gv = *(const f32x4*)(gr + col);
;                 f32x4 bv = (f32x4){0.f, 0.f, 0.f, 0.f}; if (bias) bv = *(const f32x4*)(bias + col);
	ds_read_b128 v[158:161], v153 offset:49152
	ds_read_b128 v[162:165], v153 offset:50176
	ds_read_b128 v[166:169], v153 offset:51200
	ds_read_b128 v[170:173], v153 offset:52224
	ds_read_b128 v[174:177], v153 offset:53248
	ds_read_b128 v[178:181], v153 offset:54272
	ds_read_b128 v[182:185], v153 offset:55296
	ds_read_b128 v[186:189], v153 offset:56320
	global_load_lds_dwordx4 v[136:137], off
	s_mov_b32 m0, s49
	v_lshl_add_u64 v[136:137], v[212:213], 0, s[74:75]
	global_load_lds_dwordx4 v[136:137], off
	s_barrier
	s_waitcnt lgkmcnt(0)
	s_waitcnt lgkmcnt(0)
	v_mfma_f32_16x16x32_bf16 v[108:111], v[128:131], v[158:161], v[108:111]
	v_mfma_f32_16x16x32_bf16 v[76:79], v[144:147], v[158:161], v[76:79]
	v_mfma_f32_16x16x32_bf16 v[104:107], v[128:131], v[166:169], v[104:107]
	v_mfma_f32_16x16x32_bf16 v[72:75], v[144:147], v[166:169], v[72:75]
	v_mfma_f32_16x16x32_bf16 v[100:103], v[128:131], v[174:177], v[100:103]
	v_mfma_f32_16x16x32_bf16 v[68:71], v[144:147], v[174:177], v[68:71]
	v_mfma_f32_16x16x32_bf16 v[92:95], v[128:131], v[182:185], v[92:95]
	v_mfma_f32_16x16x32_bf16 v[60:63], v[144:147], v[182:185], v[60:63]
	v_mfma_f32_16x16x32_bf16 v[108:111], v[132:135], v[162:165], v[108:111]
	v_mfma_f32_16x16x32_bf16 v[76:79], v[154:157], v[162:165], v[76:79]
	v_mfma_f32_16x16x32_bf16 v[104:107], v[132:135], v[170:173], v[104:107]
	v_mfma_f32_16x16x32_bf16 v[72:75], v[154:157], v[170:173], v[72:75]
	v_mfma_f32_16x16x32_bf16 v[100:103], v[132:135], v[178:181], v[100:103]
	v_mfma_f32_16x16x32_bf16 v[68:71], v[154:157], v[178:181], v[68:71]
	v_mfma_f32_16x16x32_bf16 v[92:95], v[132:135], v[186:189], v[92:95]
	v_mfma_f32_16x16x32_bf16 v[60:63], v[154:157], v[186:189], v[60:63]
	s_barrier
	s_add_u32 s4, s30, 0x100080
	s_addc_u32 s5, s31, 0
	s_add_i32 s30, s59, s33
	s_mov_b32 m0, s30
	v_lshl_add_u64 v[128:129], s[4:5], 0, v[192:193]
	global_load_lds_dwordx4 v[128:129], off
	s_add_i32 m0, s30, 0x2000
	v_lshl_add_u64 v[128:129], s[4:5], 0, v[138:139]
	global_load_lds_dwordx4 v[128:129], off
	s_waitcnt vmcnt(6)
	s_barrier
	v_mfma_f32_16x16x32_bf16 v[44:47], v[194:197], v[158:161], v[44:47]
	v_mfma_f32_16x16x32_bf16 v[12:15], v[204:207], v[158:161], v[12:15]
	v_mfma_f32_16x16x32_bf16 v[40:43], v[194:197], v[166:169], v[40:43]
	v_mfma_f32_16x16x32_bf16 v[8:11], v[204:207], v[166:169], v[8:11]
	v_mfma_f32_16x16x32_bf16 v[32:35], v[194:197], v[174:177], v[32:35]
	v_mfma_f32_16x16x32_bf16 v[4:7], v[204:207], v[174:177], v[4:7]
	v_mfma_f32_16x16x32_bf16 v[24:27], v[194:197], v[182:185], v[24:27]
	v_mfma_f32_16x16x32_bf16 v[0:3], v[204:207], v[182:185], v[0:3]
	v_mfma_f32_16x16x32_bf16 v[44:47], v[200:203], v[162:165], v[44:47]
	v_mfma_f32_16x16x32_bf16 v[12:15], v[208:211], v[162:165], v[12:15]
	v_mfma_f32_16x16x32_bf16 v[40:43], v[200:203], v[170:173], v[40:43]
	v_mfma_f32_16x16x32_bf16 v[8:11], v[208:211], v[170:173], v[8:11]
	v_mfma_f32_16x16x32_bf16 v[32:35], v[200:203], v[178:181], v[32:35]
	v_mfma_f32_16x16x32_bf16 v[4:7], v[208:211], v[178:181], v[4:7]
	v_mfma_f32_16x16x32_bf16 v[24:27], v[200:203], v[186:189], v[24:27]
	v_mfma_f32_16x16x32_bf16 v[0:3], v[208:211], v[186:189], v[0:3]
	s_add_i32 s56, s56, 2
	s_add_u32 s54, s54, 0x100
	s_addc_u32 s55, s55, 0
	s_cmp_gt_u32 s56, 61
	s_mov_b64 s[4:5], s[28:29]
	s_barrier
	s_cbranch_scc0 .LBB0_266
	s_ashr_i32 s4, s26, 31
	s_lshr_b32 s4, s4, 29
	s_add_i32 s4, s26, s4
	s_ashr_i32 s4, s4, 3
	s_add_i32 s4, s4, s76
	s_mul_hi_i32 s5, s4, 0x6000
	s_mulk_i32 s4, 0x6000
	v_lshl_or_b32 v148, s51, 8, v152
	s_add_u32 s4, s45, s4
	s_addc_u32 s5, s46, s5
	v_ashrrev_i32_e32 v149, 31, v148
	v_lshl_add_u64 v[146:147], v[148:149], 2, s[4:5]
	global_load_dwordx4 v[130:133], v[146:147], off
	global_load_dwordx4 v[158:161], v[146:147], off offset:64
	global_load_dwordx4 v[162:165], v[146:147], off offset:512
	global_load_dwordx4 v[166:169], v[146:147], off offset:576
	v_cndmask_b32_e64 v129, 0, 1, s[10:11]
	v_mov_b32_e32 v128, 0
	v_cmp_ne_u32_e64 s[4:5], 1, v129
	s_andn2_b64 vcc, exec, s[10:11]
	v_lshl_add_u64 v[144:145], v[148:149], 2, s[8:9]
	v_mov_b32_e32 v134, 0
	v_mov_b32_e32 v135, 0
	v_mov_b32_e32 v136, 0
	v_mov_b32_e32 v137, 0
	s_cbranch_vccnz .LBB0_269
	global_load_dwordx4 v[134:137], v[144:145], off
	global_load_dwordx4 v[170:173], v[144:145], off offset:64
	global_load_dwordx4 v[174:177], v[144:145], off offset:512
	global_load_dwordx4 v[178:181], v[144:145], off offset:576

; #define PG8_STAGE(bufoff, gbase, voff) do { _Pragma("unroll") for (int _i = 0; _i < 2; ++_i) \
;         __builtin_amdgcn_global_load_lds((const unsigned*)((const char*)(gbase) + (voff)[_i]), (PG8_LAS unsigned*)(lds + (bufoff) + ldsw + _i * 8192), 16, 0, 0); } while (0)
; #define PG8_LDA(dst, b, h) do { _Pragma("unroll") for (int m = 0; m < 4; ++m) _Pragma("unroll") for (int k = 0; k < 2; ++k) dst[m][k] = *(const PG8_LAS bf16x8*)(lds + PG8_SA(b, h) + aoff + m * 2048 + k * 1024); } while (0)
; #define PG8_LDB(dst, b, h) do { _Pragma("unroll") for (int n = 0; n < 2; ++n) _Pragma("unroll") for (int k = 0; k < 2; ++k) dst[n][k] = *(const PG8_LAS bf16x8*)(lds + PG8_SB(b, h) + boff + n * 2048 + k * 1024); } while (0)
; #define PG8_MMA(ai, bj, At, Bt) do { __builtin_amdgcn_s_setprio(1); _Pragma("unroll") for (int m = 0; m < 4; ++m) _Pragma("unroll") for (int n = 0; n < 2; ++n) _Pragma("unroll") for (int k = 0; k < 2; ++k) \
;         acc[ai][bj][m][n] = __builtin_amdgcn_mfma_f32_16x16x32_bf16(Bt[n][k], At[m][k], acc[ai][bj][m][n], 0, 0, 0); __builtin_amdgcn_s_setprio(0); } while (0)
; #define PG8_WAIT_L(n) asm volatile("s_waitcnt lgkmcnt(" #n ")" ::: "memory")
; #define PG8_BAR __builtin_amdgcn_s_barrier()
; #define PG8_SCHED __builtin_amdgcn_sched_barrier(0)
; template <class Epi, class Sched>
; __device__ __forceinline__ void gemm_phase(PG8_LAS unsigned char* lds, const Gemm g, const Sched& S, const Epi& E, int tid_in) {
;     ...
;         for (int t = 0; t < nt; t += 2) {
;             const bool last = (t == nt - 2);
;             const char* a1 = cA + (size_t)(t + 1) * kstep;
;             const char* a2 = last ? nA : cA + (size_t)(t + 2) * kstep; const char* b2 = last ? nB : cB + (size_t)(t + 2) * kstep;
;             const char* a3 = a2 + kstep; const char* b3 = b2 + kstep;
;             if (last && has_next) S.a_ready(nxt);
;             PG8_LDB(B0, 0, 0); PG8_SCHED; PG8_LDA(At, 0, 0); PG8_STAGE(PG8_SA(1, 1), a1 + hstep, voffA);
;             PG8_WAIT_L(8); PG8_BAR; PG8_WAIT_L(0); PG8_MMA(0, 0, At, B0); PG8_BAR; PG8_SCHED;
;             PG8_LDB(B1, 0, 1); PG8_STAGE(PG8_SB(0, 0), b2, voffB);
;             PG8_BAR; PG8_WAIT_L(0); PG8_MMA(0, 1, At, B1); PG8_BAR;
;             PG8_LDA(At, 0, 1); PG8_STAGE(PG8_SA(0, 0), a2, voffA);
;             PG8_BAR; PG8_WAIT_L(0); PG8_MMA(1, 0, At, B0); PG8_BAR; PG8_SCHED;
.LBB0_295:
	s_add_u32 s24, s22, 0xfffc0080
	s_addc_u32 s25, s23, -1
	s_add_i32 s51, 0, 0x10000
	v_add_u32_e32 v154, s51, v151
	ds_read_b128 v[120:123], v154
	ds_read_b128 v[124:127], v154 offset:1024
	ds_read_b128 v[146:149], v154 offset:2048
	ds_read_b128 v[154:157], v154 offset:3072
	s_cmp_eq_u32 s50, 12
	s_cselect_b32 s27, s9, s25
	s_cselect_b32 s26, s45, s24
	s_cselect_b32 s25, s5, s49
	s_cselect_b32 s24, s46, s48
	v_lshl_add_u64 v[190:191], s[22:23], 0, v[142:143]
	s_add_i32 m0, s15, 0xc000
	ds_read_b128 v[158:161], v153
	ds_read_b128 v[162:165], v153 offset:1024
	ds_read_b128 v[166:169], v153 offset:2048
	ds_read_b128 v[170:173], v153 offset:3072
	ds_read_b128 v[174:177], v153 offset:4096
	ds_read_b128 v[178:181], v153 offset:5120
	ds_read_b128 v[182:185], v153 offset:6144
	ds_read_b128 v[186:189], v153 offset:7168
	global_load_lds_dwordx4 v[190:191], off
	s_add_i32 m0, s15, 0xe000
	v_lshl_add_u64 v[190:191], s[22:23], 0, v[144:145]
	global_load_lds_dwordx4 v[190:191], off
	s_waitcnt lgkmcnt(8)
	s_barrier
	s_waitcnt lgkmcnt(0)
	s_waitcnt lgkmcnt(0)
	v_mfma_f32_16x16x32_bf16 v[132:135], v[120:123], v[158:161], v[132:135]
	v_mfma_f32_16x16x32_bf16 v[128:131], v[146:149], v[158:161], v[128:131]
	v_mfma_f32_16x16x32_bf16 v[116:119], v[120:123], v[166:169], v[116:119]
	v_mfma_f32_16x16x32_bf16 v[112:115], v[146:149], v[166:169], v[112:115]
	v_mfma_f32_16x16x32_bf16 v[108:111], v[120:123], v[174:177], v[108:111]
	v_mfma_f32_16x16x32_bf16 v[104:107], v[146:149], v[174:177], v[104:107]
	v_mfma_f32_16x16x32_bf16 v[100:103], v[120:123], v[182:185], v[100:103]
	v_mfma_f32_16x16x32_bf16 v[96:99], v[146:149], v[182:185], v[96:99]
	v_mfma_f32_16x16x32_bf16 v[132:135], v[124:127], v[162:165], v[132:135]
	v_mfma_f32_16x16x32_bf16 v[128:131], v[154:157], v[162:165], v[128:131]
	v_mfma_f32_16x16x32_bf16 v[116:119], v[124:127], v[170:173], v[116:119]
	v_mfma_f32_16x16x32_bf16 v[112:115], v[154:157], v[170:173], v[112:115]
	v_mfma_f32_16x16x32_bf16 v[108:111], v[124:127], v[178:181], v[108:111]
	v_mfma_f32_16x16x32_bf16 v[104:107], v[154:157], v[178:181], v[104:107]
	v_mfma_f32_16x16x32_bf16 v[100:103], v[124:127], v[186:189], v[100:103]
	v_mfma_f32_16x16x32_bf16 v[96:99], v[154:157], v[186:189], v[96:99]
	s_barrier
	s_add_i32 s54, 0, 0x14000
	v_add_u32_e32 v190, s54, v151
	s_add_i32 s51, s51, s38
	ds_read_b128 v[194:197], v190
	ds_read_b128 v[200:203], v190 offset:1024
	ds_read_b128 v[204:207], v190 offset:2048
	ds_read_b128 v[208:211], v190 offset:3072
	v_lshl_add_u64 v[190:191], s[24:25], 0, v[192:193]
	s_mov_b32 m0, s51
	v_lshl_add_u64 v[212:213], s[24:25], 0, v[140:141]
	global_load_lds_dwordx4 v[190:191], off
	s_add_i32 m0, s51, 0x2000
	s_nop 0
	global_load_lds_dwordx4 v[212:213], off
	s_barrier
	s_waitcnt lgkmcnt(0)
	s_waitcnt lgkmcnt(0)
	v_mfma_f32_16x16x32_bf16 v[60:63], v[194:197], v[158:161], v[60:63]
	v_mfma_f32_16x16x32_bf16 v[56:59], v[204:207], v[158:161], v[56:59]
	v_mfma_f32_16x16x32_bf16 v[52:55], v[194:197], v[166:169], v[52:55]
	v_mfma_f32_16x16x32_bf16 v[48:51], v[204:207], v[166:169], v[48:51]
	v_mfma_f32_16x16x32_bf16 v[44:47], v[194:197], v[174:177], v[44:47]
	v_mfma_f32_16x16x32_bf16 v[40:43], v[204:207], v[174:177], v[40:43]
	v_mfma_f32_16x16x32_bf16 v[36:39], v[194:197], v[182:185], v[36:39]
	v_mfma_f32_16x16x32_bf16 v[32:35], v[204:207], v[182:185], v[32:35]
	v_mfma_f32_16x16x32_bf16 v[60:63], v[200:203], v[162:165], v[60:63]
	v_mfma_f32_16x16x32_bf16 v[56:59], v[208:211], v[162:165], v[56:59]
	v_mfma_f32_16x16x32_bf16 v[52:55], v[200:203], v[170:173], v[52:55]
	v_mfma_f32_16x16x32_bf16 v[48:51], v[208:211], v[170:173], v[48:51]
	v_mfma_f32_16x16x32_bf16 v[44:47], v[200:203], v[178:181], v[44:47]
	v_mfma_f32_16x16x32_bf16 v[40:43], v[208:211], v[178:181], v[40:43]
	v_mfma_f32_16x16x32_bf16 v[36:39], v[200:203], v[186:189], v[36:39]
	v_mfma_f32_16x16x32_bf16 v[32:35], v[208:211], v[186:189], v[32:35]
	s_mov_b32 m0, s15
	v_lshl_add_u64 v[214:215], s[26:27], 0, v[136:137]
	s_barrier
	ds_read_b128 v[158:161], v153 offset:16384
	ds_read_b128 v[162:165], v153 offset:17408
	ds_read_b128 v[166:169], v153 offset:18432
	ds_read_b128 v[170:173], v153 offset:19456
	ds_read_b128 v[174:177], v153 offset:20480
	ds_read_b128 v[178:181], v153 offset:21504
	ds_read_b128 v[182:185], v153 offset:22528
	ds_read_b128 v[186:189], v153 offset:23552
	global_load_lds_dwordx4 v[214:215], off
	s_mov_b32 m0, s39
	v_lshl_add_u64 v[216:217], s[26:27], 0, v[138:139]
	global_load_lds_dwordx4 v[216:217], off
	s_barrier
	s_waitcnt lgkmcnt(0)
	s_waitcnt lgkmcnt(0)
	v_mfma_f32_16x16x32_bf16 v[92:95], v[120:123], v[158:161], v[92:95]
	v_mfma_f32_16x16x32_bf16 v[88:91], v[146:149], v[158:161], v[88:91]
	v_mfma_f32_16x16x32_bf16 v[84:87], v[120:123], v[166:169], v[84:87]
	v_mfma_f32_16x16x32_bf16 v[80:83], v[146:149], v[166:169], v[80:83]
	v_mfma_f32_16x16x32_bf16 v[76:79], v[120:123], v[174:177], v[76:79]
	v_mfma_f32_16x16x32_bf16 v[72:75], v[146:149], v[174:177], v[72:75]
	v_mfma_f32_16x16x32_bf16 v[68:71], v[120:123], v[182:185], v[68:71]
	v_mfma_f32_16x16x32_bf16 v[64:67], v[146:149], v[182:185], v[64:67]
	v_mfma_f32_16x16x32_bf16 v[92:95], v[124:127], v[162:165], v[92:95]
	v_mfma_f32_16x16x32_bf16 v[88:91], v[154:157], v[162:165], v[88:91]
	v_mfma_f32_16x16x32_bf16 v[84:87], v[124:127], v[170:173], v[84:87]
	v_mfma_f32_16x16x32_bf16 v[80:83], v[154:157], v[170:173], v[80:83]
	v_mfma_f32_16x16x32_bf16 v[76:79], v[124:127], v[178:181], v[76:79]
	v_mfma_f32_16x16x32_bf16 v[72:75], v[154:157], v[178:181], v[72:75]
	v_mfma_f32_16x16x32_bf16 v[68:71], v[124:127], v[186:189], v[68:71]
	v_mfma_f32_16x16x32_bf16 v[64:67], v[154:157], v[186:189], v[64:67]
	s_barrier
; #define PG8_STAGE(bufoff, gbase, voff) do { _Pragma("unroll") for (int _i = 0; _i < 2; ++_i) \
;         __builtin_amdgcn_global_load_lds((const unsigned*)((const char*)(gbase) + (voff)[_i]), (PG8_LAS unsigned*)(lds + (bufoff) + ldsw + _i * 8192), 16, 0, 0); } while (0)
; #define PG8_LDA(dst, b, h) do { _Pragma("unroll") for (int m = 0; m < 4; ++m) _Pragma("unroll") for (int k = 0; k < 2; ++k) dst[m][k] = *(const PG8_LAS bf16x8*)(lds + PG8_SA(b, h) + aoff + m * 2048 + k * 1024); } while (0)
; #define PG8_LDB(dst, b, h) do { _Pragma("unroll") for (int n = 0; n < 2; ++n) _Pragma("unroll") for (int k = 0; k < 2; ++k) dst[n][k] = *(const PG8_LAS bf16x8*)(lds + PG8_SB(b, h) + boff + n * 2048 + k * 1024); } while (0)
; #define PG8_MMA(ai, bj, At, Bt) do { __builtin_amdgcn_s_setprio(1); _Pragma("unroll") for (int m = 0; m < 4; ++m) _Pragma("unroll") for (int n = 0; n < 2; ++n) _Pragma("unroll") for (int k = 0; k < 2; ++k) \
;         acc[ai][bj][m][n] = __builtin_amdgcn_mfma_f32_16x16x32_bf16(Bt[n][k], At[m][k], acc[ai][bj][m][n], 0, 0, 0); __builtin_amdgcn_s_setprio(0); } while (0)
; #define PG8_WAIT_V(n) asm volatile("s_waitcnt vmcnt(" #n ")" ::: "memory")
; #define PG8_WAIT_L(n) asm volatile("s_waitcnt lgkmcnt(" #n ")" ::: "memory")
; #define PG8_BAR __builtin_amdgcn_s_barrier()
; #define PG8_SCHED __builtin_amdgcn_sched_barrier(0)
; template <class Epi, class Sched>
; __device__ __forceinline__ void gemm_phase(PG8_LAS unsigned char* lds, const Gemm g, const Sched& S, const Epi& E, int tid_in) {
;     ...
;             PG8_STAGE(PG8_SB(0, 1), b2 + hstep, voffB);
;             PG8_WAIT_V(6); PG8_BAR; PG8_MMA(1, 1, At, B1); PG8_BAR;
;             PG8_LDB(B0, 1, 0); PG8_SCHED; PG8_LDA(At, 1, 0); PG8_STAGE(PG8_SA(0, 1), a2 + hstep, voffA);
;             PG8_WAIT_L(8); PG8_BAR; PG8_WAIT_L(0); PG8_MMA(0, 0, At, B0); PG8_BAR; PG8_SCHED;
;             PG8_LDB(B1, 1, 1); PG8_STAGE(PG8_SB(1, 0), b3, voffB);
;             PG8_BAR; PG8_WAIT_L(0); PG8_MMA(0, 1, At, B1); PG8_BAR;
;             PG8_LDA(At, 1, 1); PG8_STAGE(PG8_SA(1, 0), a3, voffA);
	s_add_u32 s52, s24, 0x40000
	s_addc_u32 s53, s25, 0
	s_add_i32 s51, s54, s38
	s_mov_b32 m0, s51
	v_lshl_add_u64 v[120:121], s[52:53], 0, v[192:193]
	global_load_lds_dwordx4 v[120:121], off
	s_add_i32 m0, s51, 0x2000
	v_lshl_add_u64 v[120:121], s[52:53], 0, v[140:141]
	global_load_lds_dwordx4 v[120:121], off
	s_waitcnt vmcnt(6)
	s_barrier
	v_mfma_f32_16x16x32_bf16 v[28:31], v[194:197], v[158:161], v[28:31]
	v_mfma_f32_16x16x32_bf16 v[24:27], v[204:207], v[158:161], v[24:27]
	v_mfma_f32_16x16x32_bf16 v[20:23], v[194:197], v[166:169], v[20:23]
	v_mfma_f32_16x16x32_bf16 v[16:19], v[204:207], v[166:169], v[16:19]
	v_mfma_f32_16x16x32_bf16 v[12:15], v[194:197], v[174:177], v[12:15]
	v_mfma_f32_16x16x32_bf16 v[8:11], v[204:207], v[174:177], v[8:11]
	v_mfma_f32_16x16x32_bf16 v[4:7], v[194:197], v[182:185], v[4:7]
	v_mfma_f32_16x16x32_bf16 v[0:3], v[204:207], v[182:185], v[0:3]
	v_mfma_f32_16x16x32_bf16 v[28:31], v[200:203], v[162:165], v[28:31]
	v_mfma_f32_16x16x32_bf16 v[24:27], v[208:211], v[162:165], v[24:27]
	v_mfma_f32_16x16x32_bf16 v[20:23], v[200:203], v[170:173], v[20:23]
	v_mfma_f32_16x16x32_bf16 v[16:19], v[208:211], v[170:173], v[16:19]
	v_mfma_f32_16x16x32_bf16 v[12:15], v[200:203], v[178:181], v[12:15]
	v_mfma_f32_16x16x32_bf16 v[8:11], v[208:211], v[178:181], v[8:11]
	v_mfma_f32_16x16x32_bf16 v[4:7], v[200:203], v[186:189], v[4:7]
	v_mfma_f32_16x16x32_bf16 v[0:3], v[208:211], v[186:189], v[0:3]
	s_add_i32 s51, 0, 0x18000
	v_add_u32_e32 v154, s51, v151
	s_barrier
	ds_read_b128 v[120:123], v154
	ds_read_b128 v[124:127], v154 offset:1024
	ds_read_b128 v[146:149], v154 offset:2048
	ds_read_b128 v[154:157], v154 offset:3072
	s_add_u32 s26, s26, 0x40000
	s_addc_u32 s27, s27, 0
	s_mov_b32 m0, s40
	v_lshl_add_u64 v[194:195], s[26:27], 0, v[136:137]
	ds_read_b128 v[158:161], v153 offset:32768
	ds_read_b128 v[162:165], v153 offset:33792
	ds_read_b128 v[166:169], v153 offset:34816
	ds_read_b128 v[170:173], v153 offset:35840
	ds_read_b128 v[174:177], v153 offset:36864
	ds_read_b128 v[178:181], v153 offset:37888
	ds_read_b128 v[182:185], v153 offset:38912
	ds_read_b128 v[186:189], v153 offset:39936
	global_load_lds_dwordx4 v[194:195], off
	s_mov_b32 m0, s41
	v_lshl_add_u64 v[194:195], s[26:27], 0, v[138:139]
	global_load_lds_dwordx4 v[194:195], off
	s_waitcnt lgkmcnt(8)
	s_barrier
	s_waitcnt lgkmcnt(0)
	s_waitcnt lgkmcnt(0)
	v_mfma_f32_16x16x32_bf16 v[132:135], v[120:123], v[158:161], v[132:135]
	v_mfma_f32_16x16x32_bf16 v[128:131], v[146:149], v[158:161], v[128:131]
	v_mfma_f32_16x16x32_bf16 v[116:119], v[120:123], v[166:169], v[116:119]
	v_mfma_f32_16x16x32_bf16 v[112:115], v[146:149], v[166:169], v[112:115]
	v_mfma_f32_16x16x32_bf16 v[108:111], v[120:123], v[174:177], v[108:111]
	v_mfma_f32_16x16x32_bf16 v[104:107], v[146:149], v[174:177], v[104:107]
	v_mfma_f32_16x16x32_bf16 v[100:103], v[120:123], v[182:185], v[100:103]
	v_mfma_f32_16x16x32_bf16 v[96:99], v[146:149], v[182:185], v[96:99]
	v_mfma_f32_16x16x32_bf16 v[132:135], v[124:127], v[162:165], v[132:135]
	v_mfma_f32_16x16x32_bf16 v[128:131], v[154:157], v[162:165], v[128:131]
	v_mfma_f32_16x16x32_bf16 v[116:119], v[124:127], v[170:173], v[116:119]
	v_mfma_f32_16x16x32_bf16 v[112:115], v[154:157], v[170:173], v[112:115]
	v_mfma_f32_16x16x32_bf16 v[108:111], v[124:127], v[178:181], v[108:111]
	v_mfma_f32_16x16x32_bf16 v[104:107], v[154:157], v[178:181], v[104:107]
	v_mfma_f32_16x16x32_bf16 v[100:103], v[124:127], v[186:189], v[100:103]
	v_mfma_f32_16x16x32_bf16 v[96:99], v[154:157], v[186:189], v[96:99]
	s_barrier
	s_add_i32 s26, 0, 0x1c000
	s_add_i32 s27, s51, s38
	v_add_u32_e32 v199, s26, v151
	v_lshl_add_u64 v[190:191], v[190:191], 0, s[74:75]
	s_mov_b32 m0, s27
	ds_read_b128 v[194:197], v199
	ds_read_b128 v[200:203], v199 offset:1024
	ds_read_b128 v[204:207], v199 offset:2048
	ds_read_b128 v[208:211], v199 offset:3072
	global_load_lds_dwordx4 v[190:191], off
	s_add_i32 m0, s27, 0x2000
	v_lshl_add_u64 v[190:191], v[212:213], 0, s[74:75]
	global_load_lds_dwordx4 v[190:191], off
	s_barrier
	s_waitcnt lgkmcnt(0)
	s_waitcnt lgkmcnt(0)
	v_mfma_f32_16x16x32_bf16 v[60:63], v[194:197], v[158:161], v[60:63]
	v_mfma_f32_16x16x32_bf16 v[56:59], v[204:207], v[158:161], v[56:59]
	v_mfma_f32_16x16x32_bf16 v[52:55], v[194:197], v[166:169], v[52:55]
	v_mfma_f32_16x16x32_bf16 v[48:51], v[204:207], v[166:169], v[48:51]
	v_mfma_f32_16x16x32_bf16 v[44:47], v[194:197], v[174:177], v[44:47]
	v_mfma_f32_16x16x32_bf16 v[40:43], v[204:207], v[174:177], v[40:43]
	v_mfma_f32_16x16x32_bf16 v[36:39], v[194:197], v[182:185], v[36:39]
	v_mfma_f32_16x16x32_bf16 v[32:35], v[204:207], v[182:185], v[32:35]
	v_mfma_f32_16x16x32_bf16 v[60:63], v[200:203], v[162:165], v[60:63]
	v_mfma_f32_16x16x32_bf16 v[56:59], v[208:211], v[162:165], v[56:59]
	v_mfma_f32_16x16x32_bf16 v[52:55], v[200:203], v[170:173], v[52:55]
	v_mfma_f32_16x16x32_bf16 v[48:51], v[208:211], v[170:173], v[48:51]
	v_mfma_f32_16x16x32_bf16 v[44:47], v[200:203], v[178:181], v[44:47]
	v_mfma_f32_16x16x32_bf16 v[40:43], v[208:211], v[178:181], v[40:43]
	v_mfma_f32_16x16x32_bf16 v[36:39], v[200:203], v[186:189], v[36:39]
	v_mfma_f32_16x16x32_bf16 v[32:35], v[208:211], v[186:189], v[32:35]
	s_mov_b32 m0, s42
	v_lshl_add_u64 v[190:191], v[214:215], 0, s[74:75]
	s_barrier
	ds_read_b128 v[158:161], v153 offset:49152
	ds_read_b128 v[162:165], v153 offset:50176
	ds_read_b128 v[166:169], v153 offset:51200
	ds_read_b128 v[170:173], v153 offset:52224
	ds_read_b128 v[174:177], v153 offset:53248
	ds_read_b128 v[178:181], v153 offset:54272
	ds_read_b128 v[182:185], v153 offset:55296
	ds_read_b128 v[186:189], v153 offset:56320
	global_load_lds_dwordx4 v[190:191], off
	s_mov_b32 m0, s43
	v_lshl_add_u64 v[190:191], v[216:217], 0, s[74:75]
	global_load_lds_dwordx4 v[190:191], off
	s_barrier
; __device__ __forceinline__ unsigned cvt_pk_bf16(float lo, float hi) { unsigned r; asm volatile("s_nop 0\n\tv_cvt_pk_bf16_f32 %0, %1, %2\n\ts_nop 1" : "=v"(r) : "v"(lo), "v"(hi)); return r; }
; #define PG8_STAGE(bufoff, gbase, voff) do { _Pragma("unroll") for (int _i = 0; _i < 2; ++_i) \
;         __builtin_amdgcn_global_load_lds((const unsigned*)((const char*)(gbase) + (voff)[_i]), (PG8_LAS unsigned*)(lds + (bufoff) + ldsw + _i * 8192), 16, 0, 0); } while (0)
; #define PG8_MMA(ai, bj, At, Bt) do { __builtin_amdgcn_s_setprio(1); _Pragma("unroll") for (int m = 0; m < 4; ++m) _Pragma("unroll") for (int n = 0; n < 2; ++n) _Pragma("unroll") for (int k = 0; k < 2; ++k) \
;         acc[ai][bj][m][n] = __builtin_amdgcn_mfma_f32_16x16x32_bf16(Bt[n][k], At[m][k], acc[ai][bj][m][n], 0, 0, 0); __builtin_amdgcn_s_setprio(0); } while (0)
; #define PG8_WAIT_V(n) asm volatile("s_waitcnt vmcnt(" #n ")" ::: "memory")
; #define PG8_WAIT_L(n) asm volatile("s_waitcnt lgkmcnt(" #n ")" ::: "memory")
; template <class Epi, class Sched>
; __device__ __forceinline__ void gemm_phase(PG8_LAS unsigned char* lds, const Gemm g, const Sched& S, const Epi& E, int tid_in) {
;     ...
;             PG8_BAR; PG8_WAIT_L(0); PG8_MMA(1, 0, At, B0); PG8_BAR; PG8_SCHED;
;             PG8_STAGE(PG8_SB(1, 1), b3 + hstep, voffB);
;             PG8_WAIT_V(6); PG8_BAR; PG8_MMA(1, 1, At, B1); PG8_BAR;
;         }
;     __device__ __forceinline__ void operator()(f32x4 (&acc)[2][2][4][2], const Unit& u, int wr, int wc, int fr, int fq) const {
;         const int row0 = u.pm * 256 + wr * 64 + fr, col0 = u.pn * 256 + wc * 32 + 8 * fq;
; #pragma unroll
;         for (int bj = 0; bj < 2; ++bj) { const f32x4 b0 = *(const f32x4*)(bias + col0 + bj * 128), b1 = *(const f32x4*)(bias + col0 + bj * 128 + 4);
; #pragma unroll
;             for (int ai = 0; ai < 2; ++ai)
; #pragma unroll
;                 for (int m = 0; m < 4; ++m) { f32x4 v0 = acc[ai][bj][m][0] + b0, v1 = acc[ai][bj][m][1] + b1;
; #pragma unroll
;                     for (int j = 0; j < 4; ++j) { v0[j] = fmaxf(v0[j], 0.f); v0[j] *= v0[j]; v1[j] = fmaxf(v1[j], 0.f); v1[j] *= v1[j]; }
;                     u32x4 w; w.x = cvt_pk_bf16(v0[0], v0[1]); w.y = cvt_pk_bf16(v0[2], v0[3]); w.z = cvt_pk_bf16(v1[0], v1[1]); w.w = cvt_pk_bf16(v1[2], v1[3]);
;                     *(u32x4*)(O + (size_t)(row0 + ai * 128 + m * 16) * 4096 + col0 + bj * 128) = w; } }
	s_waitcnt lgkmcnt(0)
	s_waitcnt lgkmcnt(0)
	v_mfma_f32_16x16x32_bf16 v[92:95], v[120:123], v[158:161], v[92:95]
	v_mfma_f32_16x16x32_bf16 v[88:91], v[146:149], v[158:161], v[88:91]
	v_mfma_f32_16x16x32_bf16 v[84:87], v[120:123], v[166:169], v[84:87]
	v_mfma_f32_16x16x32_bf16 v[80:83], v[146:149], v[166:169], v[80:83]
	v_mfma_f32_16x16x32_bf16 v[76:79], v[120:123], v[174:177], v[76:79]
	v_mfma_f32_16x16x32_bf16 v[72:75], v[146:149], v[174:177], v[72:75]
	v_mfma_f32_16x16x32_bf16 v[68:71], v[120:123], v[182:185], v[68:71]
	v_mfma_f32_16x16x32_bf16 v[64:67], v[146:149], v[182:185], v[64:67]
	v_mfma_f32_16x16x32_bf16 v[92:95], v[124:127], v[162:165], v[92:95]
	v_mfma_f32_16x16x32_bf16 v[88:91], v[154:157], v[162:165], v[88:91]
	v_mfma_f32_16x16x32_bf16 v[84:87], v[124:127], v[170:173], v[84:87]
	v_mfma_f32_16x16x32_bf16 v[80:83], v[154:157], v[170:173], v[80:83]
	v_mfma_f32_16x16x32_bf16 v[76:79], v[124:127], v[178:181], v[76:79]
	v_mfma_f32_16x16x32_bf16 v[72:75], v[154:157], v[178:181], v[72:75]
	v_mfma_f32_16x16x32_bf16 v[68:71], v[124:127], v[186:189], v[68:71]
	v_mfma_f32_16x16x32_bf16 v[64:67], v[154:157], v[186:189], v[64:67]
	s_barrier
	s_add_u32 s24, s24, 0x40080
	s_addc_u32 s25, s25, 0
	s_add_i32 s26, s26, s38
	s_mov_b32 m0, s26
	v_lshl_add_u64 v[120:121], s[24:25], 0, v[192:193]
	global_load_lds_dwordx4 v[120:121], off
	s_add_i32 m0, s26, 0x2000
	v_lshl_add_u64 v[120:121], s[24:25], 0, v[140:141]
	global_load_lds_dwordx4 v[120:121], off
	s_waitcnt vmcnt(6)
	s_barrier
	v_mfma_f32_16x16x32_bf16 v[28:31], v[194:197], v[158:161], v[28:31]
	v_mfma_f32_16x16x32_bf16 v[24:27], v[204:207], v[158:161], v[24:27]
	v_mfma_f32_16x16x32_bf16 v[20:23], v[194:197], v[166:169], v[20:23]
	v_mfma_f32_16x16x32_bf16 v[16:19], v[204:207], v[166:169], v[16:19]
	v_mfma_f32_16x16x32_bf16 v[12:15], v[194:197], v[174:177], v[12:15]
	v_mfma_f32_16x16x32_bf16 v[8:11], v[204:207], v[174:177], v[8:11]
	v_mfma_f32_16x16x32_bf16 v[4:7], v[194:197], v[182:185], v[4:7]
	v_mfma_f32_16x16x32_bf16 v[0:3], v[204:207], v[182:185], v[0:3]
	v_mfma_f32_16x16x32_bf16 v[28:31], v[200:203], v[162:165], v[28:31]
	v_mfma_f32_16x16x32_bf16 v[24:27], v[208:211], v[162:165], v[24:27]
	v_mfma_f32_16x16x32_bf16 v[20:23], v[200:203], v[170:173], v[20:23]
	v_mfma_f32_16x16x32_bf16 v[16:19], v[208:211], v[170:173], v[16:19]
	v_mfma_f32_16x16x32_bf16 v[12:15], v[200:203], v[178:181], v[12:15]
	v_mfma_f32_16x16x32_bf16 v[8:11], v[208:211], v[178:181], v[8:11]
	v_mfma_f32_16x16x32_bf16 v[4:7], v[200:203], v[186:189], v[4:7]
	v_mfma_f32_16x16x32_bf16 v[0:3], v[208:211], v[186:189], v[0:3]
	s_add_i32 s50, s50, 2
	s_add_u32 s22, s22, 0x100
	s_addc_u32 s23, s23, 0
	s_add_u32 s48, s48, 0x100
	s_addc_u32 s49, s49, 0
	s_cmp_gt_u32 s50, 13
	s_barrier
	s_cbranch_scc0 .LBB0_295
	v_lshl_or_b32 v154, s33, 8, v152
	v_ashrrev_i32_e32 v155, 31, v154
	v_lshl_add_u64 v[146:147], v[154:155], 2, s[6:7]
	global_load_dwordx4 v[120:123], v[146:147], off offset:16
	global_load_dwordx4 v[124:127], v[146:147], off
	global_load_dwordx4 v[200:203], v[146:147], off offset:528
	global_load_dwordx4 v[204:207], v[146:147], off offset:512
	v_lshl_add_u32 v148, s14, 8, v150
	v_ashrrev_i32_e32 v149, 31, v148
	s_mov_b32 s5, 0x100000
	s_mov_b64 s[22:23], 0x100000
	s_mov_b32 s33, s4
	s_mov_b32 s14, s8
	s_mov_b64 s[24:25], s[12:13]
	s_waitcnt vmcnt(0)
	v_pk_add_f32 v[128:129], v[128:129], v[120:121]
	v_pk_add_f32 v[134:135], v[134:135], v[126:127]
	v_pk_add_f32 v[132:133], v[132:133], v[124:125]
	v_pk_add_f32 v[130:131], v[130:131], v[122:123]
	v_max_f32_e32 v132, 0, v132
	v_max_f32_e32 v128, 0, v128
	v_max_f32_e32 v133, 0, v133
	v_max_f32_e32 v129, 0, v129
	v_max_f32_e32 v134, 0, v134
	v_mul_f32_e32 v132, v132, v132
	v_mul_f32_e32 v128, v128, v128
	v_mul_f32_e32 v133, v133, v133
	v_mul_f32_e32 v129, v129, v129
	v_mul_f32_e32 v134, v134, v134
	v_max_f32_e32 v130, 0, v130
	v_max_f32_e32 v135, 0, v135
	v_max_f32_e32 v131, 0, v131
	v_mul_f32_e32 v130, v130, v130
	v_mul_f32_e32 v135, v135, v135
	v_mul_f32_e32 v131, v131, v131
	v_cvt_pk_bf16_f32 v132, v132, v133
	v_cvt_pk_bf16_f32 v133, v134, v135
	v_cvt_pk_bf16_f32 v134, v128, v129
	v_lshlrev_b64 v[128:129], 13, v[148:149]
	v_cvt_pk_bf16_f32 v135, v130, v131
	v_lshl_add_u64 v[128:129], s[0:1], 0, v[128:129]
	v_lshlrev_b64 v[130:131], 1, v[154:155]
	v_pk_add_f32 v[114:115], v[114:115], v[122:123]
	v_lshl_add_u64 v[128:129], v[128:129], 0, v[130:131]
	v_pk_add_f32 v[118:119], v[118:119], v[126:127]
	v_pk_add_f32 v[116:117], v[116:117], v[124:125]
	v_pk_add_f32 v[112:113], v[112:113], v[120:121]
	v_max_f32_e32 v114, 0, v114
	global_store_dwordx4 v[128:129], v[132:135], off
	v_max_f32_e32 v116, 0, v116
	v_max_f32_e32 v112, 0, v112
	v_mul_f32_e32 v132, v114, v114
	v_max_f32_e32 v114, 0, v119
	v_mul_f32_e32 v116, v116, v116
	v_mul_f32_e32 v112, v112, v112
	v_max_f32_e32 v117, 0, v117
	v_max_f32_e32 v113, 0, v113
	v_max_f32_e32 v118, 0, v118
	v_mul_f32_e32 v119, v114, v114
	v_max_f32_e32 v114, 0, v115
	v_mul_f32_e32 v117, v117, v117
	v_mul_f32_e32 v113, v113, v113
	v_mul_f32_e32 v118, v118, v118
	v_mul_f32_e32 v133, v114, v114
	v_cvt_pk_bf16_f32 v114, v116, v117
	v_cvt_pk_bf16_f32 v115, v118, v119
	v_cvt_pk_bf16_f32 v116, v112, v113
	v_or_b32_e32 v112, 16, v148
	v_ashrrev_i32_e32 v113, 31, v112
	v_lshlrev_b64 v[112:113], 13, v[112:113]
	v_lshl_add_u64 v[112:113], s[0:1], 0, v[112:113]
	v_pk_add_f32 v[106:107], v[106:107], v[122:123]
	v_lshl_add_u64 v[112:113], v[112:113], 0, v[130:131]
	v_pk_add_f32 v[110:111], v[110:111], v[126:127]
	v_pk_add_f32 v[108:109], v[108:109], v[124:125]
	v_pk_add_f32 v[104:105], v[104:105], v[120:121]
	v_max_f32_e32 v106, 0, v106
	v_cvt_pk_bf16_f32 v117, v132, v133
; __device__ __forceinline__ unsigned cvt_pk_bf16(float lo, float hi) { unsigned r; asm volatile("s_nop 0\n\tv_cvt_pk_bf16_f32 %0, %1, %2\n\ts_nop 1" : "=v"(r) : "v"(lo), "v"(hi)); return r; }
;     __device__ __forceinline__ void operator()(f32x4 (&acc)[2][2][4][2], const Unit& u, int wr, int wc, int fr, int fq) const {
;     ...
;         for (int bj = 0; bj < 2; ++bj) { const f32x4 b0 = *(const f32x4*)(bias + col0 + bj * 128), b1 = *(const f32x4*)(bias + col0 + bj * 128 + 4);
; #pragma unroll
;             for (int ai = 0; ai < 2; ++ai)
; #pragma unroll
;                 for (int m = 0; m < 4; ++m) { f32x4 v0 = acc[ai][bj][m][0] + b0, v1 = acc[ai][bj][m][1] + b1;
; #pragma unroll
;                     for (int j = 0; j < 4; ++j) { v0[j] = fmaxf(v0[j], 0.f); v0[j] *= v0[j]; v1[j] = fmaxf(v1[j], 0.f); v1[j] *= v1[j]; }
;                     u32x4 w; w.x = cvt_pk_bf16(v0[0], v0[1]); w.y = cvt_pk_bf16(v0[2], v0[3]); w.z = cvt_pk_bf16(v1[0], v1[1]); w.w = cvt_pk_bf16(v1[2], v1[3]);
;                     *(u32x4*)(O + (size_t)(row0 + ai * 128 + m * 16) * 4096 + col0 + bj * 128) = w; } }
	global_store_dwordx4 v[112:113], v[114:117], off
	v_max_f32_e32 v108, 0, v108
	v_max_f32_e32 v104, 0, v104
	v_mul_f32_e32 v114, v106, v106
	v_max_f32_e32 v106, 0, v111
	v_mul_f32_e32 v108, v108, v108
	v_mul_f32_e32 v104, v104, v104
	v_max_f32_e32 v109, 0, v109
	v_max_f32_e32 v105, 0, v105
	v_max_f32_e32 v110, 0, v110
	v_mul_f32_e32 v111, v106, v106
	v_max_f32_e32 v106, 0, v107
	v_mul_f32_e32 v109, v109, v109
	v_mul_f32_e32 v105, v105, v105
	v_mul_f32_e32 v110, v110, v110
	v_mul_f32_e32 v115, v106, v106
	v_cvt_pk_bf16_f32 v106, v108, v109
	v_cvt_pk_bf16_f32 v107, v110, v111
	v_cvt_pk_bf16_f32 v108, v104, v105
	v_or_b32_e32 v104, 32, v148
	v_ashrrev_i32_e32 v105, 31, v104
	v_lshlrev_b64 v[104:105], 13, v[104:105]
	v_lshl_add_u64 v[104:105], s[0:1], 0, v[104:105]
	v_pk_add_f32 v[98:99], v[98:99], v[122:123]
	v_lshl_add_u64 v[104:105], v[104:105], 0, v[130:131]
	v_pk_add_f32 v[102:103], v[102:103], v[126:127]
	v_pk_add_f32 v[100:101], v[100:101], v[124:125]
	v_pk_add_f32 v[96:97], v[96:97], v[120:121]
	v_max_f32_e32 v98, 0, v98
	v_cvt_pk_bf16_f32 v109, v114, v115
	global_store_dwordx4 v[104:105], v[106:109], off
	v_max_f32_e32 v100, 0, v100
	v_max_f32_e32 v96, 0, v96
	v_mul_f32_e32 v106, v98, v98
	v_max_f32_e32 v98, 0, v103
	v_mul_f32_e32 v100, v100, v100
	v_mul_f32_e32 v96, v96, v96
	v_max_f32_e32 v101, 0, v101
	v_max_f32_e32 v97, 0, v97
	v_max_f32_e32 v102, 0, v102
	v_mul_f32_e32 v103, v98, v98
	v_max_f32_e32 v98, 0, v99
	v_mul_f32_e32 v101, v101, v101
	v_mul_f32_e32 v97, v97, v97
	v_mul_f32_e32 v102, v102, v102
	v_mul_f32_e32 v107, v98, v98
	v_cvt_pk_bf16_f32 v98, v100, v101
	v_cvt_pk_bf16_f32 v99, v102, v103
	v_cvt_pk_bf16_f32 v100, v96, v97
	v_or_b32_e32 v96, 48, v148
	v_ashrrev_i32_e32 v97, 31, v96
	v_lshlrev_b64 v[96:97], 13, v[96:97]
	v_lshl_add_u64 v[96:97], s[0:1], 0, v[96:97]
	v_pk_add_f32 v[90:91], v[90:91], v[122:123]
	v_lshl_add_u64 v[96:97], v[96:97], 0, v[130:131]
	v_pk_add_f32 v[94:95], v[94:95], v[126:127]
	v_max_f32_e32 v90, 0, v90
	v_cvt_pk_bf16_f32 v101, v106, v107
	global_store_dwordx4 v[96:97], v[98:101], off
	v_pk_add_f32 v[92:93], v[92:93], v[124:125]
	v_max_f32_e32 v94, 0, v94
	v_mul_f32_e32 v98, v90, v90
	v_max_f32_e32 v90, 0, v95
	v_max_f32_e32 v92, 0, v92
	v_max_f32_e32 v93, 0, v93
	v_mul_f32_e32 v94, v94, v94
	v_mul_f32_e32 v95, v90, v90
	v_max_f32_e32 v90, 0, v91
	v_pk_add_f32 v[88:89], v[88:89], v[120:121]
	v_mul_f32_e32 v92, v92, v92
	v_mul_f32_e32 v93, v93, v93
	v_mul_f32_e32 v99, v90, v90
	v_cvt_pk_bf16_f32 v90, v92, v93
	v_cvt_pk_bf16_f32 v91, v94, v95
	v_add_co_u32_e32 v94, vcc, s5, v128
	v_pk_add_f32 v[82:83], v[82:83], v[122:123]
	v_max_f32_e32 v88, 0, v88
	v_max_f32_e32 v89, 0, v89
	v_addc_co_u32_e32 v95, vcc, 0, v129, vcc
	v_pk_add_f32 v[86:87], v[86:87], v[126:127]
	v_max_f32_e32 v82, 0, v82
	v_mul_f32_e32 v88, v88, v88
	v_mul_f32_e32 v89, v89, v89
	v_cvt_pk_bf16_f32 v92, v88, v89
	v_cvt_pk_bf16_f32 v93, v98, v99
	global_store_dwordx4 v[94:95], v[90:93], off
	v_pk_add_f32 v[84:85], v[84:85], v[124:125]
	v_max_f32_e32 v86, 0, v86
	v_mul_f32_e32 v90, v82, v82
	v_max_f32_e32 v82, 0, v87
	v_max_f32_e32 v84, 0, v84
	v_max_f32_e32 v85, 0, v85
	v_mul_f32_e32 v86, v86, v86
	v_mul_f32_e32 v87, v82, v82
	v_max_f32_e32 v82, 0, v83
	s_mov_b32 s5, 0x120000
	v_pk_add_f32 v[80:81], v[80:81], v[120:121]
	v_mul_f32_e32 v84, v84, v84
	v_mul_f32_e32 v85, v85, v85
	v_mul_f32_e32 v91, v82, v82
	v_cvt_pk_bf16_f32 v82, v84, v85
	v_cvt_pk_bf16_f32 v83, v86, v87
	v_add_co_u32_e32 v86, vcc, s5, v128
	v_pk_add_f32 v[74:75], v[74:75], v[122:123]
	v_max_f32_e32 v80, 0, v80
	v_max_f32_e32 v81, 0, v81
	v_addc_co_u32_e32 v87, vcc, 0, v129, vcc
	v_pk_add_f32 v[78:79], v[78:79], v[126:127]
	v_max_f32_e32 v74, 0, v74
	v_mul_f32_e32 v80, v80, v80
	v_mul_f32_e32 v81, v81, v81
	v_cvt_pk_bf16_f32 v84, v80, v81
	v_cvt_pk_bf16_f32 v85, v90, v91
	global_store_dwordx4 v[86:87], v[82:85], off
	v_pk_add_f32 v[76:77], v[76:77], v[124:125]
	v_max_f32_e32 v78, 0, v78
	v_mul_f32_e32 v82, v74, v74
	v_max_f32_e32 v74, 0, v79
	v_max_f32_e32 v76, 0, v76
	v_max_f32_e32 v77, 0, v77
	v_mul_f32_e32 v78, v78, v78
	v_mul_f32_e32 v79, v74, v74
	v_max_f32_e32 v74, 0, v75
	s_mov_b32 s5, 0x140000
	v_pk_add_f32 v[72:73], v[72:73], v[120:121]
	v_mul_f32_e32 v76, v76, v76
	v_mul_f32_e32 v77, v77, v77
	v_mul_f32_e32 v83, v74, v74
	v_cvt_pk_bf16_f32 v74, v76, v77
	v_cvt_pk_bf16_f32 v75, v78, v79
	v_add_co_u32_e32 v78, vcc, s5, v128
	v_pk_add_f32 v[64:65], v[64:65], v[120:121]
	v_max_f32_e32 v72, 0, v72
	v_max_f32_e32 v73, 0, v73
	v_addc_co_u32_e32 v79, vcc, 0, v129, vcc
	v_pk_add_f32 v[68:69], v[68:69], v[124:125]
	v_pk_add_f32 v[66:67], v[66:67], v[122:123]
	v_max_f32_e32 v64, 0, v64
	v_mul_f32_e32 v72, v72, v72
	v_mul_f32_e32 v73, v73, v73
	v_cvt_pk_bf16_f32 v76, v72, v73
	v_cvt_pk_bf16_f32 v77, v82, v83
	global_store_dwordx4 v[78:79], v[74:77], off
	v_pk_add_f32 v[70:71], v[70:71], v[126:127]
	v_max_f32_e32 v68, 0, v68
	v_mul_f32_e32 v74, v64, v64
	v_max_f32_e32 v64, 0, v69
	v_max_f32_e32 v65, 0, v65
	v_max_f32_e32 v66, 0, v66
	v_mul_f32_e32 v68, v68, v68
	v_mul_f32_e32 v64, v64, v64
	v_mul_f32_e32 v69, v65, v65
	v_max_f32_e32 v65, 0, v70
	v_mul_f32_e32 v70, v66, v66
	v_max_f32_e32 v66, 0, v71
	s_mov_b32 s5, 0x160000
	v_mul_f32_e32 v65, v65, v65
	v_mul_f32_e32 v66, v66, v66
	v_max_f32_e32 v67, 0, v67
	v_cvt_pk_bf16_f32 v64, v68, v64
	v_add_co_u32_e32 v68, vcc, s5, v128
	v_mul_f32_e32 v67, v67, v67
	v_cvt_pk_bf16_f32 v65, v65, v66
	v_cvt_pk_bf16_f32 v66, v74, v69
	s_nop 0
	v_addc_co_u32_e32 v69, vcc, 0, v129, vcc
	v_cvt_pk_bf16_f32 v67, v70, v67
	global_store_dwordx4 v[68:69], v[64:67], off
	s_nop 1
	v_mov_b32_e32 v64, v200
	v_mov_b32_e32 v65, v201
; __device__ __forceinline__ unsigned cvt_pk_bf16(float lo, float hi) { unsigned r; asm volatile("s_nop 0\n\tv_cvt_pk_bf16_f32 %0, %1, %2\n\ts_nop 1" : "=v"(r) : "v"(lo), "v"(hi)); return r; }
; #define PG8_WAIT_V(n) asm volatile("s_waitcnt vmcnt(" #n ")" ::: "memory")
; #define PG8_BAR __builtin_amdgcn_s_barrier()
; template <class Epi, class Sched>
; __device__ __forceinline__ void gemm_phase(PG8_LAS unsigned char* lds, const Gemm g, const Sched& S, const Epi& E, int tid_in) {
;     ...
;         if (!has_next) break;
; #pragma unroll
;         for (int a = 0; a < 2; ++a)
; #pragma unroll
;             for (int b = 0; b < 2; ++b)
; #pragma unroll
;                 for (int m = 0; m < 4; ++m)
; #pragma unroll
;                     for (int n = 0; n < 2; ++n) acc[a][b][m][n] = (f32x4){0.f, 0.f, 0.f, 0.f};
;         cur = nxt; cA = nA; cB = nB; ++ui;
;     }
;     PG8_WAIT_V(0);
;     if (wr == 0) PG8_BAR;
;     PG8_BAR;
;     __device__ __forceinline__ void operator()(f32x4 (&acc)[2][2][4][2], const Unit& u, int wr, int wc, int fr, int fq) const {
;     ...
;         for (int bj = 0; bj < 2; ++bj) { const f32x4 b0 = *(const f32x4*)(bias + col0 + bj * 128), b1 = *(const f32x4*)(bias + col0 + bj * 128 + 4);
; #pragma unroll
;             for (int ai = 0; ai < 2; ++ai)
; #pragma unroll
;                 for (int m = 0; m < 4; ++m) { f32x4 v0 = acc[ai][bj][m][0] + b0, v1 = acc[ai][bj][m][1] + b1;
; #pragma unroll
;                     for (int j = 0; j < 4; ++j) { v0[j] = fmaxf(v0[j], 0.f); v0[j] *= v0[j]; v1[j] = fmaxf(v1[j], 0.f); v1[j] *= v1[j]; }
;                     u32x4 w; w.x = cvt_pk_bf16(v0[0], v0[1]); w.y = cvt_pk_bf16(v0[2], v0[3]); w.z = cvt_pk_bf16(v1[0], v1[1]); w.w = cvt_pk_bf16(v1[2], v1[3]);
;                     *(u32x4*)(O + (size_t)(row0 + ai * 128 + m * 16) * 4096 + col0 + bj * 128) = w; } }
	v_mov_b32_e32 v66, v202
	v_mov_b32_e32 v67, v203
	v_mov_b32_e32 v68, v204
	v_mov_b32_e32 v69, v205
	v_mov_b32_e32 v70, v206
	v_mov_b32_e32 v71, v207
	v_lshl_add_u64 v[88:89], v[128:129], 0, s[22:23]
	s_mov_b64 s[22:23], 0x120000
	v_lshl_add_u64 v[80:81], v[128:129], 0, s[22:23]
	s_mov_b64 s[22:23], 0x140000
	v_lshl_add_u64 v[72:73], v[128:129], 0, s[22:23]
	s_mov_b64 s[22:23], 0x160000
	v_lshl_add_u64 v[74:75], v[128:129], 0, s[22:23]
	s_and_b64 vcc, exec, s[2:3]
	s_mov_b64 s[22:23], s[10:11]
	v_pk_add_f32 v[56:57], v[56:57], v[64:65]
	v_pk_add_f32 v[60:61], v[60:61], v[68:69]
	v_pk_add_f32 v[58:59], v[58:59], v[66:67]
	v_max_f32_e32 v56, 0, v56
	v_pk_add_f32 v[62:63], v[62:63], v[70:71]
	v_mul_f32_e32 v76, v56, v56
	v_max_f32_e32 v56, 0, v61
	v_max_f32_e32 v57, 0, v57
	v_max_f32_e32 v58, 0, v58
	v_max_f32_e32 v60, 0, v60
	v_mul_f32_e32 v56, v56, v56
	v_mul_f32_e32 v61, v57, v57
	v_max_f32_e32 v57, 0, v62
	v_mul_f32_e32 v62, v58, v58
	v_max_f32_e32 v58, 0, v63
	v_max_f32_e32 v59, 0, v59
	v_pk_add_f32 v[48:49], v[48:49], v[64:65]
	v_mul_f32_e32 v60, v60, v60
	v_mul_f32_e32 v57, v57, v57
	v_mul_f32_e32 v58, v58, v58
	v_mul_f32_e32 v59, v59, v59
	v_cvt_pk_bf16_f32 v56, v60, v56
	v_pk_add_f32 v[52:53], v[52:53], v[68:69]
	v_pk_add_f32 v[50:51], v[50:51], v[66:67]
	v_max_f32_e32 v48, 0, v48
	v_cvt_pk_bf16_f32 v57, v57, v58
	v_cvt_pk_bf16_f32 v58, v76, v61
	v_cvt_pk_bf16_f32 v59, v62, v59
	global_store_dwordx4 v[128:129], v[56:59], off offset:256
	v_pk_add_f32 v[54:55], v[54:55], v[70:71]
	v_max_f32_e32 v49, 0, v49
	v_mul_f32_e32 v56, v48, v48
	v_max_f32_e32 v48, 0, v53
	v_max_f32_e32 v50, 0, v50
	v_max_f32_e32 v52, 0, v52
	v_mul_f32_e32 v48, v48, v48
	v_mul_f32_e32 v53, v49, v49
	v_max_f32_e32 v49, 0, v54
	v_mul_f32_e32 v54, v50, v50
	v_max_f32_e32 v50, 0, v55
	v_max_f32_e32 v51, 0, v51
	v_pk_add_f32 v[40:41], v[40:41], v[64:65]
	v_mul_f32_e32 v52, v52, v52
	v_mul_f32_e32 v49, v49, v49
	v_mul_f32_e32 v50, v50, v50
	v_mul_f32_e32 v51, v51, v51
	v_cvt_pk_bf16_f32 v48, v52, v48
	v_pk_add_f32 v[44:45], v[44:45], v[68:69]
	v_pk_add_f32 v[42:43], v[42:43], v[66:67]
	v_max_f32_e32 v40, 0, v40
	v_cvt_pk_bf16_f32 v49, v49, v50
	v_cvt_pk_bf16_f32 v50, v56, v53
	v_cvt_pk_bf16_f32 v51, v54, v51
	global_store_dwordx4 v[112:113], v[48:51], off offset:256
	v_pk_add_f32 v[46:47], v[46:47], v[70:71]
	v_max_f32_e32 v41, 0, v41
	v_mul_f32_e32 v48, v40, v40
	v_max_f32_e32 v40, 0, v45
	v_max_f32_e32 v42, 0, v42
	v_max_f32_e32 v44, 0, v44
	v_mul_f32_e32 v40, v40, v40
	v_mul_f32_e32 v45, v41, v41
	v_max_f32_e32 v41, 0, v46
	v_mul_f32_e32 v46, v42, v42
	v_max_f32_e32 v42, 0, v47
	v_max_f32_e32 v43, 0, v43
	v_pk_add_f32 v[32:33], v[32:33], v[64:65]
	v_mul_f32_e32 v44, v44, v44
	v_mul_f32_e32 v41, v41, v41
	v_mul_f32_e32 v42, v42, v42
	v_mul_f32_e32 v43, v43, v43
	v_cvt_pk_bf16_f32 v40, v44, v40
	v_pk_add_f32 v[36:37], v[36:37], v[68:69]
	v_pk_add_f32 v[34:35], v[34:35], v[66:67]
	v_max_f32_e32 v32, 0, v32
	v_cvt_pk_bf16_f32 v41, v41, v42
	v_cvt_pk_bf16_f32 v42, v48, v45
	v_cvt_pk_bf16_f32 v43, v46, v43
	global_store_dwordx4 v[104:105], v[40:43], off offset:256
	v_pk_add_f32 v[38:39], v[38:39], v[70:71]
	v_max_f32_e32 v33, 0, v33
	v_mul_f32_e32 v40, v32, v32
	v_max_f32_e32 v32, 0, v37
	v_max_f32_e32 v34, 0, v34
	v_max_f32_e32 v36, 0, v36
	v_mul_f32_e32 v32, v32, v32
	v_mul_f32_e32 v37, v33, v33
	v_max_f32_e32 v33, 0, v38
	v_mul_f32_e32 v38, v34, v34
	v_max_f32_e32 v34, 0, v39
	v_max_f32_e32 v35, 0, v35
	v_pk_add_f32 v[24:25], v[24:25], v[64:65]
	v_mul_f32_e32 v36, v36, v36
	v_mul_f32_e32 v33, v33, v33
	v_mul_f32_e32 v34, v34, v34
	v_mul_f32_e32 v35, v35, v35
	v_cvt_pk_bf16_f32 v32, v36, v32
	v_pk_add_f32 v[28:29], v[28:29], v[68:69]
	v_pk_add_f32 v[26:27], v[26:27], v[66:67]
	v_max_f32_e32 v24, 0, v24
	v_cvt_pk_bf16_f32 v33, v33, v34
	v_cvt_pk_bf16_f32 v34, v40, v37
	v_cvt_pk_bf16_f32 v35, v38, v35
	global_store_dwordx4 v[96:97], v[32:35], off offset:256
	v_pk_add_f32 v[30:31], v[30:31], v[70:71]
	v_max_f32_e32 v25, 0, v25
	v_mul_f32_e32 v32, v24, v24
	v_max_f32_e32 v24, 0, v29
	v_max_f32_e32 v26, 0, v26
	v_max_f32_e32 v28, 0, v28
	v_mul_f32_e32 v24, v24, v24
	v_mul_f32_e32 v29, v25, v25
	v_max_f32_e32 v25, 0, v30
	v_mul_f32_e32 v30, v26, v26
	v_max_f32_e32 v26, 0, v31
	v_max_f32_e32 v27, 0, v27
	v_pk_add_f32 v[16:17], v[16:17], v[64:65]
	v_mul_f32_e32 v28, v28, v28
	v_mul_f32_e32 v25, v25, v25
	v_mul_f32_e32 v26, v26, v26
	v_mul_f32_e32 v27, v27, v27
	v_cvt_pk_bf16_f32 v24, v28, v24
	v_pk_add_f32 v[20:21], v[20:21], v[68:69]
	v_pk_add_f32 v[18:19], v[18:19], v[66:67]
	v_max_f32_e32 v16, 0, v16
	v_cvt_pk_bf16_f32 v25, v25, v26
	v_cvt_pk_bf16_f32 v26, v32, v29
	v_cvt_pk_bf16_f32 v27, v30, v27
	global_store_dwordx4 v[88:89], v[24:27], off offset:256
	v_pk_add_f32 v[22:23], v[22:23], v[70:71]
	v_max_f32_e32 v17, 0, v17
	v_mul_f32_e32 v24, v16, v16
	v_max_f32_e32 v16, 0, v21
	v_max_f32_e32 v18, 0, v18
	v_max_f32_e32 v20, 0, v20
	v_mul_f32_e32 v16, v16, v16
	v_mul_f32_e32 v21, v17, v17
	v_max_f32_e32 v17, 0, v22
	v_mul_f32_e32 v22, v18, v18
	v_max_f32_e32 v18, 0, v23
	v_max_f32_e32 v19, 0, v19
	v_pk_add_f32 v[8:9], v[8:9], v[64:65]
	v_mul_f32_e32 v20, v20, v20
	v_mul_f32_e32 v17, v17, v17
	v_mul_f32_e32 v18, v18, v18
	v_mul_f32_e32 v19, v19, v19
	v_cvt_pk_bf16_f32 v16, v20, v16
	v_pk_add_f32 v[12:13], v[12:13], v[68:69]
	v_pk_add_f32 v[10:11], v[10:11], v[66:67]
	v_max_f32_e32 v8, 0, v8
	v_cvt_pk_bf16_f32 v17, v17, v18
	v_cvt_pk_bf16_f32 v18, v24, v21
	v_cvt_pk_bf16_f32 v19, v22, v19
	global_store_dwordx4 v[80:81], v[16:19], off offset:256
	v_pk_add_f32 v[14:15], v[14:15], v[70:71]
	v_max_f32_e32 v9, 0, v9
	v_mul_f32_e32 v16, v8, v8
	v_max_f32_e32 v8, 0, v13
	v_max_f32_e32 v10, 0, v10
	v_max_f32_e32 v12, 0, v12
	v_mul_f32_e32 v8, v8, v8
	v_mul_f32_e32 v13, v9, v9
	v_max_f32_e32 v9, 0, v14
	v_mul_f32_e32 v14, v10, v10
	v_max_f32_e32 v10, 0, v15
	v_max_f32_e32 v11, 0, v11
	v_pk_add_f32 v[2:3], v[2:3], v[66:67]
	v_pk_add_f32 v[0:1], v[0:1], v[64:65]
	v_mul_f32_e32 v12, v12, v12
	v_mul_f32_e32 v9, v9, v9
	v_mul_f32_e32 v10, v10, v10
	v_mul_f32_e32 v11, v11, v11
	v_cvt_pk_bf16_f32 v8, v12, v8
	v_pk_add_f32 v[6:7], v[6:7], v[70:71]
	v_pk_add_f32 v[4:5], v[4:5], v[68:69]
	v_max_f32_e32 v0, 0, v0
	v_max_f32_e32 v1, 0, v1
	v_max_f32_e32 v2, 0, v2
	v_cvt_pk_bf16_f32 v9, v9, v10
	v_cvt_pk_bf16_f32 v10, v16, v13
	v_cvt_pk_bf16_f32 v11, v14, v11
	global_store_dwordx4 v[72:73], v[8:11], off offset:256
	v_max_f32_e32 v3, 0, v3
	v_max_f32_e32 v4, 0, v4
	v_mul_f32_e32 v8, v0, v0
	v_max_f32_e32 v0, 0, v5
	v_mul_f32_e32 v5, v1, v1
	v_max_f32_e32 v1, 0, v6
	v_mul_f32_e32 v6, v2, v2
	v_max_f32_e32 v2, 0, v7
	v_mul_f32_e32 v0, v0, v0
	v_mul_f32_e32 v1, v1, v1
	v_mul_f32_e32 v2, v2, v2
	v_mul_f32_e32 v3, v3, v3
	v_mul_f32_e32 v4, v4, v4
	v_cvt_pk_bf16_f32 v0, v4, v0
	v_cvt_pk_bf16_f32 v1, v1, v2
	v_cvt_pk_bf16_f32 v2, v8, v5
	v_cvt_pk_bf16_f32 v3, v6, v3
	s_nop 1
	global_store_dwordx4 v[74:75], v[0:3], off offset:256
	s_cbranch_vccz .LBB0_288
	s_waitcnt vmcnt(0)
	s_cmpk_gt_u32 s28, 0xff
	s_cbranch_scc1 .LBB0_299
	s_barrier

; #define PG8_STAGE(bufoff, gbase, voff) do { _Pragma("unroll") for (int _i = 0; _i < 2; ++_i) \
;         __builtin_amdgcn_global_load_lds((const unsigned*)((const char*)(gbase) + (voff)[_i]), (PG8_LAS unsigned*)(lds + (bufoff) + ldsw + _i * 8192), 16, 0, 0); } while (0)
; #define PG8_LDA(dst, b, h) do { _Pragma("unroll") for (int m = 0; m < 4; ++m) _Pragma("unroll") for (int k = 0; k < 2; ++k) dst[m][k] = *(const PG8_LAS bf16x8*)(lds + PG8_SA(b, h) + aoff + m * 2048 + k * 1024); } while (0)
; #define PG8_LDB(dst, b, h) do { _Pragma("unroll") for (int n = 0; n < 2; ++n) _Pragma("unroll") for (int k = 0; k < 2; ++k) dst[n][k] = *(const PG8_LAS bf16x8*)(lds + PG8_SB(b, h) + boff + n * 2048 + k * 1024); } while (0)
; #define PG8_MMA(ai, bj, At, Bt) do { __builtin_amdgcn_s_setprio(1); _Pragma("unroll") for (int m = 0; m < 4; ++m) _Pragma("unroll") for (int n = 0; n < 2; ++n) _Pragma("unroll") for (int k = 0; k < 2; ++k) \
;         acc[ai][bj][m][n] = __builtin_amdgcn_mfma_f32_16x16x32_bf16(Bt[n][k], At[m][k], acc[ai][bj][m][n], 0, 0, 0); __builtin_amdgcn_s_setprio(0); } while (0)
; #define PG8_WAIT_L(n) asm volatile("s_waitcnt lgkmcnt(" #n ")" ::: "memory")
; #define PG8_BAR __builtin_amdgcn_s_barrier()
; #define PG8_SCHED __builtin_amdgcn_sched_barrier(0)
; template <class Epi, class Sched>
; __device__ __forceinline__ void gemm_phase(PG8_LAS unsigned char* lds, const Gemm g, const Sched& S, const Epi& E, int tid_in) {
;     ...
;         for (int t = 0; t < nt; t += 2) {
;             const bool last = (t == nt - 2);
;             const char* a1 = cA + (size_t)(t + 1) * kstep;
;             const char* a2 = last ? nA : cA + (size_t)(t + 2) * kstep; const char* b2 = last ? nB : cB + (size_t)(t + 2) * kstep;
;             const char* a3 = a2 + kstep; const char* b3 = b2 + kstep;
;             if (last && has_next) S.a_ready(nxt);
;             PG8_LDB(B0, 0, 0); PG8_SCHED; PG8_LDA(At, 0, 0); PG8_STAGE(PG8_SA(1, 1), a1 + hstep, voffA);
;             PG8_WAIT_L(8); PG8_BAR; PG8_WAIT_L(0); PG8_MMA(0, 0, At, B0); PG8_BAR; PG8_SCHED;
;             PG8_LDB(B1, 0, 1); PG8_STAGE(PG8_SB(0, 0), b2, voffB);
;             PG8_BAR; PG8_WAIT_L(0); PG8_MMA(0, 1, At, B1); PG8_BAR;
;             PG8_LDA(At, 0, 1); PG8_STAGE(PG8_SA(0, 0), a2, voffA);
;             PG8_BAR; PG8_WAIT_L(0); PG8_MMA(1, 0, At, B0); PG8_BAR; PG8_SCHED;
.LBB0_325:
	s_add_u32 s16, s14, 0x100
	s_addc_u32 s17, s15, 0
	s_add_i32 s46, 0, 0x10000
	v_add_u32_e32 v138, s46, v141
	ds_read_b128 v[128:131], v138
	ds_read_b128 v[144:147], v138 offset:1024
	ds_read_b128 v[148:151], v138 offset:2048
	ds_read_b128 v[152:155], v138 offset:3072
	s_cmp_eq_u32 s45, 12
	s_cselect_b32 s21, s7, s17
	s_cselect_b32 s20, s41, s16
	s_cselect_b32 s19, s5, s44
	s_cselect_b32 s18, s42, s43
	v_lshl_add_u64 v[138:139], s[14:15], 0, v[134:135]
	s_add_i32 m0, s13, 0xc000
	ds_read_b128 v[156:159], v143
	ds_read_b128 v[160:163], v143 offset:1024
	ds_read_b128 v[164:167], v143 offset:2048
	ds_read_b128 v[168:171], v143 offset:3072
	ds_read_b128 v[172:175], v143 offset:4096
	ds_read_b128 v[176:179], v143 offset:5120
	ds_read_b128 v[180:183], v143 offset:6144
	ds_read_b128 v[184:187], v143 offset:7168
	global_load_lds_dwordx4 v[138:139], off
	s_add_i32 m0, s13, 0xe000
	v_lshl_add_u64 v[138:139], s[14:15], 0, v[136:137]
	global_load_lds_dwordx4 v[138:139], off
	s_waitcnt lgkmcnt(8)
	s_barrier
	s_waitcnt lgkmcnt(0)
	s_waitcnt lgkmcnt(0)
	v_mfma_f32_16x16x32_bf16 v[124:127], v[128:131], v[156:159], v[124:127]
	v_mfma_f32_16x16x32_bf16 v[92:95], v[148:151], v[156:159], v[92:95]
	v_mfma_f32_16x16x32_bf16 v[120:123], v[128:131], v[164:167], v[120:123]
	v_mfma_f32_16x16x32_bf16 v[88:91], v[148:151], v[164:167], v[88:91]
	v_mfma_f32_16x16x32_bf16 v[116:119], v[128:131], v[172:175], v[116:119]
	v_mfma_f32_16x16x32_bf16 v[84:87], v[148:151], v[172:175], v[84:87]
	v_mfma_f32_16x16x32_bf16 v[112:115], v[128:131], v[180:183], v[112:115]
	v_mfma_f32_16x16x32_bf16 v[80:83], v[148:151], v[180:183], v[80:83]
	v_mfma_f32_16x16x32_bf16 v[124:127], v[144:147], v[160:163], v[124:127]
	v_mfma_f32_16x16x32_bf16 v[92:95], v[152:155], v[160:163], v[92:95]
	v_mfma_f32_16x16x32_bf16 v[120:123], v[144:147], v[168:171], v[120:123]
	v_mfma_f32_16x16x32_bf16 v[88:91], v[152:155], v[168:171], v[88:91]
	v_mfma_f32_16x16x32_bf16 v[116:119], v[144:147], v[176:179], v[116:119]
	v_mfma_f32_16x16x32_bf16 v[84:87], v[152:155], v[176:179], v[84:87]
	v_mfma_f32_16x16x32_bf16 v[112:115], v[144:147], v[184:187], v[112:115]
	v_mfma_f32_16x16x32_bf16 v[80:83], v[152:155], v[184:187], v[80:83]
	s_barrier
	s_add_i32 s48, 0, 0x14000
	v_add_u32_e32 v138, s48, v141
	s_add_i32 s14, s46, s28
	ds_read_b128 v[188:191], v138
	ds_read_b128 v[194:197], v138 offset:1024
	ds_read_b128 v[200:203], v138 offset:2048
	ds_read_b128 v[204:207], v138 offset:3072
	v_lshl_add_u64 v[138:139], s[18:19], 0, v[192:193]
	s_mov_b32 m0, s14
	v_lshl_add_u64 v[208:209], s[18:19], 0, v[132:133]
	global_load_lds_dwordx4 v[138:139], off
	s_add_i32 m0, s14, 0x2000
	s_nop 0
	global_load_lds_dwordx4 v[208:209], off
	s_barrier
	s_waitcnt lgkmcnt(0)
	s_waitcnt lgkmcnt(0)
	v_mfma_f32_16x16x32_bf16 v[60:63], v[188:191], v[156:159], v[60:63]
	v_mfma_f32_16x16x32_bf16 v[28:31], v[200:203], v[156:159], v[28:31]
	v_mfma_f32_16x16x32_bf16 v[56:59], v[188:191], v[164:167], v[56:59]
	v_mfma_f32_16x16x32_bf16 v[24:27], v[200:203], v[164:167], v[24:27]
	v_mfma_f32_16x16x32_bf16 v[52:55], v[188:191], v[172:175], v[52:55]
	v_mfma_f32_16x16x32_bf16 v[20:23], v[200:203], v[172:175], v[20:23]
	v_mfma_f32_16x16x32_bf16 v[48:51], v[188:191], v[180:183], v[48:51]
	v_mfma_f32_16x16x32_bf16 v[16:19], v[200:203], v[180:183], v[16:19]
	v_mfma_f32_16x16x32_bf16 v[60:63], v[194:197], v[160:163], v[60:63]
	v_mfma_f32_16x16x32_bf16 v[28:31], v[204:207], v[160:163], v[28:31]
	v_mfma_f32_16x16x32_bf16 v[56:59], v[194:197], v[168:171], v[56:59]
	v_mfma_f32_16x16x32_bf16 v[24:27], v[204:207], v[168:171], v[24:27]
	v_mfma_f32_16x16x32_bf16 v[52:55], v[194:197], v[176:179], v[52:55]
	v_mfma_f32_16x16x32_bf16 v[20:23], v[204:207], v[176:179], v[20:23]
	v_mfma_f32_16x16x32_bf16 v[48:51], v[194:197], v[184:187], v[48:51]
	v_mfma_f32_16x16x32_bf16 v[16:19], v[204:207], v[184:187], v[16:19]
	s_mov_b32 m0, s13
	v_lshl_add_u64 v[210:211], s[20:21], 0, v[192:193]
	s_barrier
	ds_read_b128 v[156:159], v143 offset:16384
	ds_read_b128 v[160:163], v143 offset:17408
	ds_read_b128 v[164:167], v143 offset:18432
	ds_read_b128 v[168:171], v143 offset:19456
	ds_read_b128 v[172:175], v143 offset:20480
	ds_read_b128 v[176:179], v143 offset:21504
	ds_read_b128 v[180:183], v143 offset:22528
	ds_read_b128 v[184:187], v143 offset:23552
	global_load_lds_dwordx4 v[210:211], off
	s_mov_b32 m0, s29
	v_lshl_add_u64 v[212:213], s[20:21], 0, v[132:133]
	global_load_lds_dwordx4 v[212:213], off
	s_barrier
	s_waitcnt lgkmcnt(0)
	s_waitcnt lgkmcnt(0)
	v_mfma_f32_16x16x32_bf16 v[108:111], v[128:131], v[156:159], v[108:111]
	v_mfma_f32_16x16x32_bf16 v[76:79], v[148:151], v[156:159], v[76:79]
	v_mfma_f32_16x16x32_bf16 v[104:107], v[128:131], v[164:167], v[104:107]
	v_mfma_f32_16x16x32_bf16 v[72:75], v[148:151], v[164:167], v[72:75]
	v_mfma_f32_16x16x32_bf16 v[100:103], v[128:131], v[172:175], v[100:103]
	v_mfma_f32_16x16x32_bf16 v[68:71], v[148:151], v[172:175], v[68:71]
	v_mfma_f32_16x16x32_bf16 v[96:99], v[128:131], v[180:183], v[96:99]
	v_mfma_f32_16x16x32_bf16 v[64:67], v[148:151], v[180:183], v[64:67]
	v_mfma_f32_16x16x32_bf16 v[108:111], v[144:147], v[160:163], v[108:111]
	v_mfma_f32_16x16x32_bf16 v[76:79], v[152:155], v[160:163], v[76:79]
	v_mfma_f32_16x16x32_bf16 v[104:107], v[144:147], v[168:171], v[104:107]
	v_mfma_f32_16x16x32_bf16 v[72:75], v[152:155], v[168:171], v[72:75]
	v_mfma_f32_16x16x32_bf16 v[100:103], v[144:147], v[176:179], v[100:103]
	v_mfma_f32_16x16x32_bf16 v[68:71], v[152:155], v[176:179], v[68:71]
	v_mfma_f32_16x16x32_bf16 v[96:99], v[144:147], v[184:187], v[96:99]
	v_mfma_f32_16x16x32_bf16 v[64:67], v[152:155], v[184:187], v[64:67]
	s_barrier
; #define PG8_STAGE(bufoff, gbase, voff) do { _Pragma("unroll") for (int _i = 0; _i < 2; ++_i) \
;         __builtin_amdgcn_global_load_lds((const unsigned*)((const char*)(gbase) + (voff)[_i]), (PG8_LAS unsigned*)(lds + (bufoff) + ldsw + _i * 8192), 16, 0, 0); } while (0)
; #define PG8_LDA(dst, b, h) do { _Pragma("unroll") for (int m = 0; m < 4; ++m) _Pragma("unroll") for (int k = 0; k < 2; ++k) dst[m][k] = *(const PG8_LAS bf16x8*)(lds + PG8_SA(b, h) + aoff + m * 2048 + k * 1024); } while (0)
; #define PG8_LDB(dst, b, h) do { _Pragma("unroll") for (int n = 0; n < 2; ++n) _Pragma("unroll") for (int k = 0; k < 2; ++k) dst[n][k] = *(const PG8_LAS bf16x8*)(lds + PG8_SB(b, h) + boff + n * 2048 + k * 1024); } while (0)
; #define PG8_MMA(ai, bj, At, Bt) do { __builtin_amdgcn_s_setprio(1); _Pragma("unroll") for (int m = 0; m < 4; ++m) _Pragma("unroll") for (int n = 0; n < 2; ++n) _Pragma("unroll") for (int k = 0; k < 2; ++k) \
;         acc[ai][bj][m][n] = __builtin_amdgcn_mfma_f32_16x16x32_bf16(Bt[n][k], At[m][k], acc[ai][bj][m][n], 0, 0, 0); __builtin_amdgcn_s_setprio(0); } while (0)
; #define PG8_WAIT_V(n) asm volatile("s_waitcnt vmcnt(" #n ")" ::: "memory")
; #define PG8_WAIT_L(n) asm volatile("s_waitcnt lgkmcnt(" #n ")" ::: "memory")
; #define PG8_BAR __builtin_amdgcn_s_barrier()
; #define PG8_SCHED __builtin_amdgcn_sched_barrier(0)
; template <class Epi, class Sched>
; __device__ __forceinline__ void gemm_phase(PG8_LAS unsigned char* lds, const Gemm g, const Sched& S, const Epi& E, int tid_in) {
;     ...
;             PG8_STAGE(PG8_SB(0, 1), b2 + hstep, voffB);
;             PG8_WAIT_V(6); PG8_BAR; PG8_MMA(1, 1, At, B1); PG8_BAR;
;             PG8_LDB(B0, 1, 0); PG8_SCHED; PG8_LDA(At, 1, 0); PG8_STAGE(PG8_SA(0, 1), a2 + hstep, voffA);
;             PG8_WAIT_L(8); PG8_BAR; PG8_WAIT_L(0); PG8_MMA(0, 0, At, B0); PG8_BAR; PG8_SCHED;
;             PG8_LDB(B1, 1, 1); PG8_STAGE(PG8_SB(1, 0), b3, voffB);
;             PG8_BAR; PG8_WAIT_L(0); PG8_MMA(0, 1, At, B1); PG8_BAR;
;             PG8_LDA(At, 1, 1); PG8_STAGE(PG8_SA(1, 0), a3, voffA);
	s_add_u32 s14, s18, 0x40000
	s_addc_u32 s15, s19, 0
	s_add_i32 s46, s48, s28
	s_mov_b32 m0, s46
	v_lshl_add_u64 v[128:129], s[14:15], 0, v[192:193]
	global_load_lds_dwordx4 v[128:129], off
	s_add_i32 m0, s46, 0x2000
	v_lshl_add_u64 v[128:129], s[14:15], 0, v[132:133]
	global_load_lds_dwordx4 v[128:129], off
	s_waitcnt vmcnt(6)
	s_barrier
	v_mfma_f32_16x16x32_bf16 v[44:47], v[188:191], v[156:159], v[44:47]
	v_mfma_f32_16x16x32_bf16 v[12:15], v[200:203], v[156:159], v[12:15]
	v_mfma_f32_16x16x32_bf16 v[40:43], v[188:191], v[164:167], v[40:43]
	v_mfma_f32_16x16x32_bf16 v[8:11], v[200:203], v[164:167], v[8:11]
	v_mfma_f32_16x16x32_bf16 v[36:39], v[188:191], v[172:175], v[36:39]
	v_mfma_f32_16x16x32_bf16 v[4:7], v[200:203], v[172:175], v[4:7]
	v_mfma_f32_16x16x32_bf16 v[32:35], v[188:191], v[180:183], v[32:35]
	v_mfma_f32_16x16x32_bf16 v[0:3], v[200:203], v[180:183], v[0:3]
	v_mfma_f32_16x16x32_bf16 v[44:47], v[194:197], v[160:163], v[44:47]
	v_mfma_f32_16x16x32_bf16 v[12:15], v[204:207], v[160:163], v[12:15]
	v_mfma_f32_16x16x32_bf16 v[40:43], v[194:197], v[168:171], v[40:43]
	v_mfma_f32_16x16x32_bf16 v[8:11], v[204:207], v[168:171], v[8:11]
	v_mfma_f32_16x16x32_bf16 v[36:39], v[194:197], v[176:179], v[36:39]
	v_mfma_f32_16x16x32_bf16 v[4:7], v[204:207], v[176:179], v[4:7]
	v_mfma_f32_16x16x32_bf16 v[32:35], v[194:197], v[184:187], v[32:35]
	v_mfma_f32_16x16x32_bf16 v[0:3], v[204:207], v[184:187], v[0:3]
	s_add_i32 s46, 0, 0x18000
	v_add_u32_e32 v152, s46, v141
	s_barrier
	ds_read_b128 v[128:131], v152
	ds_read_b128 v[144:147], v152 offset:1024
	ds_read_b128 v[148:151], v152 offset:2048
	ds_read_b128 v[152:155], v152 offset:3072
	s_add_u32 s14, s20, 0x40000
	s_addc_u32 s15, s21, 0
	s_mov_b32 m0, s30
	v_lshl_add_u64 v[188:189], s[14:15], 0, v[192:193]
	ds_read_b128 v[156:159], v143 offset:32768
	ds_read_b128 v[160:163], v143 offset:33792
	ds_read_b128 v[164:167], v143 offset:34816
	ds_read_b128 v[168:171], v143 offset:35840
	ds_read_b128 v[172:175], v143 offset:36864
	ds_read_b128 v[176:179], v143 offset:37888
	ds_read_b128 v[180:183], v143 offset:38912
	ds_read_b128 v[184:187], v143 offset:39936
	global_load_lds_dwordx4 v[188:189], off
	s_mov_b32 m0, s31
	v_lshl_add_u64 v[188:189], s[14:15], 0, v[132:133]
	global_load_lds_dwordx4 v[188:189], off
	s_waitcnt lgkmcnt(8)
	s_barrier
	s_waitcnt lgkmcnt(0)
	s_waitcnt lgkmcnt(0)
	v_mfma_f32_16x16x32_bf16 v[124:127], v[128:131], v[156:159], v[124:127]
	v_mfma_f32_16x16x32_bf16 v[92:95], v[148:151], v[156:159], v[92:95]
	v_mfma_f32_16x16x32_bf16 v[120:123], v[128:131], v[164:167], v[120:123]
	v_mfma_f32_16x16x32_bf16 v[88:91], v[148:151], v[164:167], v[88:91]
	v_mfma_f32_16x16x32_bf16 v[116:119], v[128:131], v[172:175], v[116:119]
	v_mfma_f32_16x16x32_bf16 v[84:87], v[148:151], v[172:175], v[84:87]
	v_mfma_f32_16x16x32_bf16 v[112:115], v[128:131], v[180:183], v[112:115]
	v_mfma_f32_16x16x32_bf16 v[80:83], v[148:151], v[180:183], v[80:83]
	v_mfma_f32_16x16x32_bf16 v[124:127], v[144:147], v[160:163], v[124:127]
	v_mfma_f32_16x16x32_bf16 v[92:95], v[152:155], v[160:163], v[92:95]
	v_mfma_f32_16x16x32_bf16 v[120:123], v[144:147], v[168:171], v[120:123]
	v_mfma_f32_16x16x32_bf16 v[88:91], v[152:155], v[168:171], v[88:91]
	v_mfma_f32_16x16x32_bf16 v[116:119], v[144:147], v[176:179], v[116:119]
	v_mfma_f32_16x16x32_bf16 v[84:87], v[152:155], v[176:179], v[84:87]
	v_mfma_f32_16x16x32_bf16 v[112:115], v[144:147], v[184:187], v[112:115]
	v_mfma_f32_16x16x32_bf16 v[80:83], v[152:155], v[184:187], v[80:83]
	s_barrier
	s_add_i32 s20, 0, 0x1c000
	s_add_i32 s14, s46, s28
	v_add_u32_e32 v199, s20, v141
	v_lshl_add_u64 v[138:139], v[138:139], 0, s[74:75]
	s_mov_b32 m0, s14
	ds_read_b128 v[188:191], v199
	ds_read_b128 v[194:197], v199 offset:1024
	ds_read_b128 v[200:203], v199 offset:2048
	ds_read_b128 v[204:207], v199 offset:3072
	global_load_lds_dwordx4 v[138:139], off
	s_add_i32 m0, s14, 0x2000
	v_lshl_add_u64 v[138:139], v[208:209], 0, s[74:75]
	global_load_lds_dwordx4 v[138:139], off
	s_barrier
	s_waitcnt lgkmcnt(0)
	s_waitcnt lgkmcnt(0)
	v_mfma_f32_16x16x32_bf16 v[60:63], v[188:191], v[156:159], v[60:63]
	v_mfma_f32_16x16x32_bf16 v[28:31], v[200:203], v[156:159], v[28:31]
	v_mfma_f32_16x16x32_bf16 v[56:59], v[188:191], v[164:167], v[56:59]
	v_mfma_f32_16x16x32_bf16 v[24:27], v[200:203], v[164:167], v[24:27]
	v_mfma_f32_16x16x32_bf16 v[52:55], v[188:191], v[172:175], v[52:55]
	v_mfma_f32_16x16x32_bf16 v[20:23], v[200:203], v[172:175], v[20:23]
	v_mfma_f32_16x16x32_bf16 v[48:51], v[188:191], v[180:183], v[48:51]
	v_mfma_f32_16x16x32_bf16 v[16:19], v[200:203], v[180:183], v[16:19]
	v_mfma_f32_16x16x32_bf16 v[60:63], v[194:197], v[160:163], v[60:63]
	v_mfma_f32_16x16x32_bf16 v[28:31], v[204:207], v[160:163], v[28:31]
	v_mfma_f32_16x16x32_bf16 v[56:59], v[194:197], v[168:171], v[56:59]
	v_mfma_f32_16x16x32_bf16 v[24:27], v[204:207], v[168:171], v[24:27]
	v_mfma_f32_16x16x32_bf16 v[52:55], v[194:197], v[176:179], v[52:55]
	v_mfma_f32_16x16x32_bf16 v[20:23], v[204:207], v[176:179], v[20:23]
	v_mfma_f32_16x16x32_bf16 v[48:51], v[194:197], v[184:187], v[48:51]
	v_mfma_f32_16x16x32_bf16 v[16:19], v[204:207], v[184:187], v[16:19]
	s_mov_b32 m0, s38
	v_lshl_add_u64 v[138:139], v[210:211], 0, s[74:75]
	s_barrier
	ds_read_b128 v[156:159], v143 offset:49152
	ds_read_b128 v[160:163], v143 offset:50176
	ds_read_b128 v[164:167], v143 offset:51200
	ds_read_b128 v[168:171], v143 offset:52224
	ds_read_b128 v[172:175], v143 offset:53248
	ds_read_b128 v[176:179], v143 offset:54272
	ds_read_b128 v[180:183], v143 offset:55296
	ds_read_b128 v[184:187], v143 offset:56320
	global_load_lds_dwordx4 v[138:139], off
	s_mov_b32 m0, s39
	v_lshl_add_u64 v[138:139], v[212:213], 0, s[74:75]
	global_load_lds_dwordx4 v[138:139], off
	s_barrier
; __device__ __forceinline__ unsigned cvt_pk_bf16(float lo, float hi) { unsigned r; asm volatile("s_nop 0\n\tv_cvt_pk_bf16_f32 %0, %1, %2\n\ts_nop 1" : "=v"(r) : "v"(lo), "v"(hi)); return r; }
; #define PG8_STAGE(bufoff, gbase, voff) do { _Pragma("unroll") for (int _i = 0; _i < 2; ++_i) \
;         __builtin_amdgcn_global_load_lds((const unsigned*)((const char*)(gbase) + (voff)[_i]), (PG8_LAS unsigned*)(lds + (bufoff) + ldsw + _i * 8192), 16, 0, 0); } while (0)
; #define PG8_MMA(ai, bj, At, Bt) do { __builtin_amdgcn_s_setprio(1); _Pragma("unroll") for (int m = 0; m < 4; ++m) _Pragma("unroll") for (int n = 0; n < 2; ++n) _Pragma("unroll") for (int k = 0; k < 2; ++k) \
;         acc[ai][bj][m][n] = __builtin_amdgcn_mfma_f32_16x16x32_bf16(Bt[n][k], At[m][k], acc[ai][bj][m][n], 0, 0, 0); __builtin_amdgcn_s_setprio(0); } while (0)
; #define PG8_WAIT_V(n) asm volatile("s_waitcnt vmcnt(" #n ")" ::: "memory")
; #define PG8_WAIT_L(n) asm volatile("s_waitcnt lgkmcnt(" #n ")" ::: "memory")
; #define PG8_BAR __builtin_amdgcn_s_barrier()
; template <class Epi, class Sched>
; __device__ __forceinline__ void gemm_phase(PG8_LAS unsigned char* lds, const Gemm g, const Sched& S, const Epi& E, int tid_in) {
;     ...
;             PG8_BAR; PG8_WAIT_L(0); PG8_MMA(1, 0, At, B0); PG8_BAR; PG8_SCHED;
;             PG8_STAGE(PG8_SB(1, 1), b3 + hstep, voffB);
;             PG8_WAIT_V(6); PG8_BAR; PG8_MMA(1, 1, At, B1); PG8_BAR;
;         }
;     __device__ __forceinline__ void operator()(f32x4 (&acc)[2][2][4][2], const Unit& u, int wr, int wc, int fr, int fq) const {
;         const int row0 = u.pm * 256 + wr * 64 + fr, col0 = u.pn * 256 + wc * 32 + 4 * fq;
;         const float* gr = gate + (size_t)(bbase + (u.pm * 256) / SEQ) * MODW;
; #pragma unroll
;         for (int bj = 0; bj < 2; ++bj)
; #pragma unroll
;             for (int n = 0; n < 2; ++n) { const int col = col0 + bj * 128 + n * 16; const f32x4 gv = *(const f32x4*)(gr + col);
;                 f32x4 bv = (f32x4){0.f, 0.f, 0.f, 0.f}; if (bias) bv = *(const f32x4*)(bias + col);
; #pragma unroll
;                 for (int ai = 0; ai < 2; ++ai)
; #pragma unroll
;                     for (int m = 0; m < 4; ++m) { const size_t row = row0 + ai * 128 + m * 16;
;                         const f32x4 o = gv * (acc[ai][bj][m][n] + bv); u32x2 w; w.x = cvt_pk_bf16(o[0], o[1]); w.y = cvt_pk_bf16(o[2], o[3]);
	s_waitcnt lgkmcnt(0)
	s_waitcnt lgkmcnt(0)
	v_mfma_f32_16x16x32_bf16 v[108:111], v[128:131], v[156:159], v[108:111]
	v_mfma_f32_16x16x32_bf16 v[76:79], v[148:151], v[156:159], v[76:79]
	v_mfma_f32_16x16x32_bf16 v[104:107], v[128:131], v[164:167], v[104:107]
	v_mfma_f32_16x16x32_bf16 v[72:75], v[148:151], v[164:167], v[72:75]
	v_mfma_f32_16x16x32_bf16 v[100:103], v[128:131], v[172:175], v[100:103]
	v_mfma_f32_16x16x32_bf16 v[68:71], v[148:151], v[172:175], v[68:71]
	v_mfma_f32_16x16x32_bf16 v[96:99], v[128:131], v[180:183], v[96:99]
	v_mfma_f32_16x16x32_bf16 v[64:67], v[148:151], v[180:183], v[64:67]
	v_mfma_f32_16x16x32_bf16 v[108:111], v[144:147], v[160:163], v[108:111]
	v_mfma_f32_16x16x32_bf16 v[76:79], v[152:155], v[160:163], v[76:79]
	v_mfma_f32_16x16x32_bf16 v[104:107], v[144:147], v[168:171], v[104:107]
	v_mfma_f32_16x16x32_bf16 v[72:75], v[152:155], v[168:171], v[72:75]
	v_mfma_f32_16x16x32_bf16 v[100:103], v[144:147], v[176:179], v[100:103]
	v_mfma_f32_16x16x32_bf16 v[68:71], v[152:155], v[176:179], v[68:71]
	v_mfma_f32_16x16x32_bf16 v[96:99], v[144:147], v[184:187], v[96:99]
	v_mfma_f32_16x16x32_bf16 v[64:67], v[152:155], v[184:187], v[64:67]
	s_barrier
	s_add_u32 s14, s18, 0x40080
	s_addc_u32 s15, s19, 0
	s_add_i32 s18, s20, s28
	s_mov_b32 m0, s18
	v_lshl_add_u64 v[128:129], s[14:15], 0, v[192:193]
	global_load_lds_dwordx4 v[128:129], off
	s_add_i32 m0, s18, 0x2000
	v_lshl_add_u64 v[128:129], s[14:15], 0, v[132:133]
	global_load_lds_dwordx4 v[128:129], off
	s_waitcnt vmcnt(6)
	s_barrier
	v_mfma_f32_16x16x32_bf16 v[44:47], v[188:191], v[156:159], v[44:47]
	v_mfma_f32_16x16x32_bf16 v[12:15], v[200:203], v[156:159], v[12:15]
	v_mfma_f32_16x16x32_bf16 v[40:43], v[188:191], v[164:167], v[40:43]
	v_mfma_f32_16x16x32_bf16 v[8:11], v[200:203], v[164:167], v[8:11]
	v_mfma_f32_16x16x32_bf16 v[36:39], v[188:191], v[172:175], v[36:39]
	v_mfma_f32_16x16x32_bf16 v[4:7], v[200:203], v[172:175], v[4:7]
	v_mfma_f32_16x16x32_bf16 v[32:35], v[188:191], v[180:183], v[32:35]
	v_mfma_f32_16x16x32_bf16 v[0:3], v[200:203], v[180:183], v[0:3]
	v_mfma_f32_16x16x32_bf16 v[44:47], v[194:197], v[160:163], v[44:47]
	v_mfma_f32_16x16x32_bf16 v[12:15], v[204:207], v[160:163], v[12:15]
	v_mfma_f32_16x16x32_bf16 v[40:43], v[194:197], v[168:171], v[40:43]
	v_mfma_f32_16x16x32_bf16 v[8:11], v[204:207], v[168:171], v[8:11]
	v_mfma_f32_16x16x32_bf16 v[36:39], v[194:197], v[176:179], v[36:39]
	v_mfma_f32_16x16x32_bf16 v[4:7], v[204:207], v[176:179], v[4:7]
	v_mfma_f32_16x16x32_bf16 v[32:35], v[194:197], v[184:187], v[32:35]
	v_mfma_f32_16x16x32_bf16 v[0:3], v[204:207], v[184:187], v[0:3]
	s_add_i32 s45, s45, 2
	s_add_u32 s43, s43, 0x100
	s_addc_u32 s44, s44, 0
	s_cmp_gt_u32 s45, 13
	s_mov_b64 s[14:15], s[16:17]
	s_barrier
	s_cbranch_scc0 .LBB0_325
	s_ashr_i32 s5, s12, 31
	s_lshr_b32 s5, s5, 29
	s_add_i32 s5, s12, s5
	s_ashr_i32 s5, s5, 3
	s_add_i32 s5, s5, s76
	s_mul_hi_i32 s7, s5, 0x6000
	s_mulk_i32 s5, 0x6000
	v_lshl_or_b32 v146, s33, 8, v142
	s_add_u32 s14, s36, s5
	s_addc_u32 s15, s37, s7
	v_ashrrev_i32_e32 v147, 31, v146
	v_lshl_add_u64 v[138:139], v[146:147], 2, s[14:15]
	global_load_dwordx4 v[128:131], v[138:139], off
	global_load_dwordx4 v[152:155], v[138:139], off offset:64
	global_load_dwordx4 v[156:159], v[138:139], off offset:512
	global_load_dwordx4 v[160:163], v[138:139], off offset:576
	v_lshl_add_u32 v144, s12, 8, v140
	v_pk_add_f32 v[124:125], v[124:125], 0 op_sel_hi:[1,0]
	v_ashrrev_i32_e32 v145, 31, v144
	v_pk_add_f32 v[126:127], v[126:127], 0 op_sel_hi:[1,0]
	v_pk_add_f32 v[120:121], v[120:121], 0 op_sel_hi:[1,0]
	v_pk_add_f32 v[122:123], v[122:123], 0 op_sel_hi:[1,0]
	v_pk_add_f32 v[116:117], v[116:117], 0 op_sel_hi:[1,0]
	v_pk_add_f32 v[118:119], v[118:119], 0 op_sel_hi:[1,0]
	v_pk_add_f32 v[112:113], v[112:113], 0 op_sel_hi:[1,0]
	v_pk_add_f32 v[114:115], v[114:115], 0 op_sel_hi:[1,0]
	v_pk_add_f32 v[110:111], v[110:111], 0 op_sel_hi:[1,0]
	v_pk_add_f32 v[108:109], v[108:109], 0 op_sel_hi:[1,0]
	v_pk_add_f32 v[106:107], v[106:107], 0 op_sel_hi:[1,0]
	v_pk_add_f32 v[104:105], v[104:105], 0 op_sel_hi:[1,0]
	v_pk_add_f32 v[102:103], v[102:103], 0 op_sel_hi:[1,0]
	v_pk_add_f32 v[100:101], v[100:101], 0 op_sel_hi:[1,0]
	v_pk_add_f32 v[98:99], v[98:99], 0 op_sel_hi:[1,0]
	v_pk_add_f32 v[96:97], v[96:97], 0 op_sel_hi:[1,0]
	s_mov_b32 s5, 0x58000
	s_mov_b64 s[14:15], 0x40000
	v_pk_add_f32 v[92:93], v[92:93], 0 op_sel_hi:[1,0]
	v_pk_add_f32 v[88:89], v[88:89], 0 op_sel_hi:[1,0]
	v_pk_add_f32 v[84:85], v[84:85], 0 op_sel_hi:[1,0]
	v_pk_add_f32 v[80:81], v[80:81], 0 op_sel_hi:[1,0]
	v_pk_add_f32 v[76:77], v[76:77], 0 op_sel_hi:[1,0]
	v_pk_add_f32 v[72:73], v[72:73], 0 op_sel_hi:[1,0]
	v_pk_add_f32 v[68:69], v[68:69], 0 op_sel_hi:[1,0]
	v_pk_add_f32 v[64:65], v[64:65], 0 op_sel_hi:[1,0]
	v_pk_add_f32 v[94:95], v[94:95], 0 op_sel_hi:[1,0]
	v_pk_add_f32 v[90:91], v[90:91], 0 op_sel_hi:[1,0]
	v_pk_add_f32 v[86:87], v[86:87], 0 op_sel_hi:[1,0]
	v_pk_add_f32 v[82:83], v[82:83], 0 op_sel_hi:[1,0]
	v_pk_add_f32 v[78:79], v[78:79], 0 op_sel_hi:[1,0]
	v_pk_add_f32 v[74:75], v[74:75], 0 op_sel_hi:[1,0]
	v_pk_add_f32 v[70:71], v[70:71], 0 op_sel_hi:[1,0]
	v_pk_add_f32 v[66:67], v[66:67], 0 op_sel_hi:[1,0]
	v_pk_add_f32 v[60:61], v[60:61], 0 op_sel_hi:[1,0]
	v_pk_add_f32 v[56:57], v[56:57], 0 op_sel_hi:[1,0]
	v_pk_add_f32 v[52:53], v[52:53], 0 op_sel_hi:[1,0]
	v_pk_add_f32 v[48:49], v[48:49], 0 op_sel_hi:[1,0]
	v_pk_add_f32 v[44:45], v[44:45], 0 op_sel_hi:[1,0]
	v_pk_add_f32 v[40:41], v[40:41], 0 op_sel_hi:[1,0]
	v_pk_add_f32 v[36:37], v[36:37], 0 op_sel_hi:[1,0]
	v_pk_add_f32 v[32:33], v[32:33], 0 op_sel_hi:[1,0]
	v_pk_add_f32 v[62:63], v[62:63], 0 op_sel_hi:[1,0]
	v_pk_add_f32 v[58:59], v[58:59], 0 op_sel_hi:[1,0]
	v_pk_add_f32 v[54:55], v[54:55], 0 op_sel_hi:[1,0]
	v_pk_add_f32 v[50:51], v[50:51], 0 op_sel_hi:[1,0]
	v_pk_add_f32 v[46:47], v[46:47], 0 op_sel_hi:[1,0]
	v_pk_add_f32 v[42:43], v[42:43], 0 op_sel_hi:[1,0]
	v_pk_add_f32 v[38:39], v[38:39], 0 op_sel_hi:[1,0]
	v_pk_add_f32 v[34:35], v[34:35], 0 op_sel_hi:[1,0]
	v_pk_add_f32 v[28:29], v[28:29], 0 op_sel_hi:[1,0]
	v_pk_add_f32 v[24:25], v[24:25], 0 op_sel_hi:[1,0]
	v_pk_add_f32 v[20:21], v[20:21], 0 op_sel_hi:[1,0]
	v_pk_add_f32 v[16:17], v[16:17], 0 op_sel_hi:[1,0]
	v_pk_add_f32 v[12:13], v[12:13], 0 op_sel_hi:[1,0]
	v_pk_add_f32 v[8:9], v[8:9], 0 op_sel_hi:[1,0]
	v_pk_add_f32 v[4:5], v[4:5], 0 op_sel_hi:[1,0]
	v_pk_add_f32 v[0:1], v[0:1], 0 op_sel_hi:[1,0]
	v_pk_add_f32 v[30:31], v[30:31], 0 op_sel_hi:[1,0]
	v_pk_add_f32 v[26:27], v[26:27], 0 op_sel_hi:[1,0]
	v_pk_add_f32 v[22:23], v[22:23], 0 op_sel_hi:[1,0]
	v_pk_add_f32 v[18:19], v[18:19], 0 op_sel_hi:[1,0]
	v_pk_add_f32 v[14:15], v[14:15], 0 op_sel_hi:[1,0]
	v_pk_add_f32 v[10:11], v[10:11], 0 op_sel_hi:[1,0]
	v_pk_add_f32 v[6:7], v[6:7], 0 op_sel_hi:[1,0]
	v_pk_add_f32 v[2:3], v[2:3], 0 op_sel_hi:[1,0]
	s_mov_b32 s33, s4
	s_mov_b32 s12, s6
	s_mov_b64 s[16:17], s[10:11]
	s_waitcnt vmcnt(0)
; __device__ __forceinline__ unsigned cvt_pk_bf16(float lo, float hi) { unsigned r; asm volatile("s_nop 0\n\tv_cvt_pk_bf16_f32 %0, %1, %2\n\ts_nop 1" : "=v"(r) : "v"(lo), "v"(hi)); return r; }
;     __device__ __forceinline__ void operator()(f32x4 (&acc)[2][2][4][2], const Unit& u, int wr, int wc, int fr, int fq) const {
;     ...
;         for (int bj = 0; bj < 2; ++bj)
; #pragma unroll
;             for (int n = 0; n < 2; ++n) { const int col = col0 + bj * 128 + n * 16; const f32x4 gv = *(const f32x4*)(gr + col);
;                 f32x4 bv = (f32x4){0.f, 0.f, 0.f, 0.f}; if (bias) bv = *(const f32x4*)(bias + col);
; #pragma unroll
;                 for (int ai = 0; ai < 2; ++ai)
; #pragma unroll
;                     for (int m = 0; m < 4; ++m) { const size_t row = row0 + ai * 128 + m * 16;
;                         const f32x4 o = gv * (acc[ai][bj][m][n] + bv); u32x2 w; w.x = cvt_pk_bf16(o[0], o[1]); w.y = cvt_pk_bf16(o[2], o[3]);
;                         *(u32x2*)(O + row * 1024 + col) = w; } }
	v_pk_mul_f32 v[124:125], v[124:125], v[128:129]
	v_pk_mul_f32 v[126:127], v[126:127], v[130:131]
	v_cvt_pk_bf16_f32 v148, v124, v125
	v_lshlrev_b64 v[124:125], 11, v[144:145]
	v_cvt_pk_bf16_f32 v149, v126, v127
	v_lshl_add_u64 v[124:125], s[0:1], 0, v[124:125]
	v_lshlrev_b64 v[126:127], 1, v[146:147]
	v_or_b32_e32 v146, 16, v144
	v_lshl_add_u64 v[124:125], v[124:125], 0, v[126:127]
	v_ashrrev_i32_e32 v147, 31, v146
	v_pk_mul_f32 v[120:121], v[120:121], v[128:129]
	global_store_dwordx2 v[124:125], v[148:149], off
	v_pk_mul_f32 v[122:123], v[122:123], v[130:131]
	v_cvt_pk_bf16_f32 v148, v120, v121
	v_lshlrev_b64 v[120:121], 11, v[146:147]
	v_cvt_pk_bf16_f32 v149, v122, v123
	v_lshl_add_u64 v[120:121], s[0:1], 0, v[120:121]
	v_or_b32_e32 v122, 32, v144
	v_lshl_add_u64 v[120:121], v[120:121], 0, v[126:127]
	v_ashrrev_i32_e32 v123, 31, v122
	v_pk_mul_f32 v[116:117], v[116:117], v[128:129]
	global_store_dwordx2 v[120:121], v[148:149], off
	v_pk_mul_f32 v[118:119], v[118:119], v[130:131]
	v_cvt_pk_bf16_f32 v146, v116, v117
	v_lshlrev_b64 v[116:117], 11, v[122:123]
	v_cvt_pk_bf16_f32 v147, v118, v119
	v_lshl_add_u64 v[116:117], s[0:1], 0, v[116:117]
	v_or_b32_e32 v118, 48, v144
	v_lshl_add_u64 v[116:117], v[116:117], 0, v[126:127]
	v_ashrrev_i32_e32 v119, 31, v118
	v_pk_mul_f32 v[112:113], v[112:113], v[128:129]
	global_store_dwordx2 v[116:117], v[146:147], off
	v_cvt_pk_bf16_f32 v122, v112, v113
	v_lshlrev_b64 v[112:113], 11, v[118:119]
	v_lshl_add_u64 v[112:113], s[0:1], 0, v[112:113]
	v_pk_mul_f32 v[114:115], v[114:115], v[130:131]
	v_lshl_add_u64 v[112:113], v[112:113], 0, v[126:127]
	v_pk_mul_f32 v[110:111], v[110:111], v[130:131]
	v_cvt_pk_bf16_f32 v123, v114, v115
	global_store_dwordx2 v[112:113], v[122:123], off
	v_pk_mul_f32 v[108:109], v[108:109], v[128:129]
	v_pk_mul_f32 v[106:107], v[106:107], v[130:131]
	v_cvt_pk_bf16_f32 v114, v108, v109
	v_cvt_pk_bf16_f32 v115, v110, v111
	v_add_co_u32_e32 v110, vcc, s63, v124
	v_pk_mul_f32 v[104:105], v[104:105], v[128:129]
	s_nop 0
	v_addc_co_u32_e32 v111, vcc, 0, v125, vcc
	global_store_dwordx2 v[110:111], v[114:115], off
	v_cvt_pk_bf16_f32 v110, v104, v105
	v_cvt_pk_bf16_f32 v111, v106, v107
	v_add_co_u32_e32 v106, vcc, s66, v124
	v_pk_mul_f32 v[102:103], v[102:103], v[130:131]
	s_nop 0
	v_addc_co_u32_e32 v107, vcc, 0, v125, vcc
	global_store_dwordx2 v[106:107], v[110:111], off
	v_pk_mul_f32 v[100:101], v[100:101], v[128:129]
	v_pk_mul_f32 v[98:99], v[98:99], v[130:131]
	v_cvt_pk_bf16_f32 v106, v100, v101
	v_cvt_pk_bf16_f32 v107, v102, v103
	v_add_co_u32_e32 v102, vcc, s55, v124
	v_pk_mul_f32 v[96:97], v[96:97], v[128:129]
	s_nop 0
	v_addc_co_u32_e32 v103, vcc, 0, v125, vcc
	global_store_dwordx2 v[102:103], v[106:107], off
	v_cvt_pk_bf16_f32 v96, v96, v97
	v_cvt_pk_bf16_f32 v97, v98, v99
	v_add_co_u32_e32 v98, vcc, s5, v124
	v_lshl_add_u64 v[108:109], v[124:125], 0, s[14:15]
	s_nop 0
	v_addc_co_u32_e32 v99, vcc, 0, v125, vcc
	global_store_dwordx2 v[98:99], v[96:97], off
	s_nop 0
	v_mov_b32_e32 v96, v152
	v_mov_b32_e32 v97, v153
	v_mov_b32_e32 v98, v154
	v_mov_b32_e32 v99, v155
	s_mov_b64 s[14:15], 0x50000
	v_lshl_add_u64 v[100:101], v[124:125], 0, s[14:15]
	s_mov_b64 s[14:15], 0x58000
	v_lshl_add_u64 v[104:105], v[124:125], 0, s[64:65]
	v_lshl_add_u64 v[102:103], v[124:125], 0, s[14:15]
	s_and_b64 vcc, exec, s[2:3]
	s_mov_b64 s[14:15], s[8:9]
	v_pk_mul_f32 v[92:93], v[92:93], v[96:97]
	v_pk_mul_f32 v[88:89], v[88:89], v[96:97]
	v_pk_mul_f32 v[84:85], v[84:85], v[96:97]
	v_pk_mul_f32 v[80:81], v[80:81], v[96:97]
	v_pk_mul_f32 v[76:77], v[76:77], v[96:97]
	v_pk_mul_f32 v[72:73], v[72:73], v[96:97]
	v_pk_mul_f32 v[68:69], v[68:69], v[96:97]
	v_pk_mul_f32 v[64:65], v[64:65], v[96:97]
	v_pk_mul_f32 v[94:95], v[94:95], v[98:99]
	v_cvt_pk_bf16_f32 v92, v92, v93
	v_pk_mul_f32 v[90:91], v[90:91], v[98:99]
	v_cvt_pk_bf16_f32 v93, v94, v95
	global_store_dwordx2 v[124:125], v[92:93], off offset:32
	v_cvt_pk_bf16_f32 v88, v88, v89
	v_cvt_pk_bf16_f32 v89, v90, v91
	global_store_dwordx2 v[120:121], v[88:89], off offset:32
	v_pk_mul_f32 v[86:87], v[86:87], v[98:99]
	v_cvt_pk_bf16_f32 v84, v84, v85
	v_pk_mul_f32 v[82:83], v[82:83], v[98:99]
	v_cvt_pk_bf16_f32 v85, v86, v87
	global_store_dwordx2 v[116:117], v[84:85], off offset:32
	v_cvt_pk_bf16_f32 v80, v80, v81
	v_cvt_pk_bf16_f32 v81, v82, v83
	global_store_dwordx2 v[112:113], v[80:81], off offset:32
; __device__ __forceinline__ unsigned cvt_pk_bf16(float lo, float hi) { unsigned r; asm volatile("s_nop 0\n\tv_cvt_pk_bf16_f32 %0, %1, %2\n\ts_nop 1" : "=v"(r) : "v"(lo), "v"(hi)); return r; }
; #define PG8_WAIT_V(n) asm volatile("s_waitcnt vmcnt(" #n ")" ::: "memory")
; #define PG8_BAR __builtin_amdgcn_s_barrier()
; template <class Epi, class Sched>
; __device__ __forceinline__ void gemm_phase(PG8_LAS unsigned char* lds, const Gemm g, const Sched& S, const Epi& E, int tid_in) {
;     ...
;     PG8_WAIT_V(0);
;     if (wr == 0) PG8_BAR;
;     PG8_BAR;
;     __device__ __forceinline__ void operator()(f32x4 (&acc)[2][2][4][2], const Unit& u, int wr, int wc, int fr, int fq) const {
;         const int row0 = u.pm * 256 + wr * 64 + fr, col0 = u.pn * 256 + wc * 32 + 4 * fq;
;         const float* gr = gate + (size_t)(bbase + (u.pm * 256) / SEQ) * MODW;
; #pragma unroll
;         for (int bj = 0; bj < 2; ++bj)
; #pragma unroll
;             for (int n = 0; n < 2; ++n) { const int col = col0 + bj * 128 + n * 16; const f32x4 gv = *(const f32x4*)(gr + col);
;                 f32x4 bv = (f32x4){0.f, 0.f, 0.f, 0.f}; if (bias) bv = *(const f32x4*)(bias + col);
; #pragma unroll
;                 for (int ai = 0; ai < 2; ++ai)
; #pragma unroll
;                     for (int m = 0; m < 4; ++m) { const size_t row = row0 + ai * 128 + m * 16;
;                         const f32x4 o = gv * (acc[ai][bj][m][n] + bv); u32x2 w; w.x = cvt_pk_bf16(o[0], o[1]); w.y = cvt_pk_bf16(o[2], o[3]);
;                         *(u32x2*)(O + row * 1024 + col) = w; } }
;     }
	v_pk_mul_f32 v[78:79], v[78:79], v[98:99]
	v_cvt_pk_bf16_f32 v76, v76, v77
	v_pk_mul_f32 v[74:75], v[74:75], v[98:99]
	v_cvt_pk_bf16_f32 v77, v78, v79
	global_store_dwordx2 v[108:109], v[76:77], off offset:32
	v_cvt_pk_bf16_f32 v72, v72, v73
	v_cvt_pk_bf16_f32 v73, v74, v75
	global_store_dwordx2 v[104:105], v[72:73], off offset:32
	v_pk_mul_f32 v[70:71], v[70:71], v[98:99]
	v_cvt_pk_bf16_f32 v68, v68, v69
	v_pk_mul_f32 v[66:67], v[66:67], v[98:99]
	v_cvt_pk_bf16_f32 v69, v70, v71
	global_store_dwordx2 v[100:101], v[68:69], off offset:32
	v_cvt_pk_bf16_f32 v64, v64, v65
	v_cvt_pk_bf16_f32 v65, v66, v67
	global_store_dwordx2 v[102:103], v[64:65], off offset:32
	s_nop 0
	v_mov_b32_e32 v64, v156
	v_mov_b32_e32 v65, v157
	v_mov_b32_e32 v66, v158
	v_mov_b32_e32 v67, v159
	v_pk_mul_f32 v[60:61], v[60:61], v[64:65]
	v_pk_mul_f32 v[56:57], v[56:57], v[64:65]
	v_pk_mul_f32 v[52:53], v[52:53], v[64:65]
	v_pk_mul_f32 v[48:49], v[48:49], v[64:65]
	v_pk_mul_f32 v[44:45], v[44:45], v[64:65]
	v_pk_mul_f32 v[40:41], v[40:41], v[64:65]
	v_pk_mul_f32 v[36:37], v[36:37], v[64:65]
	v_pk_mul_f32 v[32:33], v[32:33], v[64:65]
	v_pk_mul_f32 v[62:63], v[62:63], v[66:67]
	v_cvt_pk_bf16_f32 v60, v60, v61
	v_pk_mul_f32 v[58:59], v[58:59], v[66:67]
	v_cvt_pk_bf16_f32 v61, v62, v63
	global_store_dwordx2 v[124:125], v[60:61], off offset:256
	v_cvt_pk_bf16_f32 v56, v56, v57
	v_cvt_pk_bf16_f32 v57, v58, v59
	global_store_dwordx2 v[120:121], v[56:57], off offset:256
	v_pk_mul_f32 v[54:55], v[54:55], v[66:67]
	v_cvt_pk_bf16_f32 v52, v52, v53
	v_pk_mul_f32 v[50:51], v[50:51], v[66:67]
	v_cvt_pk_bf16_f32 v53, v54, v55
	global_store_dwordx2 v[116:117], v[52:53], off offset:256
	v_cvt_pk_bf16_f32 v48, v48, v49
	v_cvt_pk_bf16_f32 v49, v50, v51
	global_store_dwordx2 v[112:113], v[48:49], off offset:256
	v_pk_mul_f32 v[46:47], v[46:47], v[66:67]
	v_cvt_pk_bf16_f32 v44, v44, v45
	v_pk_mul_f32 v[42:43], v[42:43], v[66:67]
	v_cvt_pk_bf16_f32 v45, v46, v47
	global_store_dwordx2 v[108:109], v[44:45], off offset:256
	v_cvt_pk_bf16_f32 v40, v40, v41
	v_cvt_pk_bf16_f32 v41, v42, v43
	global_store_dwordx2 v[104:105], v[40:41], off offset:256
	v_pk_mul_f32 v[38:39], v[38:39], v[66:67]
	v_cvt_pk_bf16_f32 v36, v36, v37
	v_pk_mul_f32 v[34:35], v[34:35], v[66:67]
	v_cvt_pk_bf16_f32 v37, v38, v39
	global_store_dwordx2 v[100:101], v[36:37], off offset:256
	v_cvt_pk_bf16_f32 v32, v32, v33
	v_cvt_pk_bf16_f32 v33, v34, v35
	global_store_dwordx2 v[102:103], v[32:33], off offset:256
	s_nop 0
	v_mov_b32_e32 v32, v160
	v_mov_b32_e32 v33, v161
	v_mov_b32_e32 v34, v162
	v_mov_b32_e32 v35, v163
	v_pk_mul_f32 v[28:29], v[28:29], v[32:33]
	v_pk_mul_f32 v[24:25], v[24:25], v[32:33]
	v_pk_mul_f32 v[20:21], v[20:21], v[32:33]
	v_pk_mul_f32 v[16:17], v[16:17], v[32:33]
	v_pk_mul_f32 v[12:13], v[12:13], v[32:33]
	v_pk_mul_f32 v[8:9], v[8:9], v[32:33]
	v_pk_mul_f32 v[4:5], v[4:5], v[32:33]
	v_pk_mul_f32 v[0:1], v[0:1], v[32:33]
	v_pk_mul_f32 v[30:31], v[30:31], v[34:35]
	v_cvt_pk_bf16_f32 v28, v28, v29
	v_pk_mul_f32 v[26:27], v[26:27], v[34:35]
	v_cvt_pk_bf16_f32 v29, v30, v31
	global_store_dwordx2 v[124:125], v[28:29], off offset:288
	v_cvt_pk_bf16_f32 v24, v24, v25
	v_cvt_pk_bf16_f32 v25, v26, v27
	global_store_dwordx2 v[120:121], v[24:25], off offset:288
	v_pk_mul_f32 v[22:23], v[22:23], v[34:35]
	v_cvt_pk_bf16_f32 v20, v20, v21
	v_pk_mul_f32 v[18:19], v[18:19], v[34:35]
	v_cvt_pk_bf16_f32 v21, v22, v23
	global_store_dwordx2 v[116:117], v[20:21], off offset:288
	v_cvt_pk_bf16_f32 v16, v16, v17
	v_cvt_pk_bf16_f32 v17, v18, v19
	global_store_dwordx2 v[112:113], v[16:17], off offset:288
	v_pk_mul_f32 v[14:15], v[14:15], v[34:35]
	v_cvt_pk_bf16_f32 v12, v12, v13
	v_pk_mul_f32 v[10:11], v[10:11], v[34:35]
	v_cvt_pk_bf16_f32 v13, v14, v15
	global_store_dwordx2 v[108:109], v[12:13], off offset:288
	v_cvt_pk_bf16_f32 v8, v8, v9
	v_cvt_pk_bf16_f32 v9, v10, v11
	global_store_dwordx2 v[104:105], v[8:9], off offset:288
	v_pk_mul_f32 v[6:7], v[6:7], v[34:35]
	v_cvt_pk_bf16_f32 v4, v4, v5
	v_pk_mul_f32 v[2:3], v[2:3], v[34:35]
	v_cvt_pk_bf16_f32 v5, v6, v7
	global_store_dwordx2 v[100:101], v[4:5], off offset:288
	v_cvt_pk_bf16_f32 v0, v0, v1
	v_cvt_pk_bf16_f32 v1, v2, v3
	s_nop 1
	global_store_dwordx2 v[102:103], v[0:1], off offset:288
	s_cbranch_vccz .LBB0_318
	s_waitcnt vmcnt(0)
	s_cmpk_gt_u32 s22, 0xff
	s_cbranch_scc1 .LBB0_329
	s_barrier

; #define PG8_STAGE(bufoff, gbase, voff) do { _Pragma("unroll") for (int _i = 0; _i < 2; ++_i) \
;         __builtin_amdgcn_global_load_lds((const unsigned*)((const char*)(gbase) + (voff)[_i]), (PG8_LAS unsigned*)(lds + (bufoff) + ldsw + _i * 8192), 16, 0, 0); } while (0)
; #define PG8_LDA(dst, b, h) do { _Pragma("unroll") for (int m = 0; m < 4; ++m) _Pragma("unroll") for (int k = 0; k < 2; ++k) dst[m][k] = *(const PG8_LAS bf16x8*)(lds + PG8_SA(b, h) + aoff + m * 2048 + k * 1024); } while (0)
; #define PG8_LDB(dst, b, h) do { _Pragma("unroll") for (int n = 0; n < 2; ++n) _Pragma("unroll") for (int k = 0; k < 2; ++k) dst[n][k] = *(const PG8_LAS bf16x8*)(lds + PG8_SB(b, h) + boff + n * 2048 + k * 1024); } while (0)
; #define PG8_MMA(ai, bj, At, Bt) do { __builtin_amdgcn_s_setprio(1); _Pragma("unroll") for (int m = 0; m < 4; ++m) _Pragma("unroll") for (int n = 0; n < 2; ++n) _Pragma("unroll") for (int k = 0; k < 2; ++k) \
;         acc[ai][bj][m][n] = __builtin_amdgcn_mfma_f32_16x16x32_bf16(Bt[n][k], At[m][k], acc[ai][bj][m][n], 0, 0, 0); __builtin_amdgcn_s_setprio(0); } while (0)
; #define PG8_WAIT_L(n) asm volatile("s_waitcnt lgkmcnt(" #n ")" ::: "memory")
; #define PG8_BAR __builtin_amdgcn_s_barrier()
; #define PG8_SCHED __builtin_amdgcn_sched_barrier(0)
; template <class Epi, class Sched>
; __device__ __forceinline__ void gemm_phase(PG8_LAS unsigned char* lds, const Gemm g, const Sched& S, const Epi& E, int tid_in) {
;     ...
;             PG8_LDB(B0, 0, 0); PG8_SCHED; PG8_LDA(At, 0, 0); PG8_STAGE(PG8_SA(1, 1), a1 + hstep, voffA);
;             PG8_WAIT_L(8); PG8_BAR; PG8_WAIT_L(0); PG8_MMA(0, 0, At, B0); PG8_BAR; PG8_SCHED;
;             PG8_LDB(B1, 0, 1); PG8_STAGE(PG8_SB(0, 0), b2, voffB);
;             PG8_BAR; PG8_WAIT_L(0); PG8_MMA(0, 1, At, B1); PG8_BAR;
;             PG8_LDA(At, 0, 1); PG8_STAGE(PG8_SA(0, 0), a2, voffA);
;             PG8_BAR; PG8_WAIT_L(0); PG8_MMA(1, 0, At, B0); PG8_BAR; PG8_SCHED;
.LBB0_350:
	s_add_u32 s20, s18, 0xfff80080
	s_addc_u32 s21, s19, -1
	s_add_i32 s46, 0, 0x10000
	v_add_u32_e32 v146, s46, v171
	ds_read_b128 v[134:137], v146
	ds_read_b128 v[138:141], v146 offset:1024
	ds_read_b128 v[142:145], v146 offset:2048
	ds_read_b128 v[146:149], v146 offset:3072
	s_cmp_eq_u32 s45, 28
	s_cselect_b32 s23, s11, s21
	s_cselect_b32 s22, s41, s20
	s_cselect_b32 s21, s9, s44
	s_cselect_b32 s20, s42, s43
	v_lshl_add_u64 v[186:187], s[18:19], 0, v[130:131]
	s_add_i32 m0, s17, 0xc000
	ds_read_b128 v[150:153], v173
	ds_read_b128 v[154:157], v173 offset:1024
	ds_read_b128 v[158:161], v173 offset:2048
	ds_read_b128 v[162:165], v173 offset:3072
	ds_read_b128 v[166:169], v173 offset:4096
	ds_read_b128 v[174:177], v173 offset:5120
	ds_read_b128 v[178:181], v173 offset:6144
	ds_read_b128 v[182:185], v173 offset:7168
	global_load_lds_dwordx4 v[186:187], off
	s_add_i32 m0, s17, 0xe000
	v_lshl_add_u64 v[186:187], s[18:19], 0, v[132:133]
	global_load_lds_dwordx4 v[186:187], off
	s_waitcnt lgkmcnt(8)
	s_barrier
	s_waitcnt lgkmcnt(0)
	s_waitcnt lgkmcnt(0)
	v_mfma_f32_16x16x32_bf16 v[124:127], v[134:137], v[150:153], v[124:127]
	v_mfma_f32_16x16x32_bf16 v[120:123], v[142:145], v[150:153], v[120:123]
	v_mfma_f32_16x16x32_bf16 v[108:111], v[134:137], v[158:161], v[108:111]
	v_mfma_f32_16x16x32_bf16 v[104:107], v[142:145], v[158:161], v[104:107]
	v_mfma_f32_16x16x32_bf16 v[96:99], v[134:137], v[166:169], v[96:99]
	v_mfma_f32_16x16x32_bf16 v[88:91], v[142:145], v[166:169], v[88:91]
	v_mfma_f32_16x16x32_bf16 v[80:83], v[134:137], v[178:181], v[80:83]
	v_mfma_f32_16x16x32_bf16 v[72:75], v[142:145], v[178:181], v[72:75]
	v_mfma_f32_16x16x32_bf16 v[124:127], v[138:141], v[154:157], v[124:127]
	v_mfma_f32_16x16x32_bf16 v[120:123], v[146:149], v[154:157], v[120:123]
	v_mfma_f32_16x16x32_bf16 v[108:111], v[138:141], v[162:165], v[108:111]
	v_mfma_f32_16x16x32_bf16 v[104:107], v[146:149], v[162:165], v[104:107]
	v_mfma_f32_16x16x32_bf16 v[96:99], v[138:141], v[174:177], v[96:99]
	v_mfma_f32_16x16x32_bf16 v[88:91], v[146:149], v[174:177], v[88:91]
	v_mfma_f32_16x16x32_bf16 v[80:83], v[138:141], v[182:185], v[80:83]
	v_mfma_f32_16x16x32_bf16 v[72:75], v[146:149], v[182:185], v[72:75]
	s_barrier
	s_add_i32 s50, 0, 0x14000
	v_add_u32_e32 v190, s50, v171
	s_add_i32 s46, s46, s30
	ds_read_b128 v[186:189], v190
	ds_read_b128 v[194:197], v190 offset:1024
	ds_read_b128 v[200:203], v190 offset:2048
	ds_read_b128 v[204:207], v190 offset:3072
	v_lshl_add_u64 v[190:191], s[20:21], 0, v[192:193]
	s_mov_b32 m0, s46
	v_lshl_add_u64 v[208:209], s[20:21], 0, v[128:129]
	global_load_lds_dwordx4 v[190:191], off
	s_add_i32 m0, s46, 0x2000
	s_nop 0
	global_load_lds_dwordx4 v[208:209], off
	s_barrier
	s_waitcnt lgkmcnt(0)
	s_waitcnt lgkmcnt(0)
	v_mfma_f32_16x16x32_bf16 v[116:119], v[186:189], v[150:153], v[116:119]
	v_mfma_f32_16x16x32_bf16 v[112:115], v[200:203], v[150:153], v[112:115]
	v_mfma_f32_16x16x32_bf16 v[100:103], v[186:189], v[158:161], v[100:103]
	v_mfma_f32_16x16x32_bf16 v[92:95], v[200:203], v[158:161], v[92:95]
	v_mfma_f32_16x16x32_bf16 v[84:87], v[186:189], v[166:169], v[84:87]
	v_mfma_f32_16x16x32_bf16 v[76:79], v[200:203], v[166:169], v[76:79]
	v_mfma_f32_16x16x32_bf16 v[68:71], v[186:189], v[178:181], v[68:71]
	v_mfma_f32_16x16x32_bf16 v[64:67], v[200:203], v[178:181], v[64:67]
	v_mfma_f32_16x16x32_bf16 v[116:119], v[194:197], v[154:157], v[116:119]
	v_mfma_f32_16x16x32_bf16 v[112:115], v[204:207], v[154:157], v[112:115]
	v_mfma_f32_16x16x32_bf16 v[100:103], v[194:197], v[162:165], v[100:103]
	v_mfma_f32_16x16x32_bf16 v[92:95], v[204:207], v[162:165], v[92:95]
	v_mfma_f32_16x16x32_bf16 v[84:87], v[194:197], v[174:177], v[84:87]
	v_mfma_f32_16x16x32_bf16 v[76:79], v[204:207], v[174:177], v[76:79]
	v_mfma_f32_16x16x32_bf16 v[68:71], v[194:197], v[182:185], v[68:71]
	v_mfma_f32_16x16x32_bf16 v[64:67], v[204:207], v[182:185], v[64:67]
	s_mov_b32 m0, s17
	v_lshl_add_u64 v[210:211], s[22:23], 0, v[192:193]
	s_barrier
	ds_read_b128 v[150:153], v173 offset:16384
	ds_read_b128 v[154:157], v173 offset:17408
	ds_read_b128 v[158:161], v173 offset:18432
	ds_read_b128 v[162:165], v173 offset:19456
	ds_read_b128 v[166:169], v173 offset:20480
	ds_read_b128 v[174:177], v173 offset:21504
	ds_read_b128 v[178:181], v173 offset:22528
	ds_read_b128 v[182:185], v173 offset:23552
	global_load_lds_dwordx4 v[210:211], off
	s_mov_b32 m0, s31
	v_lshl_add_u64 v[212:213], s[22:23], 0, v[128:129]
	global_load_lds_dwordx4 v[212:213], off
	s_barrier
	s_waitcnt lgkmcnt(0)
	s_waitcnt lgkmcnt(0)
	v_mfma_f32_16x16x32_bf16 v[60:63], v[134:137], v[150:153], v[60:63]
	v_mfma_f32_16x16x32_bf16 v[56:59], v[142:145], v[150:153], v[56:59]
	v_mfma_f32_16x16x32_bf16 v[48:51], v[134:137], v[158:161], v[48:51]
	v_mfma_f32_16x16x32_bf16 v[40:43], v[142:145], v[158:161], v[40:43]
	v_mfma_f32_16x16x32_bf16 v[32:35], v[134:137], v[166:169], v[32:35]
	v_mfma_f32_16x16x32_bf16 v[24:27], v[142:145], v[166:169], v[24:27]
	v_mfma_f32_16x16x32_bf16 v[16:19], v[134:137], v[178:181], v[16:19]
	v_mfma_f32_16x16x32_bf16 v[8:11], v[142:145], v[178:181], v[8:11]
	v_mfma_f32_16x16x32_bf16 v[60:63], v[138:141], v[154:157], v[60:63]
	v_mfma_f32_16x16x32_bf16 v[56:59], v[146:149], v[154:157], v[56:59]
	v_mfma_f32_16x16x32_bf16 v[48:51], v[138:141], v[162:165], v[48:51]
	v_mfma_f32_16x16x32_bf16 v[40:43], v[146:149], v[162:165], v[40:43]
	v_mfma_f32_16x16x32_bf16 v[32:35], v[138:141], v[174:177], v[32:35]
	v_mfma_f32_16x16x32_bf16 v[24:27], v[146:149], v[174:177], v[24:27]
	v_mfma_f32_16x16x32_bf16 v[16:19], v[138:141], v[182:185], v[16:19]
	v_mfma_f32_16x16x32_bf16 v[8:11], v[146:149], v[182:185], v[8:11]
	s_barrier
; #define PG8_STAGE(bufoff, gbase, voff) do { _Pragma("unroll") for (int _i = 0; _i < 2; ++_i) \
;         __builtin_amdgcn_global_load_lds((const unsigned*)((const char*)(gbase) + (voff)[_i]), (PG8_LAS unsigned*)(lds + (bufoff) + ldsw + _i * 8192), 16, 0, 0); } while (0)
; #define PG8_LDA(dst, b, h) do { _Pragma("unroll") for (int m = 0; m < 4; ++m) _Pragma("unroll") for (int k = 0; k < 2; ++k) dst[m][k] = *(const PG8_LAS bf16x8*)(lds + PG8_SA(b, h) + aoff + m * 2048 + k * 1024); } while (0)
; #define PG8_LDB(dst, b, h) do { _Pragma("unroll") for (int n = 0; n < 2; ++n) _Pragma("unroll") for (int k = 0; k < 2; ++k) dst[n][k] = *(const PG8_LAS bf16x8*)(lds + PG8_SB(b, h) + boff + n * 2048 + k * 1024); } while (0)
; #define PG8_MMA(ai, bj, At, Bt) do { __builtin_amdgcn_s_setprio(1); _Pragma("unroll") for (int m = 0; m < 4; ++m) _Pragma("unroll") for (int n = 0; n < 2; ++n) _Pragma("unroll") for (int k = 0; k < 2; ++k) \
;         acc[ai][bj][m][n] = __builtin_amdgcn_mfma_f32_16x16x32_bf16(Bt[n][k], At[m][k], acc[ai][bj][m][n], 0, 0, 0); __builtin_amdgcn_s_setprio(0); } while (0)
; #define PG8_WAIT_V(n) asm volatile("s_waitcnt vmcnt(" #n ")" ::: "memory")
; #define PG8_WAIT_L(n) asm volatile("s_waitcnt lgkmcnt(" #n ")" ::: "memory")
; #define PG8_BAR __builtin_amdgcn_s_barrier()
; #define PG8_SCHED __builtin_amdgcn_sched_barrier(0)
; template <class Epi, class Sched>
; __device__ __forceinline__ void gemm_phase(PG8_LAS unsigned char* lds, const Gemm g, const Sched& S, const Epi& E, int tid_in) {
;     ...
;             PG8_STAGE(PG8_SB(0, 1), b2 + hstep, voffB);
;             PG8_WAIT_V(6); PG8_BAR; PG8_MMA(1, 1, At, B1); PG8_BAR;
;             PG8_LDB(B0, 1, 0); PG8_SCHED; PG8_LDA(At, 1, 0); PG8_STAGE(PG8_SA(0, 1), a2 + hstep, voffA);
;             PG8_WAIT_L(8); PG8_BAR; PG8_WAIT_L(0); PG8_MMA(0, 0, At, B0); PG8_BAR; PG8_SCHED;
;             PG8_LDB(B1, 1, 1); PG8_STAGE(PG8_SB(1, 0), b3, voffB);
;             PG8_BAR; PG8_WAIT_L(0); PG8_MMA(0, 1, At, B1); PG8_BAR;
;             PG8_LDA(At, 1, 1); PG8_STAGE(PG8_SA(1, 0), a3, voffA);
	s_add_u32 s48, s20, 0x80000
	s_addc_u32 s49, s21, 0
	s_add_i32 s46, s50, s30
	s_mov_b32 m0, s46
	v_lshl_add_u64 v[134:135], s[48:49], 0, v[192:193]
	global_load_lds_dwordx4 v[134:135], off
	s_add_i32 m0, s46, 0x2000
	v_lshl_add_u64 v[134:135], s[48:49], 0, v[128:129]
	global_load_lds_dwordx4 v[134:135], off
	s_waitcnt vmcnt(6)
	s_barrier
	v_mfma_f32_16x16x32_bf16 v[52:55], v[186:189], v[150:153], v[52:55]
	v_mfma_f32_16x16x32_bf16 v[44:47], v[200:203], v[150:153], v[44:47]
	v_mfma_f32_16x16x32_bf16 v[36:39], v[186:189], v[158:161], v[36:39]
	v_mfma_f32_16x16x32_bf16 v[28:31], v[200:203], v[158:161], v[28:31]
	v_mfma_f32_16x16x32_bf16 v[20:23], v[186:189], v[166:169], v[20:23]
	v_mfma_f32_16x16x32_bf16 v[12:15], v[200:203], v[166:169], v[12:15]
	v_mfma_f32_16x16x32_bf16 v[4:7], v[186:189], v[178:181], v[4:7]
	v_mfma_f32_16x16x32_bf16 v[0:3], v[200:203], v[178:181], v[0:3]
	v_mfma_f32_16x16x32_bf16 v[52:55], v[194:197], v[154:157], v[52:55]
	v_mfma_f32_16x16x32_bf16 v[44:47], v[204:207], v[154:157], v[44:47]
	v_mfma_f32_16x16x32_bf16 v[36:39], v[194:197], v[162:165], v[36:39]
	v_mfma_f32_16x16x32_bf16 v[28:31], v[204:207], v[162:165], v[28:31]
	v_mfma_f32_16x16x32_bf16 v[20:23], v[194:197], v[174:177], v[20:23]
	v_mfma_f32_16x16x32_bf16 v[12:15], v[204:207], v[174:177], v[12:15]
	v_mfma_f32_16x16x32_bf16 v[4:7], v[194:197], v[182:185], v[4:7]
	v_mfma_f32_16x16x32_bf16 v[0:3], v[204:207], v[182:185], v[0:3]
	s_add_i32 s46, 0, 0x18000
	v_add_u32_e32 v146, s46, v171
	s_barrier
	ds_read_b128 v[134:137], v146
	ds_read_b128 v[138:141], v146 offset:1024
	ds_read_b128 v[142:145], v146 offset:2048
	ds_read_b128 v[146:149], v146 offset:3072
	s_add_u32 s22, s22, 0x80000
	s_addc_u32 s23, s23, 0
	s_mov_b32 m0, s36
	v_lshl_add_u64 v[186:187], s[22:23], 0, v[192:193]
	ds_read_b128 v[150:153], v173 offset:32768
	ds_read_b128 v[154:157], v173 offset:33792
	ds_read_b128 v[158:161], v173 offset:34816
	ds_read_b128 v[162:165], v173 offset:35840
	ds_read_b128 v[166:169], v173 offset:36864
	ds_read_b128 v[174:177], v173 offset:37888
	ds_read_b128 v[178:181], v173 offset:38912
	ds_read_b128 v[182:185], v173 offset:39936
	global_load_lds_dwordx4 v[186:187], off
	s_mov_b32 m0, s37
	v_lshl_add_u64 v[186:187], s[22:23], 0, v[128:129]
	global_load_lds_dwordx4 v[186:187], off
	s_waitcnt lgkmcnt(8)
	s_barrier
	s_waitcnt lgkmcnt(0)
	s_waitcnt lgkmcnt(0)
	v_mfma_f32_16x16x32_bf16 v[124:127], v[134:137], v[150:153], v[124:127]
	v_mfma_f32_16x16x32_bf16 v[120:123], v[142:145], v[150:153], v[120:123]
	v_mfma_f32_16x16x32_bf16 v[108:111], v[134:137], v[158:161], v[108:111]
	v_mfma_f32_16x16x32_bf16 v[104:107], v[142:145], v[158:161], v[104:107]
	v_mfma_f32_16x16x32_bf16 v[96:99], v[134:137], v[166:169], v[96:99]
	v_mfma_f32_16x16x32_bf16 v[88:91], v[142:145], v[166:169], v[88:91]
	v_mfma_f32_16x16x32_bf16 v[80:83], v[134:137], v[178:181], v[80:83]
	v_mfma_f32_16x16x32_bf16 v[72:75], v[142:145], v[178:181], v[72:75]
	v_mfma_f32_16x16x32_bf16 v[124:127], v[138:141], v[154:157], v[124:127]
	v_mfma_f32_16x16x32_bf16 v[120:123], v[146:149], v[154:157], v[120:123]
	v_mfma_f32_16x16x32_bf16 v[108:111], v[138:141], v[162:165], v[108:111]
	v_mfma_f32_16x16x32_bf16 v[104:107], v[146:149], v[162:165], v[104:107]
	v_mfma_f32_16x16x32_bf16 v[96:99], v[138:141], v[174:177], v[96:99]
	v_mfma_f32_16x16x32_bf16 v[88:91], v[146:149], v[174:177], v[88:91]
	v_mfma_f32_16x16x32_bf16 v[80:83], v[138:141], v[182:185], v[80:83]
	v_mfma_f32_16x16x32_bf16 v[72:75], v[146:149], v[182:185], v[72:75]
	s_barrier
	s_add_i32 s22, 0, 0x1c000
	s_add_i32 s23, s46, s30
	v_add_u32_e32 v199, s22, v171
	v_lshl_add_u64 v[190:191], v[190:191], 0, s[74:75]
	s_mov_b32 m0, s23
	ds_read_b128 v[186:189], v199
	ds_read_b128 v[194:197], v199 offset:1024
	ds_read_b128 v[200:203], v199 offset:2048
	ds_read_b128 v[204:207], v199 offset:3072
	global_load_lds_dwordx4 v[190:191], off
	s_add_i32 m0, s23, 0x2000
	v_lshl_add_u64 v[190:191], v[208:209], 0, s[74:75]
	global_load_lds_dwordx4 v[190:191], off
	s_barrier
	s_waitcnt lgkmcnt(0)
	s_waitcnt lgkmcnt(0)
	v_mfma_f32_16x16x32_bf16 v[116:119], v[186:189], v[150:153], v[116:119]
	v_mfma_f32_16x16x32_bf16 v[112:115], v[200:203], v[150:153], v[112:115]
	v_mfma_f32_16x16x32_bf16 v[100:103], v[186:189], v[158:161], v[100:103]
	v_mfma_f32_16x16x32_bf16 v[92:95], v[200:203], v[158:161], v[92:95]
	v_mfma_f32_16x16x32_bf16 v[84:87], v[186:189], v[166:169], v[84:87]
	v_mfma_f32_16x16x32_bf16 v[76:79], v[200:203], v[166:169], v[76:79]
	v_mfma_f32_16x16x32_bf16 v[68:71], v[186:189], v[178:181], v[68:71]
	v_mfma_f32_16x16x32_bf16 v[64:67], v[200:203], v[178:181], v[64:67]
	v_mfma_f32_16x16x32_bf16 v[116:119], v[194:197], v[154:157], v[116:119]
	v_mfma_f32_16x16x32_bf16 v[112:115], v[204:207], v[154:157], v[112:115]
	v_mfma_f32_16x16x32_bf16 v[100:103], v[194:197], v[162:165], v[100:103]
	v_mfma_f32_16x16x32_bf16 v[92:95], v[204:207], v[162:165], v[92:95]
	v_mfma_f32_16x16x32_bf16 v[84:87], v[194:197], v[174:177], v[84:87]
	v_mfma_f32_16x16x32_bf16 v[76:79], v[204:207], v[174:177], v[76:79]
	v_mfma_f32_16x16x32_bf16 v[68:71], v[194:197], v[182:185], v[68:71]
	v_mfma_f32_16x16x32_bf16 v[64:67], v[204:207], v[182:185], v[64:67]
	s_mov_b32 m0, s38
	v_lshl_add_u64 v[190:191], v[210:211], 0, s[74:75]
	s_barrier
	ds_read_b128 v[150:153], v173 offset:49152
	ds_read_b128 v[154:157], v173 offset:50176
	ds_read_b128 v[158:161], v173 offset:51200
	ds_read_b128 v[162:165], v173 offset:52224
	ds_read_b128 v[166:169], v173 offset:53248
	ds_read_b128 v[174:177], v173 offset:54272
	ds_read_b128 v[178:181], v173 offset:55296
	ds_read_b128 v[182:185], v173 offset:56320
	global_load_lds_dwordx4 v[190:191], off
	s_mov_b32 m0, s39
	v_lshl_add_u64 v[190:191], v[212:213], 0, s[74:75]
	global_load_lds_dwordx4 v[190:191], off
	s_barrier
; #define PG8_STAGE(bufoff, gbase, voff) do { _Pragma("unroll") for (int _i = 0; _i < 2; ++_i) \
;         __builtin_amdgcn_global_load_lds((const unsigned*)((const char*)(gbase) + (voff)[_i]), (PG8_LAS unsigned*)(lds + (bufoff) + ldsw + _i * 8192), 16, 0, 0); } while (0)
; #define PG8_MMA(ai, bj, At, Bt) do { __builtin_amdgcn_s_setprio(1); _Pragma("unroll") for (int m = 0; m < 4; ++m) _Pragma("unroll") for (int n = 0; n < 2; ++n) _Pragma("unroll") for (int k = 0; k < 2; ++k) \
;         acc[ai][bj][m][n] = __builtin_amdgcn_mfma_f32_16x16x32_bf16(Bt[n][k], At[m][k], acc[ai][bj][m][n], 0, 0, 0); __builtin_amdgcn_s_setprio(0); } while (0)
; #define PG8_WAIT_V(n) asm volatile("s_waitcnt vmcnt(" #n ")" ::: "memory")
; #define PG8_WAIT_L(n) asm volatile("s_waitcnt lgkmcnt(" #n ")" ::: "memory")
; #define PG8_BAR __builtin_amdgcn_s_barrier()
; #define PG8_SCHED __builtin_amdgcn_sched_barrier(0)
; template <class Epi, class Sched>
; __device__ __forceinline__ void gemm_phase(PG8_LAS unsigned char* lds, const Gemm g, const Sched& S, const Epi& E, int tid_in) {
;     ...
;             PG8_BAR; PG8_WAIT_L(0); PG8_MMA(1, 0, At, B0); PG8_BAR; PG8_SCHED;
;             PG8_STAGE(PG8_SB(1, 1), b3 + hstep, voffB);
;             PG8_WAIT_V(6); PG8_BAR; PG8_MMA(1, 1, At, B1); PG8_BAR;
;         }
;     __device__ __forceinline__ void operator()(f32x4 (&acc)[2][2][4][2], const Unit& u, int wr, int wc, int fr, int fq) const {
;         const int row0 = u.pm * 256 + wr * 64 + fr, col0 = u.pn * 256 + wc * 32 + 4 * fq;
; #pragma unroll
;         for (int ai = 0; ai < 2; ++ai) {
;             u32x2 gw[4][2][2];
; #pragma unroll
;             for (int m = 0; m < 4; ++m)
; #pragma unroll
;                 for (int bj = 0; bj < 2; ++bj)
; #pragma unroll
;                     for (int n = 0; n < 2; ++n) gw[m][bj][n] = *(const u32x2*)(gates + (size_t)(row0 + ai * 128 + m * 16) * 2048 + col0 + bj * 128 + n * 16);
	s_waitcnt lgkmcnt(0)
	s_waitcnt lgkmcnt(0)
	v_mfma_f32_16x16x32_bf16 v[60:63], v[134:137], v[150:153], v[60:63]
	v_mfma_f32_16x16x32_bf16 v[56:59], v[142:145], v[150:153], v[56:59]
	v_mfma_f32_16x16x32_bf16 v[48:51], v[134:137], v[158:161], v[48:51]
	v_mfma_f32_16x16x32_bf16 v[40:43], v[142:145], v[158:161], v[40:43]
	v_mfma_f32_16x16x32_bf16 v[32:35], v[134:137], v[166:169], v[32:35]
	v_mfma_f32_16x16x32_bf16 v[24:27], v[142:145], v[166:169], v[24:27]
	v_mfma_f32_16x16x32_bf16 v[16:19], v[134:137], v[178:181], v[16:19]
	v_mfma_f32_16x16x32_bf16 v[8:11], v[142:145], v[178:181], v[8:11]
	v_mfma_f32_16x16x32_bf16 v[60:63], v[138:141], v[154:157], v[60:63]
	v_mfma_f32_16x16x32_bf16 v[56:59], v[146:149], v[154:157], v[56:59]
	v_mfma_f32_16x16x32_bf16 v[48:51], v[138:141], v[162:165], v[48:51]
	v_mfma_f32_16x16x32_bf16 v[40:43], v[146:149], v[162:165], v[40:43]
	v_mfma_f32_16x16x32_bf16 v[32:35], v[138:141], v[174:177], v[32:35]
	v_mfma_f32_16x16x32_bf16 v[24:27], v[146:149], v[174:177], v[24:27]
	v_mfma_f32_16x16x32_bf16 v[16:19], v[138:141], v[182:185], v[16:19]
	v_mfma_f32_16x16x32_bf16 v[8:11], v[146:149], v[182:185], v[8:11]
	s_barrier
	s_add_u32 s20, s20, 0x80080
	s_addc_u32 s21, s21, 0
	s_add_i32 s22, s22, s30
	s_mov_b32 m0, s22
	v_lshl_add_u64 v[134:135], s[20:21], 0, v[192:193]
	global_load_lds_dwordx4 v[134:135], off
	s_add_i32 m0, s22, 0x2000
	v_lshl_add_u64 v[134:135], s[20:21], 0, v[128:129]
	global_load_lds_dwordx4 v[134:135], off
	s_waitcnt vmcnt(6)
	s_barrier
	v_mfma_f32_16x16x32_bf16 v[52:55], v[186:189], v[150:153], v[52:55]
	v_mfma_f32_16x16x32_bf16 v[44:47], v[200:203], v[150:153], v[44:47]
	v_mfma_f32_16x16x32_bf16 v[36:39], v[186:189], v[158:161], v[36:39]
	v_mfma_f32_16x16x32_bf16 v[28:31], v[200:203], v[158:161], v[28:31]
	v_mfma_f32_16x16x32_bf16 v[20:23], v[186:189], v[166:169], v[20:23]
	v_mfma_f32_16x16x32_bf16 v[12:15], v[200:203], v[166:169], v[12:15]
	v_mfma_f32_16x16x32_bf16 v[4:7], v[186:189], v[178:181], v[4:7]
	v_mfma_f32_16x16x32_bf16 v[0:3], v[200:203], v[178:181], v[0:3]
	v_mfma_f32_16x16x32_bf16 v[52:55], v[194:197], v[154:157], v[52:55]
	v_mfma_f32_16x16x32_bf16 v[44:47], v[204:207], v[154:157], v[44:47]
	v_mfma_f32_16x16x32_bf16 v[36:39], v[194:197], v[162:165], v[36:39]
	v_mfma_f32_16x16x32_bf16 v[28:31], v[204:207], v[162:165], v[28:31]
	v_mfma_f32_16x16x32_bf16 v[20:23], v[194:197], v[174:177], v[20:23]
	v_mfma_f32_16x16x32_bf16 v[12:15], v[204:207], v[174:177], v[12:15]
	v_mfma_f32_16x16x32_bf16 v[4:7], v[194:197], v[182:185], v[4:7]
	v_mfma_f32_16x16x32_bf16 v[0:3], v[204:207], v[182:185], v[0:3]
	s_add_i32 s45, s45, 2
	s_add_u32 s18, s18, 0x100
	s_addc_u32 s19, s19, 0
	s_add_u32 s43, s43, 0x100
	s_addc_u32 s44, s44, 0
	s_cmp_gt_u32 s45, 29
	s_barrier
	s_cbranch_scc0 .LBB0_350
	v_lshl_or_b32 v134, s33, 8, v172
	v_lshl_add_u32 v136, s16, 8, v170
	v_ashrrev_i32_e32 v135, 31, v134
	v_lshlrev_b64 v[134:135], 1, v[134:135]
	v_ashrrev_i32_e32 v137, 31, v136
	v_lshl_add_u64 v[138:139], s[0:1], 0, v[134:135]
	v_lshlrev_b64 v[140:141], 12, v[136:137]
	v_lshl_add_u64 v[140:141], v[138:139], 0, v[140:141]
	global_load_dwordx2 v[174:175], v[140:141], off
	global_load_dwordx2 v[176:177], v[140:141], off offset:32
	global_load_dwordx2 v[178:179], v[140:141], off offset:256
	global_load_dwordx2 v[180:181], v[140:141], off offset:288
	v_or_b32_e32 v166, 16, v136
	v_ashrrev_i32_e32 v167, 31, v166
	v_lshlrev_b64 v[140:141], 12, v[166:167]
	v_lshl_add_u64 v[140:141], v[138:139], 0, v[140:141]
	global_load_dwordx2 v[168:169], v[140:141], off
	global_load_dwordx2 v[164:165], v[140:141], off offset:32
	global_load_dwordx2 v[162:163], v[140:141], off offset:256
	global_load_dwordx2 v[160:161], v[140:141], off offset:288
	v_or_b32_e32 v156, 32, v136
	v_ashrrev_i32_e32 v157, 31, v156
	v_lshlrev_b64 v[140:141], 12, v[156:157]
	v_lshl_add_u64 v[140:141], v[138:139], 0, v[140:141]
	global_load_dwordx2 v[158:159], v[140:141], off
	global_load_dwordx2 v[154:155], v[140:141], off offset:32
	global_load_dwordx2 v[152:153], v[140:141], off offset:256
	global_load_dwordx2 v[146:147], v[140:141], off offset:288
	v_or_b32_e32 v148, 48, v136
	v_ashrrev_i32_e32 v149, 31, v148
	v_lshlrev_b64 v[140:141], 12, v[148:149]
	v_lshl_add_u64 v[140:141], v[138:139], 0, v[140:141]
	global_load_dwordx2 v[150:151], v[140:141], off
	global_load_dwordx2 v[144:145], v[140:141], off offset:32
	global_load_dwordx2 v[142:143], v[140:141], off offset:256
	s_nop 0
	global_load_dwordx2 v[140:141], v[140:141], off offset:288
	v_lshlrev_b64 v[182:183], 11, v[136:137]
	s_and_b64 vcc, exec, s[2:3]
	s_mov_b32 s33, s8
	s_mov_b32 s16, s10
	s_mov_b64 s[20:21], s[14:15]
	s_mov_b64 s[18:19], s[12:13]
	s_waitcnt vmcnt(0)
; __device__ __forceinline__ unsigned cvt_pk_bf16(float lo, float hi) { unsigned r; asm volatile("s_nop 0\n\tv_cvt_pk_bf16_f32 %0, %1, %2\n\ts_nop 1" : "=v"(r) : "v"(lo), "v"(hi)); return r; }
; __device__ __forceinline__ float bflo(unsigned w) { return __uint_as_float(w << 16); }
; __device__ __forceinline__ float bfhi(unsigned w) { return __uint_as_float(w & 0xffff0000u); }
;     __device__ __forceinline__ void operator()(f32x4 (&acc)[2][2][4][2], const Unit& u, int wr, int wc, int fr, int fq) const {
;     ...
;             for (int m = 0; m < 4; ++m) { const size_t row = row0 + ai * 128 + m * 16;
; #pragma unroll
;                 for (int bj = 0; bj < 2; ++bj)
; #pragma unroll
;                     for (int n = 0; n < 2; ++n) { const int col = col0 + bj * 128 + n * 16; const u32x2 g2 = gw[m][bj][n];
;                         const f32x4 gv = (f32x4){bflo(g2.x), bfhi(g2.x), bflo(g2.y), bfhi(g2.y)};
;                         const f32x4 o = gv * acc[ai][bj][m][n]; u32x2 w; w.x = cvt_pk_bf16(o[0], o[1]); w.y = cvt_pk_bf16(o[2], o[3]); *(u32x2*)(tmp + row * 1024 + col) = w; } }
	v_lshlrev_b32_e32 v184, 16, v174
	v_and_b32_e32 v185, 0xffff0000, v174
	v_lshlrev_b32_e32 v174, 16, v175
	v_and_b32_e32 v175, 0xffff0000, v175
	v_pk_mul_f32 v[126:127], v[126:127], v[174:175]
	v_pk_mul_f32 v[124:125], v[124:125], v[184:185]
	v_lshlrev_b32_e32 v174, 16, v177
	v_cvt_pk_bf16_f32 v124, v124, v125
	v_cvt_pk_bf16_f32 v125, v126, v127
	v_lshl_add_u64 v[126:127], s[4:5], 0, v[182:183]
	v_lshl_add_u64 v[126:127], v[126:127], 0, v[134:135]
	global_store_dwordx2 v[126:127], v[124:125], off
	v_lshlrev_b32_e32 v124, 16, v176
	v_and_b32_e32 v125, 0xffff0000, v176
	v_and_b32_e32 v175, 0xffff0000, v177
	v_pk_mul_f32 v[120:121], v[120:121], v[124:125]
	v_pk_mul_f32 v[122:123], v[122:123], v[174:175]
	v_cvt_pk_bf16_f32 v120, v120, v121
	s_nop 0
	v_cvt_pk_bf16_f32 v121, v122, v123
	global_store_dwordx2 v[126:127], v[120:121], off offset:32
	v_lshlrev_b32_e32 v120, 16, v178
	v_and_b32_e32 v121, 0xffff0000, v178
	v_lshlrev_b32_e32 v122, 16, v179
	v_and_b32_e32 v123, 0xffff0000, v179
	v_pk_mul_f32 v[116:117], v[116:117], v[120:121]
	v_pk_mul_f32 v[118:119], v[118:119], v[122:123]
	v_cvt_pk_bf16_f32 v116, v116, v117
	s_nop 0
	v_cvt_pk_bf16_f32 v117, v118, v119
	global_store_dwordx2 v[126:127], v[116:117], off offset:256
	v_lshlrev_b32_e32 v116, 16, v180
	v_and_b32_e32 v117, 0xffff0000, v180
	v_lshlrev_b32_e32 v118, 16, v181
	v_and_b32_e32 v119, 0xffff0000, v181
	v_pk_mul_f32 v[114:115], v[114:115], v[118:119]
	v_pk_mul_f32 v[112:113], v[112:113], v[116:117]
	v_lshlrev_b32_e32 v116, 16, v169
	v_cvt_pk_bf16_f32 v112, v112, v113
	v_cvt_pk_bf16_f32 v113, v114, v115
	v_lshlrev_b32_e32 v114, 16, v168
	v_and_b32_e32 v115, 0xffff0000, v168
	v_and_b32_e32 v117, 0xffff0000, v169
	global_store_dwordx2 v[126:127], v[112:113], off offset:288
	v_lshlrev_b64 v[112:113], 11, v[166:167]
	v_pk_mul_f32 v[110:111], v[110:111], v[116:117]
	v_pk_mul_f32 v[108:109], v[108:109], v[114:115]
	s_nop 0
	v_cvt_pk_bf16_f32 v108, v108, v109
	v_cvt_pk_bf16_f32 v109, v110, v111
	v_lshl_add_u64 v[110:111], s[4:5], 0, v[112:113]
	v_lshl_add_u64 v[110:111], v[110:111], 0, v[134:135]
	global_store_dwordx2 v[110:111], v[108:109], off
	v_lshlrev_b32_e32 v108, 16, v164
	v_and_b32_e32 v109, 0xffff0000, v164
	v_lshlrev_b32_e32 v112, 16, v165
	v_and_b32_e32 v113, 0xffff0000, v165
	v_pk_mul_f32 v[104:105], v[104:105], v[108:109]
	v_pk_mul_f32 v[106:107], v[106:107], v[112:113]
	v_cvt_pk_bf16_f32 v104, v104, v105
	s_nop 0
	v_cvt_pk_bf16_f32 v105, v106, v107
	global_store_dwordx2 v[110:111], v[104:105], off offset:32
	v_lshlrev_b32_e32 v104, 16, v162
	v_and_b32_e32 v105, 0xffff0000, v162
	v_lshlrev_b32_e32 v106, 16, v163
	v_and_b32_e32 v107, 0xffff0000, v163
	v_pk_mul_f32 v[100:101], v[100:101], v[104:105]
	v_pk_mul_f32 v[102:103], v[102:103], v[106:107]
	v_cvt_pk_bf16_f32 v100, v100, v101
	s_nop 0
	v_cvt_pk_bf16_f32 v101, v102, v103
	global_store_dwordx2 v[110:111], v[100:101], off offset:256
	v_lshlrev_b32_e32 v100, 16, v160
	v_and_b32_e32 v101, 0xffff0000, v160
	v_lshlrev_b32_e32 v102, 16, v161
	v_and_b32_e32 v103, 0xffff0000, v161
	v_pk_mul_f32 v[92:93], v[92:93], v[100:101]
	v_pk_mul_f32 v[94:95], v[94:95], v[102:103]
	v_cvt_pk_bf16_f32 v92, v92, v93
	v_lshlrev_b32_e32 v100, 16, v159
	v_cvt_pk_bf16_f32 v93, v94, v95
	global_store_dwordx2 v[110:111], v[92:93], off offset:288
	v_lshlrev_b64 v[92:93], 11, v[156:157]
	v_lshlrev_b32_e32 v94, 16, v158
	v_and_b32_e32 v95, 0xffff0000, v158
	v_and_b32_e32 v101, 0xffff0000, v159
	v_pk_mul_f32 v[94:95], v[96:97], v[94:95]
	v_lshl_add_u64 v[92:93], s[4:5], 0, v[92:93]
	v_pk_mul_f32 v[98:99], v[98:99], v[100:101]
	v_cvt_pk_bf16_f32 v94, v94, v95
	v_lshl_add_u64 v[92:93], v[92:93], 0, v[134:135]
	v_cvt_pk_bf16_f32 v95, v98, v99
	global_store_dwordx2 v[92:93], v[94:95], off
	v_lshlrev_b32_e32 v94, 16, v154
	v_and_b32_e32 v95, 0xffff0000, v154
	v_lshlrev_b32_e32 v96, 16, v155
	v_and_b32_e32 v97, 0xffff0000, v155
	v_pk_mul_f32 v[88:89], v[88:89], v[94:95]
	v_pk_mul_f32 v[90:91], v[90:91], v[96:97]
	v_cvt_pk_bf16_f32 v88, v88, v89
	v_add_u32_e32 v94, 0xa0, v136
	v_cvt_pk_bf16_f32 v89, v90, v91
	global_store_dwordx2 v[92:93], v[88:89], off offset:32
	v_lshlrev_b32_e32 v88, 16, v152
	v_and_b32_e32 v89, 0xffff0000, v152
	v_lshlrev_b32_e32 v90, 16, v153
	v_and_b32_e32 v91, 0xffff0000, v153
	v_pk_mul_f32 v[84:85], v[84:85], v[88:89]
	v_pk_mul_f32 v[86:87], v[86:87], v[90:91]
	v_cvt_pk_bf16_f32 v84, v84, v85
	v_ashrrev_i32_e32 v95, 31, v94
	v_cvt_pk_bf16_f32 v85, v86, v87
	global_store_dwordx2 v[92:93], v[84:85], off offset:256
	v_lshlrev_b32_e32 v84, 16, v146
	v_and_b32_e32 v85, 0xffff0000, v146
	v_lshlrev_b32_e32 v86, 16, v147
	v_and_b32_e32 v87, 0xffff0000, v147
	v_pk_mul_f32 v[76:77], v[76:77], v[84:85]
	v_pk_mul_f32 v[78:79], v[78:79], v[86:87]
	v_cvt_pk_bf16_f32 v76, v76, v77
	v_lshlrev_b32_e32 v84, 16, v151
	v_cvt_pk_bf16_f32 v77, v78, v79
	global_store_dwordx2 v[92:93], v[76:77], off offset:288
	v_lshlrev_b64 v[76:77], 11, v[148:149]
	v_lshlrev_b32_e32 v78, 16, v150
	v_and_b32_e32 v79, 0xffff0000, v150
	v_and_b32_e32 v85, 0xffff0000, v151
	v_pk_mul_f32 v[78:79], v[80:81], v[78:79]
	v_lshl_add_u64 v[76:77], s[4:5], 0, v[76:77]
	v_pk_mul_f32 v[82:83], v[82:83], v[84:85]
	v_cvt_pk_bf16_f32 v78, v78, v79
	v_lshl_add_u64 v[76:77], v[76:77], 0, v[134:135]
	v_cvt_pk_bf16_f32 v79, v82, v83
	global_store_dwordx2 v[76:77], v[78:79], off
	v_lshlrev_b32_e32 v78, 16, v144
	v_and_b32_e32 v79, 0xffff0000, v144
	v_lshlrev_b32_e32 v80, 16, v145
	v_and_b32_e32 v81, 0xffff0000, v145
	v_pk_mul_f32 v[72:73], v[72:73], v[78:79]
	v_pk_mul_f32 v[74:75], v[74:75], v[80:81]
	v_cvt_pk_bf16_f32 v72, v72, v73
	v_add_u32_e32 v84, 0x90, v136
	v_cvt_pk_bf16_f32 v73, v74, v75
; __device__ __forceinline__ unsigned cvt_pk_bf16(float lo, float hi) { unsigned r; asm volatile("s_nop 0\n\tv_cvt_pk_bf16_f32 %0, %1, %2\n\ts_nop 1" : "=v"(r) : "v"(lo), "v"(hi)); return r; }
; __device__ __forceinline__ float bflo(unsigned w) { return __uint_as_float(w << 16); }
; __device__ __forceinline__ float bfhi(unsigned w) { return __uint_as_float(w & 0xffff0000u); }
;     __device__ __forceinline__ void operator()(f32x4 (&acc)[2][2][4][2], const Unit& u, int wr, int wc, int fr, int fq) const {
;     ...
;             u32x2 gw[4][2][2];
; #pragma unroll
;             for (int m = 0; m < 4; ++m)
; #pragma unroll
;                 for (int bj = 0; bj < 2; ++bj)
; #pragma unroll
;                     for (int n = 0; n < 2; ++n) gw[m][bj][n] = *(const u32x2*)(gates + (size_t)(row0 + ai * 128 + m * 16) * 2048 + col0 + bj * 128 + n * 16);
;     ...
;             for (int m = 0; m < 4; ++m) { const size_t row = row0 + ai * 128 + m * 16;
; #pragma unroll
;                 for (int bj = 0; bj < 2; ++bj)
; #pragma unroll
;                     for (int n = 0; n < 2; ++n) { const int col = col0 + bj * 128 + n * 16; const u32x2 g2 = gw[m][bj][n];
;                         const f32x4 gv = (f32x4){bflo(g2.x), bfhi(g2.x), bflo(g2.y), bfhi(g2.y)};
;                         const f32x4 o = gv * acc[ai][bj][m][n]; u32x2 w; w.x = cvt_pk_bf16(o[0], o[1]); w.y = cvt_pk_bf16(o[2], o[3]); *(u32x2*)(tmp + row * 1024 + col) = w; } }
	global_store_dwordx2 v[76:77], v[72:73], off offset:32
	v_lshlrev_b32_e32 v72, 16, v142
	v_and_b32_e32 v73, 0xffff0000, v142
	v_lshlrev_b32_e32 v74, 16, v143
	v_and_b32_e32 v75, 0xffff0000, v143
	v_pk_mul_f32 v[68:69], v[68:69], v[72:73]
	v_pk_mul_f32 v[70:71], v[70:71], v[74:75]
	v_cvt_pk_bf16_f32 v68, v68, v69
	v_add_u32_e32 v74, 0x80, v136
	v_cvt_pk_bf16_f32 v69, v70, v71
	global_store_dwordx2 v[76:77], v[68:69], off offset:256
	v_lshlrev_b32_e32 v68, 16, v140
	v_and_b32_e32 v69, 0xffff0000, v140
	v_lshlrev_b32_e32 v70, 16, v141
	v_and_b32_e32 v71, 0xffff0000, v141
	v_pk_mul_f32 v[64:65], v[64:65], v[68:69]
	v_pk_mul_f32 v[66:67], v[66:67], v[70:71]
	v_cvt_pk_bf16_f32 v64, v64, v65
	v_ashrrev_i32_e32 v75, 31, v74
	v_cvt_pk_bf16_f32 v65, v66, v67
	global_store_dwordx2 v[76:77], v[64:65], off offset:288
	v_lshlrev_b64 v[64:65], 12, v[74:75]
	v_lshl_add_u64 v[64:65], v[138:139], 0, v[64:65]
	global_load_dwordx2 v[76:77], v[64:65], off
	global_load_dwordx2 v[78:79], v[64:65], off offset:32
	global_load_dwordx2 v[80:81], v[64:65], off offset:256
	global_load_dwordx2 v[82:83], v[64:65], off offset:288
	v_ashrrev_i32_e32 v85, 31, v84
	v_lshlrev_b64 v[64:65], 12, v[84:85]
	v_lshl_add_u64 v[64:65], v[138:139], 0, v[64:65]
	global_load_dwordx2 v[86:87], v[64:65], off
	global_load_dwordx2 v[88:89], v[64:65], off offset:32
	global_load_dwordx2 v[90:91], v[64:65], off offset:256
	global_load_dwordx2 v[92:93], v[64:65], off offset:288
	v_lshlrev_b64 v[64:65], 12, v[94:95]
	v_lshl_add_u64 v[64:65], v[138:139], 0, v[64:65]
	global_load_dwordx2 v[96:97], v[64:65], off
	global_load_dwordx2 v[98:99], v[64:65], off offset:32
	global_load_dwordx2 v[100:101], v[64:65], off offset:256
	global_load_dwordx2 v[102:103], v[64:65], off offset:288
	v_add_u32_e32 v70, 0xb0, v136
	v_ashrrev_i32_e32 v71, 31, v70
	v_lshlrev_b64 v[64:65], 12, v[70:71]
	v_lshl_add_u64 v[64:65], v[138:139], 0, v[64:65]
	global_load_dwordx2 v[72:73], v[64:65], off
	global_load_dwordx2 v[68:69], v[64:65], off offset:32
	global_load_dwordx2 v[66:67], v[64:65], off offset:256
	s_nop 0
	global_load_dwordx2 v[64:65], v[64:65], off offset:288
	v_lshlrev_b64 v[74:75], 11, v[74:75]
	s_waitcnt vmcnt(0)
; __device__ __forceinline__ unsigned cvt_pk_bf16(float lo, float hi) { unsigned r; asm volatile("s_nop 0\n\tv_cvt_pk_bf16_f32 %0, %1, %2\n\ts_nop 1" : "=v"(r) : "v"(lo), "v"(hi)); return r; }
; #define PG8_WAIT_V(n) asm volatile("s_waitcnt vmcnt(" #n ")" ::: "memory")
; #define PG8_BAR __builtin_amdgcn_s_barrier()
; __device__ __forceinline__ float bflo(unsigned w) { return __uint_as_float(w << 16); }
; __device__ __forceinline__ float bfhi(unsigned w) { return __uint_as_float(w & 0xffff0000u); }
; template <class Epi, class Sched>
; __device__ __forceinline__ void gemm_phase(PG8_LAS unsigned char* lds, const Gemm g, const Sched& S, const Epi& E, int tid_in) {
;     ...
;         if (!has_next) break;
; #pragma unroll
;         for (int a = 0; a < 2; ++a)
; #pragma unroll
;             for (int b = 0; b < 2; ++b)
; #pragma unroll
;                 for (int m = 0; m < 4; ++m)
; #pragma unroll
;                     for (int n = 0; n < 2; ++n) acc[a][b][m][n] = (f32x4){0.f, 0.f, 0.f, 0.f};
;         cur = nxt; cA = nA; cB = nB; ++ui;
;     }
;     PG8_WAIT_V(0);
;     if (wr == 0) PG8_BAR;
;     PG8_BAR;
;     __device__ __forceinline__ void operator()(f32x4 (&acc)[2][2][4][2], const Unit& u, int wr, int wc, int fr, int fq) const {
;     ...
;             for (int m = 0; m < 4; ++m) { const size_t row = row0 + ai * 128 + m * 16;
; #pragma unroll
;                 for (int bj = 0; bj < 2; ++bj)
; #pragma unroll
;                     for (int n = 0; n < 2; ++n) { const int col = col0 + bj * 128 + n * 16; const u32x2 g2 = gw[m][bj][n];
;                         const f32x4 gv = (f32x4){bflo(g2.x), bfhi(g2.x), bflo(g2.y), bfhi(g2.y)};
;                         const f32x4 o = gv * acc[ai][bj][m][n]; u32x2 w; w.x = cvt_pk_bf16(o[0], o[1]); w.y = cvt_pk_bf16(o[2], o[3]); *(u32x2*)(tmp + row * 1024 + col) = w; } }
	v_lshlrev_b32_e32 v104, 16, v76
	v_and_b32_e32 v105, 0xffff0000, v76
	v_lshlrev_b32_e32 v76, 16, v77
	v_and_b32_e32 v77, 0xffff0000, v77
	v_pk_mul_f32 v[62:63], v[62:63], v[76:77]
	v_pk_mul_f32 v[60:61], v[60:61], v[104:105]
	s_nop 0
	v_cvt_pk_bf16_f32 v60, v60, v61
	v_cvt_pk_bf16_f32 v61, v62, v63
	v_lshl_add_u64 v[62:63], s[4:5], 0, v[74:75]
	v_lshl_add_u64 v[62:63], v[62:63], 0, v[134:135]
	global_store_dwordx2 v[62:63], v[60:61], off
	v_lshlrev_b32_e32 v60, 16, v78
	v_and_b32_e32 v61, 0xffff0000, v78
	v_lshlrev_b32_e32 v74, 16, v79
	v_and_b32_e32 v75, 0xffff0000, v79
	v_pk_mul_f32 v[56:57], v[56:57], v[60:61]
	v_pk_mul_f32 v[58:59], v[58:59], v[74:75]
	v_cvt_pk_bf16_f32 v56, v56, v57
	s_nop 0
	v_cvt_pk_bf16_f32 v57, v58, v59
	global_store_dwordx2 v[62:63], v[56:57], off offset:32
	v_lshlrev_b32_e32 v56, 16, v80
	v_and_b32_e32 v57, 0xffff0000, v80
	v_lshlrev_b32_e32 v58, 16, v81
	v_and_b32_e32 v59, 0xffff0000, v81
	v_pk_mul_f32 v[52:53], v[52:53], v[56:57]
	v_pk_mul_f32 v[54:55], v[54:55], v[58:59]
	v_cvt_pk_bf16_f32 v52, v52, v53
	s_nop 0
	v_cvt_pk_bf16_f32 v53, v54, v55
	global_store_dwordx2 v[62:63], v[52:53], off offset:256
	v_lshlrev_b32_e32 v52, 16, v82
	v_and_b32_e32 v53, 0xffff0000, v82
	v_lshlrev_b32_e32 v54, 16, v83
	v_and_b32_e32 v55, 0xffff0000, v83
	v_pk_mul_f32 v[44:45], v[44:45], v[52:53]
	v_pk_mul_f32 v[46:47], v[46:47], v[54:55]
	v_cvt_pk_bf16_f32 v44, v44, v45
	v_lshlrev_b32_e32 v52, 16, v87
	v_cvt_pk_bf16_f32 v45, v46, v47
	global_store_dwordx2 v[62:63], v[44:45], off offset:288
	v_lshlrev_b64 v[44:45], 11, v[84:85]
	v_lshlrev_b32_e32 v46, 16, v86
	v_and_b32_e32 v47, 0xffff0000, v86
	v_and_b32_e32 v53, 0xffff0000, v87
	v_pk_mul_f32 v[46:47], v[48:49], v[46:47]
	v_lshl_add_u64 v[44:45], s[4:5], 0, v[44:45]
	v_pk_mul_f32 v[50:51], v[50:51], v[52:53]
	v_cvt_pk_bf16_f32 v46, v46, v47
	v_lshl_add_u64 v[44:45], v[44:45], 0, v[134:135]
	v_cvt_pk_bf16_f32 v47, v50, v51
	global_store_dwordx2 v[44:45], v[46:47], off
	v_lshlrev_b32_e32 v46, 16, v88
	v_and_b32_e32 v47, 0xffff0000, v88
	v_lshlrev_b32_e32 v48, 16, v89
	v_and_b32_e32 v49, 0xffff0000, v89
	v_pk_mul_f32 v[40:41], v[40:41], v[46:47]
	v_pk_mul_f32 v[42:43], v[42:43], v[48:49]
	v_cvt_pk_bf16_f32 v40, v40, v41
	s_nop 0
	v_cvt_pk_bf16_f32 v41, v42, v43
	global_store_dwordx2 v[44:45], v[40:41], off offset:32
	v_lshlrev_b32_e32 v40, 16, v90
	v_and_b32_e32 v41, 0xffff0000, v90
	v_lshlrev_b32_e32 v42, 16, v91
	v_and_b32_e32 v43, 0xffff0000, v91
	v_pk_mul_f32 v[36:37], v[36:37], v[40:41]
	v_pk_mul_f32 v[38:39], v[38:39], v[42:43]
	v_cvt_pk_bf16_f32 v36, v36, v37
	s_nop 0
	v_cvt_pk_bf16_f32 v37, v38, v39
	global_store_dwordx2 v[44:45], v[36:37], off offset:256
	v_lshlrev_b32_e32 v36, 16, v92
	v_and_b32_e32 v37, 0xffff0000, v92
	v_lshlrev_b32_e32 v38, 16, v93
	v_and_b32_e32 v39, 0xffff0000, v93
	v_pk_mul_f32 v[28:29], v[28:29], v[36:37]
	v_pk_mul_f32 v[30:31], v[30:31], v[38:39]
	v_cvt_pk_bf16_f32 v28, v28, v29
	v_lshlrev_b32_e32 v36, 16, v97
	v_cvt_pk_bf16_f32 v29, v30, v31
	global_store_dwordx2 v[44:45], v[28:29], off offset:288
	v_lshlrev_b64 v[28:29], 11, v[94:95]
	v_lshlrev_b32_e32 v30, 16, v96
	v_and_b32_e32 v31, 0xffff0000, v96
	v_and_b32_e32 v37, 0xffff0000, v97
	v_pk_mul_f32 v[30:31], v[32:33], v[30:31]
	v_lshl_add_u64 v[28:29], s[4:5], 0, v[28:29]
	v_pk_mul_f32 v[34:35], v[34:35], v[36:37]
	v_cvt_pk_bf16_f32 v30, v30, v31
	v_lshl_add_u64 v[28:29], v[28:29], 0, v[134:135]
	v_cvt_pk_bf16_f32 v31, v34, v35
	global_store_dwordx2 v[28:29], v[30:31], off
	v_lshlrev_b32_e32 v30, 16, v98
	v_and_b32_e32 v31, 0xffff0000, v98
	v_lshlrev_b32_e32 v32, 16, v99
	v_and_b32_e32 v33, 0xffff0000, v99
	v_pk_mul_f32 v[24:25], v[24:25], v[30:31]
	v_pk_mul_f32 v[26:27], v[26:27], v[32:33]
	v_cvt_pk_bf16_f32 v24, v24, v25
	s_nop 0
	v_cvt_pk_bf16_f32 v25, v26, v27
	global_store_dwordx2 v[28:29], v[24:25], off offset:32
	v_lshlrev_b32_e32 v24, 16, v100
	v_and_b32_e32 v25, 0xffff0000, v100
	v_lshlrev_b32_e32 v26, 16, v101
	v_and_b32_e32 v27, 0xffff0000, v101
	v_pk_mul_f32 v[20:21], v[20:21], v[24:25]
	v_pk_mul_f32 v[22:23], v[22:23], v[26:27]
	v_cvt_pk_bf16_f32 v20, v20, v21
	s_nop 0
	v_cvt_pk_bf16_f32 v21, v22, v23
	global_store_dwordx2 v[28:29], v[20:21], off offset:256
	v_lshlrev_b32_e32 v20, 16, v102
	v_and_b32_e32 v21, 0xffff0000, v102
	v_lshlrev_b32_e32 v22, 16, v103
	v_and_b32_e32 v23, 0xffff0000, v103
	v_pk_mul_f32 v[12:13], v[12:13], v[20:21]
	v_pk_mul_f32 v[14:15], v[14:15], v[22:23]
	v_cvt_pk_bf16_f32 v12, v12, v13
	v_lshlrev_b32_e32 v20, 16, v73
	v_cvt_pk_bf16_f32 v13, v14, v15
	global_store_dwordx2 v[28:29], v[12:13], off offset:288
	v_lshlrev_b64 v[12:13], 11, v[70:71]
	v_lshlrev_b32_e32 v14, 16, v72
	v_and_b32_e32 v15, 0xffff0000, v72
	v_and_b32_e32 v21, 0xffff0000, v73
	v_pk_mul_f32 v[14:15], v[16:17], v[14:15]
	v_lshl_add_u64 v[12:13], s[4:5], 0, v[12:13]
	v_pk_mul_f32 v[18:19], v[18:19], v[20:21]
	v_cvt_pk_bf16_f32 v14, v14, v15
	v_lshl_add_u64 v[12:13], v[12:13], 0, v[134:135]
	v_cvt_pk_bf16_f32 v15, v18, v19
	global_store_dwordx2 v[12:13], v[14:15], off
	v_lshlrev_b32_e32 v14, 16, v68
	v_and_b32_e32 v15, 0xffff0000, v68
	v_lshlrev_b32_e32 v16, 16, v69
	v_and_b32_e32 v17, 0xffff0000, v69
	v_pk_mul_f32 v[8:9], v[8:9], v[14:15]
	v_pk_mul_f32 v[10:11], v[10:11], v[16:17]
	v_cvt_pk_bf16_f32 v8, v8, v9
	s_nop 0
	v_cvt_pk_bf16_f32 v9, v10, v11
	global_store_dwordx2 v[12:13], v[8:9], off offset:32
	v_lshlrev_b32_e32 v8, 16, v66
	v_and_b32_e32 v9, 0xffff0000, v66
	v_lshlrev_b32_e32 v10, 16, v67
	v_and_b32_e32 v11, 0xffff0000, v67
	v_pk_mul_f32 v[4:5], v[4:5], v[8:9]
	v_pk_mul_f32 v[6:7], v[6:7], v[10:11]
	v_cvt_pk_bf16_f32 v4, v4, v5
	s_nop 0
	v_cvt_pk_bf16_f32 v5, v6, v7
	global_store_dwordx2 v[12:13], v[4:5], off offset:256
	v_lshlrev_b32_e32 v4, 16, v64
	v_and_b32_e32 v5, 0xffff0000, v64
	v_lshlrev_b32_e32 v6, 16, v65
	v_and_b32_e32 v7, 0xffff0000, v65
	v_pk_mul_f32 v[0:1], v[0:1], v[4:5]
	v_pk_mul_f32 v[2:3], v[2:3], v[6:7]
	v_cvt_pk_bf16_f32 v0, v0, v1
	s_nop 0
	v_cvt_pk_bf16_f32 v1, v2, v3
	s_nop 1
	global_store_dwordx2 v[12:13], v[0:1], off offset:288
	s_cbranch_vccz .LBB0_343
	s_waitcnt vmcnt(0)
	s_cmpk_gt_u32 s24, 0xff
	s_cbranch_scc1 .LBB0_354
	s_barrier

; #define PG8_STAGE(bufoff, gbase, voff) do { _Pragma("unroll") for (int _i = 0; _i < 2; ++_i) \
;         __builtin_amdgcn_global_load_lds((const unsigned*)((const char*)(gbase) + (voff)[_i]), (PG8_LAS unsigned*)(lds + (bufoff) + ldsw + _i * 8192), 16, 0, 0); } while (0)
; #define PG8_LDA(dst, b, h) do { _Pragma("unroll") for (int m = 0; m < 4; ++m) _Pragma("unroll") for (int k = 0; k < 2; ++k) dst[m][k] = *(const PG8_LAS bf16x8*)(lds + PG8_SA(b, h) + aoff + m * 2048 + k * 1024); } while (0)
; #define PG8_LDB(dst, b, h) do { _Pragma("unroll") for (int n = 0; n < 2; ++n) _Pragma("unroll") for (int k = 0; k < 2; ++k) dst[n][k] = *(const PG8_LAS bf16x8*)(lds + PG8_SB(b, h) + boff + n * 2048 + k * 1024); } while (0)
; #define PG8_MMA(ai, bj, At, Bt) do { __builtin_amdgcn_s_setprio(1); _Pragma("unroll") for (int m = 0; m < 4; ++m) _Pragma("unroll") for (int n = 0; n < 2; ++n) _Pragma("unroll") for (int k = 0; k < 2; ++k) \
;         acc[ai][bj][m][n] = __builtin_amdgcn_mfma_f32_16x16x32_bf16(Bt[n][k], At[m][k], acc[ai][bj][m][n], 0, 0, 0); __builtin_amdgcn_s_setprio(0); } while (0)
; #define PG8_WAIT_L(n) asm volatile("s_waitcnt lgkmcnt(" #n ")" ::: "memory")
; #define PG8_BAR __builtin_amdgcn_s_barrier()
; #define PG8_SCHED __builtin_amdgcn_sched_barrier(0)
; template <class Epi, class Sched>
; __device__ __forceinline__ void gemm_phase(PG8_LAS unsigned char* lds, const Gemm g, const Sched& S, const Epi& E, int tid_in) {
;     ...
;             PG8_LDB(B0, 0, 0); PG8_SCHED; PG8_LDA(At, 0, 0); PG8_STAGE(PG8_SA(1, 1), a1 + hstep, voffA);
;             PG8_WAIT_L(8); PG8_BAR; PG8_WAIT_L(0); PG8_MMA(0, 0, At, B0); PG8_BAR; PG8_SCHED;
;             PG8_LDB(B1, 0, 1); PG8_STAGE(PG8_SB(0, 0), b2, voffB);
;             PG8_BAR; PG8_WAIT_L(0); PG8_MMA(0, 1, At, B1); PG8_BAR;
;             PG8_LDA(At, 0, 1); PG8_STAGE(PG8_SA(0, 0), a2, voffA);
;             PG8_BAR; PG8_WAIT_L(0); PG8_MMA(1, 0, At, B0); PG8_BAR; PG8_SCHED;
.LBB0_370:
	s_add_u32 s20, s18, 0xfffc0080
	s_addc_u32 s21, s19, -1
	s_add_i32 s46, 0, 0x10000
	v_add_u32_e32 v146, s46, v214
	ds_read_b128 v[134:137], v146
	ds_read_b128 v[138:141], v146 offset:1024
	ds_read_b128 v[142:145], v146 offset:2048
	ds_read_b128 v[146:149], v146 offset:3072
	s_cmp_eq_u32 s45, 12
	s_cselect_b32 s23, s11, s21
	s_cselect_b32 s22, s41, s20
	s_cselect_b32 s21, s9, s44
	s_cselect_b32 s20, s42, s43
	v_lshl_add_u64 v[182:183], s[18:19], 0, v[130:131]
	s_add_i32 m0, s17, 0xc000
	ds_read_b128 v[150:153], v216
	ds_read_b128 v[154:157], v216 offset:1024
	ds_read_b128 v[158:161], v216 offset:2048
	ds_read_b128 v[162:165], v216 offset:3072
	ds_read_b128 v[166:169], v216 offset:4096
	ds_read_b128 v[170:173], v216 offset:5120
	ds_read_b128 v[174:177], v216 offset:6144
	ds_read_b128 v[178:181], v216 offset:7168
	global_load_lds_dwordx4 v[182:183], off
	s_add_i32 m0, s17, 0xe000
	v_lshl_add_u64 v[182:183], s[18:19], 0, v[132:133]
	global_load_lds_dwordx4 v[182:183], off
	s_waitcnt lgkmcnt(8)
	s_barrier
	s_waitcnt lgkmcnt(0)
	s_waitcnt lgkmcnt(0)
	v_mfma_f32_16x16x32_bf16 v[124:127], v[134:137], v[150:153], v[124:127]
	v_mfma_f32_16x16x32_bf16 v[120:123], v[142:145], v[150:153], v[120:123]
	v_mfma_f32_16x16x32_bf16 v[108:111], v[134:137], v[158:161], v[108:111]
	v_mfma_f32_16x16x32_bf16 v[104:107], v[142:145], v[158:161], v[104:107]
	v_mfma_f32_16x16x32_bf16 v[92:95], v[134:137], v[166:169], v[92:95]
	v_mfma_f32_16x16x32_bf16 v[88:91], v[142:145], v[166:169], v[88:91]
	v_mfma_f32_16x16x32_bf16 v[76:79], v[134:137], v[174:177], v[76:79]
	v_mfma_f32_16x16x32_bf16 v[72:75], v[142:145], v[174:177], v[72:75]
	v_mfma_f32_16x16x32_bf16 v[124:127], v[138:141], v[154:157], v[124:127]
	v_mfma_f32_16x16x32_bf16 v[120:123], v[146:149], v[154:157], v[120:123]
	v_mfma_f32_16x16x32_bf16 v[108:111], v[138:141], v[162:165], v[108:111]
	v_mfma_f32_16x16x32_bf16 v[104:107], v[146:149], v[162:165], v[104:107]
	v_mfma_f32_16x16x32_bf16 v[92:95], v[138:141], v[170:173], v[92:95]
	v_mfma_f32_16x16x32_bf16 v[88:91], v[146:149], v[170:173], v[88:91]
	v_mfma_f32_16x16x32_bf16 v[76:79], v[138:141], v[178:181], v[76:79]
	v_mfma_f32_16x16x32_bf16 v[72:75], v[146:149], v[178:181], v[72:75]
	s_barrier
	s_add_i32 s50, 0, 0x14000
	v_add_u32_e32 v190, s50, v214
	s_add_i32 s46, s46, s30
	ds_read_b128 v[182:185], v190
	ds_read_b128 v[186:189], v190 offset:1024
	ds_read_b128 v[194:197], v190 offset:2048
	ds_read_b128 v[200:203], v190 offset:3072
	v_lshl_add_u64 v[190:191], s[20:21], 0, v[192:193]
	s_mov_b32 m0, s46
	v_lshl_add_u64 v[204:205], s[20:21], 0, v[128:129]
	global_load_lds_dwordx4 v[190:191], off
	s_add_i32 m0, s46, 0x2000
	s_nop 0
	global_load_lds_dwordx4 v[204:205], off
	s_barrier
	s_waitcnt lgkmcnt(0)
	s_waitcnt lgkmcnt(0)
	v_mfma_f32_16x16x32_bf16 v[116:119], v[182:185], v[150:153], v[116:119]
	v_mfma_f32_16x16x32_bf16 v[112:115], v[194:197], v[150:153], v[112:115]
	v_mfma_f32_16x16x32_bf16 v[100:103], v[182:185], v[158:161], v[100:103]
	v_mfma_f32_16x16x32_bf16 v[96:99], v[194:197], v[158:161], v[96:99]
	v_mfma_f32_16x16x32_bf16 v[84:87], v[182:185], v[166:169], v[84:87]
	v_mfma_f32_16x16x32_bf16 v[80:83], v[194:197], v[166:169], v[80:83]
	v_mfma_f32_16x16x32_bf16 v[68:71], v[182:185], v[174:177], v[68:71]
	v_mfma_f32_16x16x32_bf16 v[64:67], v[194:197], v[174:177], v[64:67]
	v_mfma_f32_16x16x32_bf16 v[116:119], v[186:189], v[154:157], v[116:119]
	v_mfma_f32_16x16x32_bf16 v[112:115], v[200:203], v[154:157], v[112:115]
	v_mfma_f32_16x16x32_bf16 v[100:103], v[186:189], v[162:165], v[100:103]
	v_mfma_f32_16x16x32_bf16 v[96:99], v[200:203], v[162:165], v[96:99]
	v_mfma_f32_16x16x32_bf16 v[84:87], v[186:189], v[170:173], v[84:87]
	v_mfma_f32_16x16x32_bf16 v[80:83], v[200:203], v[170:173], v[80:83]
	v_mfma_f32_16x16x32_bf16 v[68:71], v[186:189], v[178:181], v[68:71]
	v_mfma_f32_16x16x32_bf16 v[64:67], v[200:203], v[178:181], v[64:67]
	s_mov_b32 m0, s17
	v_lshl_add_u64 v[206:207], s[22:23], 0, v[192:193]
	s_barrier
	ds_read_b128 v[150:153], v216 offset:16384
	ds_read_b128 v[154:157], v216 offset:17408
	ds_read_b128 v[158:161], v216 offset:18432
	ds_read_b128 v[162:165], v216 offset:19456
	ds_read_b128 v[166:169], v216 offset:20480
	ds_read_b128 v[170:173], v216 offset:21504
	ds_read_b128 v[174:177], v216 offset:22528
	ds_read_b128 v[178:181], v216 offset:23552
	global_load_lds_dwordx4 v[206:207], off
	s_mov_b32 m0, s31
	v_lshl_add_u64 v[208:209], s[22:23], 0, v[128:129]
	global_load_lds_dwordx4 v[208:209], off
	s_barrier
	s_waitcnt lgkmcnt(0)
	s_waitcnt lgkmcnt(0)
	v_mfma_f32_16x16x32_bf16 v[60:63], v[134:137], v[150:153], v[60:63]
	v_mfma_f32_16x16x32_bf16 v[56:59], v[142:145], v[150:153], v[56:59]
	v_mfma_f32_16x16x32_bf16 v[44:47], v[134:137], v[158:161], v[44:47]
	v_mfma_f32_16x16x32_bf16 v[40:43], v[142:145], v[158:161], v[40:43]
	v_mfma_f32_16x16x32_bf16 v[28:31], v[134:137], v[166:169], v[28:31]
	v_mfma_f32_16x16x32_bf16 v[24:27], v[142:145], v[166:169], v[24:27]
	v_mfma_f32_16x16x32_bf16 v[12:15], v[134:137], v[174:177], v[12:15]
	v_mfma_f32_16x16x32_bf16 v[8:11], v[142:145], v[174:177], v[8:11]
	v_mfma_f32_16x16x32_bf16 v[60:63], v[138:141], v[154:157], v[60:63]
	v_mfma_f32_16x16x32_bf16 v[56:59], v[146:149], v[154:157], v[56:59]
	v_mfma_f32_16x16x32_bf16 v[44:47], v[138:141], v[162:165], v[44:47]
	v_mfma_f32_16x16x32_bf16 v[40:43], v[146:149], v[162:165], v[40:43]
	v_mfma_f32_16x16x32_bf16 v[28:31], v[138:141], v[170:173], v[28:31]
	v_mfma_f32_16x16x32_bf16 v[24:27], v[146:149], v[170:173], v[24:27]
	v_mfma_f32_16x16x32_bf16 v[12:15], v[138:141], v[178:181], v[12:15]
	v_mfma_f32_16x16x32_bf16 v[8:11], v[146:149], v[178:181], v[8:11]
	s_barrier
; #define PG8_STAGE(bufoff, gbase, voff) do { _Pragma("unroll") for (int _i = 0; _i < 2; ++_i) \
;         __builtin_amdgcn_global_load_lds((const unsigned*)((const char*)(gbase) + (voff)[_i]), (PG8_LAS unsigned*)(lds + (bufoff) + ldsw + _i * 8192), 16, 0, 0); } while (0)
; #define PG8_LDA(dst, b, h) do { _Pragma("unroll") for (int m = 0; m < 4; ++m) _Pragma("unroll") for (int k = 0; k < 2; ++k) dst[m][k] = *(const PG8_LAS bf16x8*)(lds + PG8_SA(b, h) + aoff + m * 2048 + k * 1024); } while (0)
; #define PG8_LDB(dst, b, h) do { _Pragma("unroll") for (int n = 0; n < 2; ++n) _Pragma("unroll") for (int k = 0; k < 2; ++k) dst[n][k] = *(const PG8_LAS bf16x8*)(lds + PG8_SB(b, h) + boff + n * 2048 + k * 1024); } while (0)
; #define PG8_MMA(ai, bj, At, Bt) do { __builtin_amdgcn_s_setprio(1); _Pragma("unroll") for (int m = 0; m < 4; ++m) _Pragma("unroll") for (int n = 0; n < 2; ++n) _Pragma("unroll") for (int k = 0; k < 2; ++k) \
;         acc[ai][bj][m][n] = __builtin_amdgcn_mfma_f32_16x16x32_bf16(Bt[n][k], At[m][k], acc[ai][bj][m][n], 0, 0, 0); __builtin_amdgcn_s_setprio(0); } while (0)
; #define PG8_WAIT_V(n) asm volatile("s_waitcnt vmcnt(" #n ")" ::: "memory")
; #define PG8_WAIT_L(n) asm volatile("s_waitcnt lgkmcnt(" #n ")" ::: "memory")
; #define PG8_BAR __builtin_amdgcn_s_barrier()
; #define PG8_SCHED __builtin_amdgcn_sched_barrier(0)
; template <class Epi, class Sched>
; __device__ __forceinline__ void gemm_phase(PG8_LAS unsigned char* lds, const Gemm g, const Sched& S, const Epi& E, int tid_in) {
;     ...
;             PG8_STAGE(PG8_SB(0, 1), b2 + hstep, voffB);
;             PG8_WAIT_V(6); PG8_BAR; PG8_MMA(1, 1, At, B1); PG8_BAR;
;             PG8_LDB(B0, 1, 0); PG8_SCHED; PG8_LDA(At, 1, 0); PG8_STAGE(PG8_SA(0, 1), a2 + hstep, voffA);
;             PG8_WAIT_L(8); PG8_BAR; PG8_WAIT_L(0); PG8_MMA(0, 0, At, B0); PG8_BAR; PG8_SCHED;
;             PG8_LDB(B1, 1, 1); PG8_STAGE(PG8_SB(1, 0), b3, voffB);
;             PG8_BAR; PG8_WAIT_L(0); PG8_MMA(0, 1, At, B1); PG8_BAR;
;             PG8_LDA(At, 1, 1); PG8_STAGE(PG8_SA(1, 0), a3, voffA);
	s_add_u32 s48, s20, 0x40000
	s_addc_u32 s49, s21, 0
	s_add_i32 s46, s50, s30
	s_mov_b32 m0, s46
	v_lshl_add_u64 v[134:135], s[48:49], 0, v[192:193]
	global_load_lds_dwordx4 v[134:135], off
	s_add_i32 m0, s46, 0x2000
	v_lshl_add_u64 v[134:135], s[48:49], 0, v[128:129]
	global_load_lds_dwordx4 v[134:135], off
	s_waitcnt vmcnt(6)
	s_barrier
	v_mfma_f32_16x16x32_bf16 v[52:55], v[182:185], v[150:153], v[52:55]
	v_mfma_f32_16x16x32_bf16 v[48:51], v[194:197], v[150:153], v[48:51]
	v_mfma_f32_16x16x32_bf16 v[36:39], v[182:185], v[158:161], v[36:39]
	v_mfma_f32_16x16x32_bf16 v[32:35], v[194:197], v[158:161], v[32:35]
	v_mfma_f32_16x16x32_bf16 v[20:23], v[182:185], v[166:169], v[20:23]
	v_mfma_f32_16x16x32_bf16 v[16:19], v[194:197], v[166:169], v[16:19]
	v_mfma_f32_16x16x32_bf16 v[4:7], v[182:185], v[174:177], v[4:7]
	v_mfma_f32_16x16x32_bf16 v[0:3], v[194:197], v[174:177], v[0:3]
	v_mfma_f32_16x16x32_bf16 v[52:55], v[186:189], v[154:157], v[52:55]
	v_mfma_f32_16x16x32_bf16 v[48:51], v[200:203], v[154:157], v[48:51]
	v_mfma_f32_16x16x32_bf16 v[36:39], v[186:189], v[162:165], v[36:39]
	v_mfma_f32_16x16x32_bf16 v[32:35], v[200:203], v[162:165], v[32:35]
	v_mfma_f32_16x16x32_bf16 v[20:23], v[186:189], v[170:173], v[20:23]
	v_mfma_f32_16x16x32_bf16 v[16:19], v[200:203], v[170:173], v[16:19]
	v_mfma_f32_16x16x32_bf16 v[4:7], v[186:189], v[178:181], v[4:7]
	v_mfma_f32_16x16x32_bf16 v[0:3], v[200:203], v[178:181], v[0:3]
	s_add_i32 s46, 0, 0x18000
	v_add_u32_e32 v146, s46, v214
	s_barrier
	ds_read_b128 v[134:137], v146
	ds_read_b128 v[138:141], v146 offset:1024
	ds_read_b128 v[142:145], v146 offset:2048
	ds_read_b128 v[146:149], v146 offset:3072
	s_add_u32 s22, s22, 0x40000
	s_addc_u32 s23, s23, 0
	s_mov_b32 m0, s36
	v_lshl_add_u64 v[182:183], s[22:23], 0, v[192:193]
	ds_read_b128 v[150:153], v216 offset:32768
	ds_read_b128 v[154:157], v216 offset:33792
	ds_read_b128 v[158:161], v216 offset:34816
	ds_read_b128 v[162:165], v216 offset:35840
	ds_read_b128 v[166:169], v216 offset:36864
	ds_read_b128 v[170:173], v216 offset:37888
	ds_read_b128 v[174:177], v216 offset:38912
	ds_read_b128 v[178:181], v216 offset:39936
	global_load_lds_dwordx4 v[182:183], off
	s_mov_b32 m0, s37
	v_lshl_add_u64 v[182:183], s[22:23], 0, v[128:129]
	global_load_lds_dwordx4 v[182:183], off
	s_waitcnt lgkmcnt(8)
	s_barrier
	s_waitcnt lgkmcnt(0)
	s_waitcnt lgkmcnt(0)
	v_mfma_f32_16x16x32_bf16 v[124:127], v[134:137], v[150:153], v[124:127]
	v_mfma_f32_16x16x32_bf16 v[120:123], v[142:145], v[150:153], v[120:123]
	v_mfma_f32_16x16x32_bf16 v[108:111], v[134:137], v[158:161], v[108:111]
	v_mfma_f32_16x16x32_bf16 v[104:107], v[142:145], v[158:161], v[104:107]
	v_mfma_f32_16x16x32_bf16 v[92:95], v[134:137], v[166:169], v[92:95]
	v_mfma_f32_16x16x32_bf16 v[88:91], v[142:145], v[166:169], v[88:91]
	v_mfma_f32_16x16x32_bf16 v[76:79], v[134:137], v[174:177], v[76:79]
	v_mfma_f32_16x16x32_bf16 v[72:75], v[142:145], v[174:177], v[72:75]
	v_mfma_f32_16x16x32_bf16 v[124:127], v[138:141], v[154:157], v[124:127]
	v_mfma_f32_16x16x32_bf16 v[120:123], v[146:149], v[154:157], v[120:123]
	v_mfma_f32_16x16x32_bf16 v[108:111], v[138:141], v[162:165], v[108:111]
	v_mfma_f32_16x16x32_bf16 v[104:107], v[146:149], v[162:165], v[104:107]
	v_mfma_f32_16x16x32_bf16 v[92:95], v[138:141], v[170:173], v[92:95]
	v_mfma_f32_16x16x32_bf16 v[88:91], v[146:149], v[170:173], v[88:91]
	v_mfma_f32_16x16x32_bf16 v[76:79], v[138:141], v[178:181], v[76:79]
	v_mfma_f32_16x16x32_bf16 v[72:75], v[146:149], v[178:181], v[72:75]
	s_barrier
	s_add_i32 s22, 0, 0x1c000
	s_add_i32 s23, s46, s30
	v_add_u32_e32 v200, s22, v214
	v_lshl_add_u64 v[190:191], v[190:191], 0, s[74:75]
	s_mov_b32 m0, s23
	ds_read_b128 v[182:185], v200
	ds_read_b128 v[186:189], v200 offset:1024
	ds_read_b128 v[194:197], v200 offset:2048
	ds_read_b128 v[200:203], v200 offset:3072
	global_load_lds_dwordx4 v[190:191], off
	s_add_i32 m0, s23, 0x2000
	v_lshl_add_u64 v[190:191], v[204:205], 0, s[74:75]
	global_load_lds_dwordx4 v[190:191], off
	s_barrier
	s_waitcnt lgkmcnt(0)
	s_waitcnt lgkmcnt(0)
	v_mfma_f32_16x16x32_bf16 v[116:119], v[182:185], v[150:153], v[116:119]
	v_mfma_f32_16x16x32_bf16 v[112:115], v[194:197], v[150:153], v[112:115]
	v_mfma_f32_16x16x32_bf16 v[100:103], v[182:185], v[158:161], v[100:103]
	v_mfma_f32_16x16x32_bf16 v[96:99], v[194:197], v[158:161], v[96:99]
	v_mfma_f32_16x16x32_bf16 v[84:87], v[182:185], v[166:169], v[84:87]
	v_mfma_f32_16x16x32_bf16 v[80:83], v[194:197], v[166:169], v[80:83]
	v_mfma_f32_16x16x32_bf16 v[68:71], v[182:185], v[174:177], v[68:71]
	v_mfma_f32_16x16x32_bf16 v[64:67], v[194:197], v[174:177], v[64:67]
	v_mfma_f32_16x16x32_bf16 v[116:119], v[186:189], v[154:157], v[116:119]
	v_mfma_f32_16x16x32_bf16 v[112:115], v[200:203], v[154:157], v[112:115]
	v_mfma_f32_16x16x32_bf16 v[100:103], v[186:189], v[162:165], v[100:103]
	v_mfma_f32_16x16x32_bf16 v[96:99], v[200:203], v[162:165], v[96:99]
	v_mfma_f32_16x16x32_bf16 v[84:87], v[186:189], v[170:173], v[84:87]
	v_mfma_f32_16x16x32_bf16 v[80:83], v[200:203], v[170:173], v[80:83]
	v_mfma_f32_16x16x32_bf16 v[68:71], v[186:189], v[178:181], v[68:71]
	v_mfma_f32_16x16x32_bf16 v[64:67], v[200:203], v[178:181], v[64:67]
	s_mov_b32 m0, s38
	v_lshl_add_u64 v[190:191], v[206:207], 0, s[74:75]
	s_barrier
	ds_read_b128 v[150:153], v216 offset:49152
	ds_read_b128 v[154:157], v216 offset:50176
	ds_read_b128 v[158:161], v216 offset:51200
	ds_read_b128 v[162:165], v216 offset:52224
	ds_read_b128 v[166:169], v216 offset:53248
	ds_read_b128 v[170:173], v216 offset:54272
	ds_read_b128 v[174:177], v216 offset:55296
	ds_read_b128 v[178:181], v216 offset:56320
	global_load_lds_dwordx4 v[190:191], off
	s_mov_b32 m0, s39
	v_lshl_add_u64 v[190:191], v[208:209], 0, s[74:75]
	global_load_lds_dwordx4 v[190:191], off
	s_barrier
; #define PG8_STAGE(bufoff, gbase, voff) do { _Pragma("unroll") for (int _i = 0; _i < 2; ++_i) \
;         __builtin_amdgcn_global_load_lds((const unsigned*)((const char*)(gbase) + (voff)[_i]), (PG8_LAS unsigned*)(lds + (bufoff) + ldsw + _i * 8192), 16, 0, 0); } while (0)
; #define PG8_MMA(ai, bj, At, Bt) do { __builtin_amdgcn_s_setprio(1); _Pragma("unroll") for (int m = 0; m < 4; ++m) _Pragma("unroll") for (int n = 0; n < 2; ++n) _Pragma("unroll") for (int k = 0; k < 2; ++k) \
;         acc[ai][bj][m][n] = __builtin_amdgcn_mfma_f32_16x16x32_bf16(Bt[n][k], At[m][k], acc[ai][bj][m][n], 0, 0, 0); __builtin_amdgcn_s_setprio(0); } while (0)
; #define PG8_WAIT_V(n) asm volatile("s_waitcnt vmcnt(" #n ")" ::: "memory")
; #define PG8_WAIT_L(n) asm volatile("s_waitcnt lgkmcnt(" #n ")" ::: "memory")
; #define PG8_BAR __builtin_amdgcn_s_barrier()
; #define PG8_SCHED __builtin_amdgcn_sched_barrier(0)
; template <class Epi, class Sched>
; __device__ __forceinline__ void gemm_phase(PG8_LAS unsigned char* lds, const Gemm g, const Sched& S, const Epi& E, int tid_in) {
;     ...
;             PG8_BAR; PG8_WAIT_L(0); PG8_MMA(1, 0, At, B0); PG8_BAR; PG8_SCHED;
;             PG8_STAGE(PG8_SB(1, 1), b3 + hstep, voffB);
;             PG8_WAIT_V(6); PG8_BAR; PG8_MMA(1, 1, At, B1); PG8_BAR;
;         }
;     __device__ __forceinline__ void operator()(f32x4 (&acc)[2][2][4][2], const Unit& u, int wr, int wc, int fr, int fq) const {
;     ...
;                     for (int n = 0; n < 2; ++n) { const size_t row = row0 + ai * 128 + m * 16; const int col = col0 + bj * 128 + n * 16;
;                         gw[m][bj][n] = *(const u32x2*)(gates + row * 2048 + 1024 + col); tw[m][bj][n] = *(const u32x2*)(tmp + row * 1024 + col); }
	s_waitcnt lgkmcnt(0)
	s_waitcnt lgkmcnt(0)
	v_mfma_f32_16x16x32_bf16 v[60:63], v[134:137], v[150:153], v[60:63]
	v_mfma_f32_16x16x32_bf16 v[56:59], v[142:145], v[150:153], v[56:59]
	v_mfma_f32_16x16x32_bf16 v[44:47], v[134:137], v[158:161], v[44:47]
	v_mfma_f32_16x16x32_bf16 v[40:43], v[142:145], v[158:161], v[40:43]
	v_mfma_f32_16x16x32_bf16 v[28:31], v[134:137], v[166:169], v[28:31]
	v_mfma_f32_16x16x32_bf16 v[24:27], v[142:145], v[166:169], v[24:27]
	v_mfma_f32_16x16x32_bf16 v[12:15], v[134:137], v[174:177], v[12:15]
	v_mfma_f32_16x16x32_bf16 v[8:11], v[142:145], v[174:177], v[8:11]
	v_mfma_f32_16x16x32_bf16 v[60:63], v[138:141], v[154:157], v[60:63]
	v_mfma_f32_16x16x32_bf16 v[56:59], v[146:149], v[154:157], v[56:59]
	v_mfma_f32_16x16x32_bf16 v[44:47], v[138:141], v[162:165], v[44:47]
	v_mfma_f32_16x16x32_bf16 v[40:43], v[146:149], v[162:165], v[40:43]
	v_mfma_f32_16x16x32_bf16 v[28:31], v[138:141], v[170:173], v[28:31]
	v_mfma_f32_16x16x32_bf16 v[24:27], v[146:149], v[170:173], v[24:27]
	v_mfma_f32_16x16x32_bf16 v[12:15], v[138:141], v[178:181], v[12:15]
	v_mfma_f32_16x16x32_bf16 v[8:11], v[146:149], v[178:181], v[8:11]
	s_barrier
	s_add_u32 s20, s20, 0x40080
	s_addc_u32 s21, s21, 0
	s_add_i32 s22, s22, s30
	s_mov_b32 m0, s22
	v_lshl_add_u64 v[134:135], s[20:21], 0, v[192:193]
	global_load_lds_dwordx4 v[134:135], off
	s_add_i32 m0, s22, 0x2000
	v_lshl_add_u64 v[134:135], s[20:21], 0, v[128:129]
	global_load_lds_dwordx4 v[134:135], off
	s_waitcnt vmcnt(6)
	s_barrier
	v_mfma_f32_16x16x32_bf16 v[52:55], v[182:185], v[150:153], v[52:55]
	v_mfma_f32_16x16x32_bf16 v[48:51], v[194:197], v[150:153], v[48:51]
	v_mfma_f32_16x16x32_bf16 v[36:39], v[182:185], v[158:161], v[36:39]
	v_mfma_f32_16x16x32_bf16 v[32:35], v[194:197], v[158:161], v[32:35]
	v_mfma_f32_16x16x32_bf16 v[20:23], v[182:185], v[166:169], v[20:23]
	v_mfma_f32_16x16x32_bf16 v[16:19], v[194:197], v[166:169], v[16:19]
	v_mfma_f32_16x16x32_bf16 v[4:7], v[182:185], v[174:177], v[4:7]
	v_mfma_f32_16x16x32_bf16 v[0:3], v[194:197], v[174:177], v[0:3]
	v_mfma_f32_16x16x32_bf16 v[52:55], v[186:189], v[154:157], v[52:55]
	v_mfma_f32_16x16x32_bf16 v[48:51], v[200:203], v[154:157], v[48:51]
	v_mfma_f32_16x16x32_bf16 v[36:39], v[186:189], v[162:165], v[36:39]
	v_mfma_f32_16x16x32_bf16 v[32:35], v[200:203], v[162:165], v[32:35]
	v_mfma_f32_16x16x32_bf16 v[20:23], v[186:189], v[170:173], v[20:23]
	v_mfma_f32_16x16x32_bf16 v[16:19], v[200:203], v[170:173], v[16:19]
	v_mfma_f32_16x16x32_bf16 v[4:7], v[186:189], v[178:181], v[4:7]
	v_mfma_f32_16x16x32_bf16 v[0:3], v[200:203], v[178:181], v[0:3]
	s_add_i32 s45, s45, 2
	s_add_u32 s18, s18, 0x100
	s_addc_u32 s19, s19, 0
	s_add_u32 s43, s43, 0x100
	s_addc_u32 s44, s44, 0
	s_cmp_gt_u32 s45, 13
	s_barrier
	s_cbranch_scc0 .LBB0_370
	v_lshl_add_u32 v136, s16, 8, v199
	v_lshl_or_b32 v134, s33, 8, v215
	v_ashrrev_i32_e32 v137, 31, v136
	v_lshlrev_b64 v[138:139], 12, v[136:137]
	v_ashrrev_i32_e32 v135, 31, v134
	v_lshl_add_u64 v[138:139], s[0:1], 0, v[138:139]
	v_lshlrev_b64 v[134:135], 1, v[134:135]
	v_lshl_add_u64 v[138:139], v[138:139], 0, v[134:135]
	global_load_dwordx2 v[194:195], v[138:139], off offset:2048
	v_lshlrev_b64 v[212:213], 11, v[136:137]
	v_lshl_add_u64 v[140:141], s[4:5], 0, v[212:213]
	v_lshl_add_u64 v[140:141], v[140:141], 0, v[134:135]
	global_load_dwordx2 v[196:197], v[140:141], off
	global_load_dwordx2 v[210:211], v[138:139], off offset:2080
	global_load_dwordx2 v[208:209], v[140:141], off offset:32
	global_load_dwordx2 v[206:207], v[138:139], off offset:2304
	global_load_dwordx2 v[204:205], v[140:141], off offset:256
	global_load_dwordx2 v[202:203], v[138:139], off offset:2336
	global_load_dwordx2 v[200:201], v[140:141], off offset:288
	v_or_b32_e32 v138, 16, v136
	v_ashrrev_i32_e32 v139, 31, v138
	v_lshlrev_b64 v[140:141], 12, v[138:139]
	v_lshl_add_u64 v[140:141], s[0:1], 0, v[140:141]
	v_lshl_add_u64 v[140:141], v[140:141], 0, v[134:135]
	global_load_dwordx2 v[190:191], v[140:141], off offset:2048
	v_lshlrev_b64 v[184:185], 11, v[138:139]
	v_lshl_add_u64 v[138:139], s[4:5], 0, v[184:185]
	v_lshl_add_u64 v[138:139], v[138:139], 0, v[134:135]
	global_load_dwordx2 v[188:189], v[138:139], off
	global_load_dwordx2 v[186:187], v[140:141], off offset:2080
	global_load_dwordx2 v[182:183], v[138:139], off offset:32
	global_load_dwordx2 v[172:173], v[140:141], off offset:2304
	global_load_dwordx2 v[170:171], v[138:139], off offset:256
	global_load_dwordx2 v[156:157], v[140:141], off offset:2336
	global_load_dwordx2 v[154:155], v[138:139], off offset:288
	v_or_b32_e32 v138, 32, v136
	v_ashrrev_i32_e32 v139, 31, v138
	v_lshlrev_b64 v[140:141], 12, v[138:139]
	v_lshl_add_u64 v[140:141], s[0:1], 0, v[140:141]
	v_lshl_add_u64 v[140:141], v[140:141], 0, v[134:135]
	global_load_dwordx2 v[180:181], v[140:141], off offset:2048
	v_lshlrev_b64 v[166:167], 11, v[138:139]
	v_lshl_add_u64 v[138:139], s[4:5], 0, v[166:167]
	v_lshl_add_u64 v[138:139], v[138:139], 0, v[134:135]
	global_load_dwordx2 v[176:177], v[138:139], off
	global_load_dwordx2 v[168:169], v[140:141], off offset:2080
	global_load_dwordx2 v[160:161], v[138:139], off offset:32
	global_load_dwordx2 v[152:153], v[140:141], off offset:2304
	global_load_dwordx2 v[148:149], v[138:139], off offset:256
	global_load_dwordx2 v[144:145], v[140:141], off offset:2336
	s_nop 0
	global_load_dwordx2 v[140:141], v[138:139], off offset:288
	v_or_b32_e32 v138, 48, v136
	v_ashrrev_i32_e32 v139, 31, v138
	v_lshlrev_b64 v[142:143], 12, v[138:139]
	v_lshl_add_u64 v[142:143], s[0:1], 0, v[142:143]
	v_lshl_add_u64 v[142:143], v[142:143], 0, v[134:135]
	global_load_dwordx2 v[178:179], v[142:143], off offset:2048
	v_lshlrev_b64 v[162:163], 11, v[138:139]
	v_lshl_add_u64 v[138:139], s[4:5], 0, v[162:163]
	v_lshl_add_u64 v[138:139], v[138:139], 0, v[134:135]
	global_load_dwordx2 v[174:175], v[138:139], off
	global_load_dwordx2 v[164:165], v[142:143], off offset:2080
	global_load_dwordx2 v[158:159], v[138:139], off offset:32
	global_load_dwordx2 v[150:151], v[142:143], off offset:2304
	global_load_dwordx2 v[146:147], v[138:139], off offset:256
	s_nop 0
	global_load_dwordx2 v[142:143], v[142:143], off offset:2336
	s_nop 0
	global_load_dwordx2 v[138:139], v[138:139], off offset:288
	s_and_b64 vcc, exec, s[2:3]
	s_mov_b32 s33, s8
	s_mov_b32 s16, s10
	s_mov_b64 s[20:21], s[14:15]
	s_mov_b64 s[18:19], s[12:13]
	s_waitcnt vmcnt(0)
; __device__ __forceinline__ unsigned cvt_pk_bf16(float lo, float hi) { unsigned r; asm volatile("s_nop 0\n\tv_cvt_pk_bf16_f32 %0, %1, %2\n\ts_nop 1" : "=v"(r) : "v"(lo), "v"(hi)); return r; }
; __device__ __forceinline__ float bflo(unsigned w) { return __uint_as_float(w << 16); }
; __device__ __forceinline__ float bfhi(unsigned w) { return __uint_as_float(w & 0xffff0000u); }
;     __device__ __forceinline__ void operator()(f32x4 (&acc)[2][2][4][2], const Unit& u, int wr, int wc, int fr, int fq) const {
;     ...
;             for (int m = 0; m < 4; ++m) { const size_t row = row0 + ai * 128 + m * 16;
; #pragma unroll
;                 for (int bj = 0; bj < 2; ++bj)
; #pragma unroll
;                     for (int n = 0; n < 2; ++n) { const int col = col0 + bj * 128 + n * 16; const u32x2 g2 = gw[m][bj][n], t2 = tw[m][bj][n];
;                         const f32x4 gv = (f32x4){bflo(g2.x), bfhi(g2.x), bflo(g2.y), bfhi(g2.y)};
;                         const f32x4 o = (f32x4){bflo(t2.x), bfhi(t2.x), bflo(t2.y), bfhi(t2.y)} + gv * acc[ai][bj][m][n];
;                         u32x2 w; w.x = cvt_pk_bf16(o[0], o[1]); w.y = cvt_pk_bf16(o[2], o[3]); *(u32x2*)(merged + row * 1024 + col) = w; } }
	v_lshlrev_b32_e32 v220, 16, v196
	v_and_b32_e32 v221, 0xffff0000, v196
	v_lshlrev_b32_e32 v218, 16, v194
	v_and_b32_e32 v219, 0xffff0000, v194
	v_lshlrev_b32_e32 v194, 16, v195
	v_and_b32_e32 v195, 0xffff0000, v195
	v_lshlrev_b32_e32 v196, 16, v197
	v_and_b32_e32 v197, 0xffff0000, v197
	v_pk_fma_f32 v[124:125], v[124:125], v[218:219], v[220:221]
	v_pk_fma_f32 v[126:127], v[126:127], v[194:195], v[196:197]
	v_cvt_pk_bf16_f32 v194, v124, v125
	v_lshl_add_u64 v[124:125], s[6:7], 0, v[212:213]
	v_cvt_pk_bf16_f32 v195, v126, v127
	v_lshl_add_u64 v[124:125], v[124:125], 0, v[134:135]
	v_lshlrev_b32_e32 v126, 16, v210
	v_and_b32_e32 v127, 0xffff0000, v210
	v_lshlrev_b32_e32 v196, 16, v208
	v_and_b32_e32 v197, 0xffff0000, v208
	global_store_dwordx2 v[124:125], v[194:195], off
	v_lshlrev_b32_e32 v194, 16, v211
	v_and_b32_e32 v195, 0xffff0000, v211
	v_lshlrev_b32_e32 v208, 16, v209
	v_and_b32_e32 v209, 0xffff0000, v209
	v_pk_fma_f32 v[120:121], v[120:121], v[126:127], v[196:197]
	v_pk_fma_f32 v[122:123], v[122:123], v[194:195], v[208:209]
	v_cvt_pk_bf16_f32 v120, v120, v121
	v_lshlrev_b32_e32 v126, 16, v204
	v_cvt_pk_bf16_f32 v121, v122, v123
	global_store_dwordx2 v[124:125], v[120:121], off offset:32
	v_lshlrev_b32_e32 v120, 16, v206
	v_and_b32_e32 v121, 0xffff0000, v206
	v_and_b32_e32 v127, 0xffff0000, v204
	v_lshlrev_b32_e32 v122, 16, v207
	v_and_b32_e32 v123, 0xffff0000, v207
	v_lshlrev_b32_e32 v194, 16, v205
	v_and_b32_e32 v195, 0xffff0000, v205
	v_pk_fma_f32 v[116:117], v[116:117], v[120:121], v[126:127]
	v_pk_fma_f32 v[118:119], v[118:119], v[122:123], v[194:195]
	v_cvt_pk_bf16_f32 v116, v116, v117
	v_lshlrev_b32_e32 v120, 16, v200
	v_cvt_pk_bf16_f32 v117, v118, v119
	global_store_dwordx2 v[124:125], v[116:117], off offset:256
	v_lshlrev_b32_e32 v116, 16, v202
	v_and_b32_e32 v117, 0xffff0000, v202
	v_and_b32_e32 v121, 0xffff0000, v200
	v_lshlrev_b32_e32 v118, 16, v203
	v_and_b32_e32 v119, 0xffff0000, v203
	v_lshlrev_b32_e32 v122, 16, v201
	v_and_b32_e32 v123, 0xffff0000, v201
	v_pk_fma_f32 v[112:113], v[112:113], v[116:117], v[120:121]
	v_pk_fma_f32 v[114:115], v[114:115], v[118:119], v[122:123]
	v_cvt_pk_bf16_f32 v112, v112, v113
	v_lshlrev_b32_e32 v116, 16, v188
	v_cvt_pk_bf16_f32 v113, v114, v115
	global_store_dwordx2 v[124:125], v[112:113], off offset:288
	v_lshlrev_b32_e32 v112, 16, v190
	v_and_b32_e32 v113, 0xffff0000, v190
	v_lshlrev_b32_e32 v114, 16, v191
	v_and_b32_e32 v115, 0xffff0000, v191
	v_and_b32_e32 v117, 0xffff0000, v188
	v_lshlrev_b32_e32 v118, 16, v189
	v_and_b32_e32 v119, 0xffff0000, v189
	v_pk_fma_f32 v[110:111], v[110:111], v[114:115], v[118:119]
	v_pk_fma_f32 v[108:109], v[108:109], v[112:113], v[116:117]
	v_lshlrev_b32_e32 v114, 16, v182
	v_cvt_pk_bf16_f32 v108, v108, v109
	v_cvt_pk_bf16_f32 v109, v110, v111
	v_lshl_add_u64 v[110:111], s[6:7], 0, v[184:185]
	v_lshl_add_u64 v[110:111], v[110:111], 0, v[134:135]
	global_store_dwordx2 v[110:111], v[108:109], off
	v_lshlrev_b32_e32 v108, 16, v186
	v_and_b32_e32 v109, 0xffff0000, v186
	v_and_b32_e32 v115, 0xffff0000, v182
	v_lshlrev_b32_e32 v112, 16, v187
	v_and_b32_e32 v113, 0xffff0000, v187
	v_lshlrev_b32_e32 v116, 16, v183
	v_and_b32_e32 v117, 0xffff0000, v183
	v_pk_fma_f32 v[104:105], v[104:105], v[108:109], v[114:115]
	v_pk_fma_f32 v[106:107], v[106:107], v[112:113], v[116:117]
	v_cvt_pk_bf16_f32 v104, v104, v105
	v_lshlrev_b32_e32 v108, 16, v170
	v_cvt_pk_bf16_f32 v105, v106, v107
	global_store_dwordx2 v[110:111], v[104:105], off offset:32
	v_lshlrev_b32_e32 v104, 16, v172
	v_and_b32_e32 v105, 0xffff0000, v172
	v_and_b32_e32 v109, 0xffff0000, v170
	v_lshlrev_b32_e32 v106, 16, v173
	v_and_b32_e32 v107, 0xffff0000, v173
	v_lshlrev_b32_e32 v112, 16, v171
	v_and_b32_e32 v113, 0xffff0000, v171
	v_pk_fma_f32 v[100:101], v[100:101], v[104:105], v[108:109]
	v_pk_fma_f32 v[102:103], v[102:103], v[106:107], v[112:113]
	v_cvt_pk_bf16_f32 v100, v100, v101
	v_lshlrev_b32_e32 v104, 16, v154
	v_cvt_pk_bf16_f32 v101, v102, v103
	global_store_dwordx2 v[110:111], v[100:101], off offset:256
	v_lshlrev_b32_e32 v100, 16, v156
	v_and_b32_e32 v101, 0xffff0000, v156
	v_and_b32_e32 v105, 0xffff0000, v154
	v_lshlrev_b32_e32 v102, 16, v157
	v_and_b32_e32 v103, 0xffff0000, v157
	v_lshlrev_b32_e32 v106, 16, v155
	v_and_b32_e32 v107, 0xffff0000, v155
	v_pk_fma_f32 v[96:97], v[96:97], v[100:101], v[104:105]
	v_pk_fma_f32 v[98:99], v[98:99], v[102:103], v[106:107]
	v_cvt_pk_bf16_f32 v96, v96, v97
	v_lshlrev_b32_e32 v100, 16, v176
	v_cvt_pk_bf16_f32 v97, v98, v99
	global_store_dwordx2 v[110:111], v[96:97], off offset:288
	v_lshlrev_b32_e32 v96, 16, v180
	v_and_b32_e32 v97, 0xffff0000, v180
	v_lshlrev_b32_e32 v98, 16, v181
	v_and_b32_e32 v99, 0xffff0000, v181
	v_and_b32_e32 v101, 0xffff0000, v176
	v_lshlrev_b32_e32 v102, 16, v177
	v_and_b32_e32 v103, 0xffff0000, v177
	v_pk_fma_f32 v[94:95], v[94:95], v[98:99], v[102:103]
	v_pk_fma_f32 v[92:93], v[92:93], v[96:97], v[100:101]
	v_lshlrev_b32_e32 v98, 16, v160
	v_cvt_pk_bf16_f32 v92, v92, v93
	v_cvt_pk_bf16_f32 v93, v94, v95
	v_lshl_add_u64 v[94:95], s[6:7], 0, v[166:167]
	v_lshl_add_u64 v[94:95], v[94:95], 0, v[134:135]
	global_store_dwordx2 v[94:95], v[92:93], off
	v_lshlrev_b32_e32 v92, 16, v168
	v_and_b32_e32 v93, 0xffff0000, v168
	v_and_b32_e32 v99, 0xffff0000, v160
	v_lshlrev_b32_e32 v96, 16, v169
	v_and_b32_e32 v97, 0xffff0000, v169
	v_lshlrev_b32_e32 v100, 16, v161
	v_and_b32_e32 v101, 0xffff0000, v161
	v_pk_fma_f32 v[88:89], v[88:89], v[92:93], v[98:99]
	v_pk_fma_f32 v[90:91], v[90:91], v[96:97], v[100:101]
	v_cvt_pk_bf16_f32 v88, v88, v89
	v_lshlrev_b32_e32 v92, 16, v148
	v_cvt_pk_bf16_f32 v89, v90, v91
	global_store_dwordx2 v[94:95], v[88:89], off offset:32
; __device__ __forceinline__ unsigned cvt_pk_bf16(float lo, float hi) { unsigned r; asm volatile("s_nop 0\n\tv_cvt_pk_bf16_f32 %0, %1, %2\n\ts_nop 1" : "=v"(r) : "v"(lo), "v"(hi)); return r; }
; __device__ __forceinline__ float bflo(unsigned w) { return __uint_as_float(w << 16); }
; __device__ __forceinline__ float bfhi(unsigned w) { return __uint_as_float(w & 0xffff0000u); }
;     __device__ __forceinline__ void operator()(f32x4 (&acc)[2][2][4][2], const Unit& u, int wr, int wc, int fr, int fq) const {
;     ...
;             u32x2 gw[4][2][2], tw[4][2][2];
; #pragma unroll
;             for (int m = 0; m < 4; ++m)
; #pragma unroll
;                 for (int bj = 0; bj < 2; ++bj)
; #pragma unroll
;                     for (int n = 0; n < 2; ++n) { const size_t row = row0 + ai * 128 + m * 16; const int col = col0 + bj * 128 + n * 16;
;                         gw[m][bj][n] = *(const u32x2*)(gates + row * 2048 + 1024 + col); tw[m][bj][n] = *(const u32x2*)(tmp + row * 1024 + col); }
;     ...
;             for (int m = 0; m < 4; ++m) { const size_t row = row0 + ai * 128 + m * 16;
; #pragma unroll
;                 for (int bj = 0; bj < 2; ++bj)
; #pragma unroll
;                     for (int n = 0; n < 2; ++n) { const int col = col0 + bj * 128 + n * 16; const u32x2 g2 = gw[m][bj][n], t2 = tw[m][bj][n];
;                         const f32x4 gv = (f32x4){bflo(g2.x), bfhi(g2.x), bflo(g2.y), bfhi(g2.y)};
;                         const f32x4 o = (f32x4){bflo(t2.x), bfhi(t2.x), bflo(t2.y), bfhi(t2.y)} + gv * acc[ai][bj][m][n];
;                         u32x2 w; w.x = cvt_pk_bf16(o[0], o[1]); w.y = cvt_pk_bf16(o[2], o[3]); *(u32x2*)(merged + row * 1024 + col) = w; } }
	v_lshlrev_b32_e32 v88, 16, v152
	v_and_b32_e32 v89, 0xffff0000, v152
	v_and_b32_e32 v93, 0xffff0000, v148
	v_lshlrev_b32_e32 v90, 16, v153
	v_and_b32_e32 v91, 0xffff0000, v153
	v_lshlrev_b32_e32 v96, 16, v149
	v_and_b32_e32 v97, 0xffff0000, v149
	v_pk_fma_f32 v[84:85], v[84:85], v[88:89], v[92:93]
	v_pk_fma_f32 v[86:87], v[86:87], v[90:91], v[96:97]
	v_cvt_pk_bf16_f32 v84, v84, v85
	v_lshlrev_b32_e32 v88, 16, v140
	v_cvt_pk_bf16_f32 v85, v86, v87
	global_store_dwordx2 v[94:95], v[84:85], off offset:256
	v_lshlrev_b32_e32 v84, 16, v144
	v_and_b32_e32 v85, 0xffff0000, v144
	v_and_b32_e32 v89, 0xffff0000, v140
	v_lshlrev_b32_e32 v86, 16, v145
	v_and_b32_e32 v87, 0xffff0000, v145
	v_lshlrev_b32_e32 v90, 16, v141
	v_and_b32_e32 v91, 0xffff0000, v141
	v_pk_fma_f32 v[80:81], v[80:81], v[84:85], v[88:89]
	v_pk_fma_f32 v[82:83], v[82:83], v[86:87], v[90:91]
	v_cvt_pk_bf16_f32 v80, v80, v81
	v_lshlrev_b32_e32 v84, 16, v174
	v_cvt_pk_bf16_f32 v81, v82, v83
	global_store_dwordx2 v[94:95], v[80:81], off offset:288
	v_lshlrev_b32_e32 v80, 16, v178
	v_and_b32_e32 v81, 0xffff0000, v178
	v_lshlrev_b32_e32 v82, 16, v179
	v_and_b32_e32 v83, 0xffff0000, v179
	v_and_b32_e32 v85, 0xffff0000, v174
	v_lshlrev_b32_e32 v86, 16, v175
	v_and_b32_e32 v87, 0xffff0000, v175
	v_pk_fma_f32 v[78:79], v[78:79], v[82:83], v[86:87]
	v_pk_fma_f32 v[76:77], v[76:77], v[80:81], v[84:85]
	v_lshlrev_b32_e32 v82, 16, v158
	v_cvt_pk_bf16_f32 v76, v76, v77
	v_cvt_pk_bf16_f32 v77, v78, v79
	v_lshl_add_u64 v[78:79], s[6:7], 0, v[162:163]
	v_lshl_add_u64 v[78:79], v[78:79], 0, v[134:135]
	global_store_dwordx2 v[78:79], v[76:77], off
	v_lshlrev_b32_e32 v76, 16, v164
	v_and_b32_e32 v77, 0xffff0000, v164
	v_and_b32_e32 v83, 0xffff0000, v158
	v_lshlrev_b32_e32 v80, 16, v165
	v_and_b32_e32 v81, 0xffff0000, v165
	v_lshlrev_b32_e32 v84, 16, v159
	v_and_b32_e32 v85, 0xffff0000, v159
	v_pk_fma_f32 v[72:73], v[72:73], v[76:77], v[82:83]
	v_pk_fma_f32 v[74:75], v[74:75], v[80:81], v[84:85]
	v_cvt_pk_bf16_f32 v72, v72, v73
	v_lshlrev_b32_e32 v76, 16, v146
	v_cvt_pk_bf16_f32 v73, v74, v75
	global_store_dwordx2 v[78:79], v[72:73], off offset:32
	v_lshlrev_b32_e32 v72, 16, v150
	v_and_b32_e32 v73, 0xffff0000, v150
	v_and_b32_e32 v77, 0xffff0000, v146
	v_lshlrev_b32_e32 v74, 16, v151
	v_and_b32_e32 v75, 0xffff0000, v151
	v_lshlrev_b32_e32 v80, 16, v147
	v_and_b32_e32 v81, 0xffff0000, v147
	v_pk_fma_f32 v[68:69], v[68:69], v[72:73], v[76:77]
	v_pk_fma_f32 v[70:71], v[70:71], v[74:75], v[80:81]
	v_cvt_pk_bf16_f32 v68, v68, v69
	v_lshlrev_b32_e32 v72, 16, v138
	v_cvt_pk_bf16_f32 v69, v70, v71
	global_store_dwordx2 v[78:79], v[68:69], off offset:256
	v_lshlrev_b32_e32 v68, 16, v142
	v_and_b32_e32 v69, 0xffff0000, v142
	v_and_b32_e32 v73, 0xffff0000, v138
	v_pk_fma_f32 v[64:65], v[64:65], v[68:69], v[72:73]
	v_lshlrev_b32_e32 v70, 16, v143
	v_and_b32_e32 v71, 0xffff0000, v143
	v_lshlrev_b32_e32 v74, 16, v139
	v_and_b32_e32 v75, 0xffff0000, v139
	v_cvt_pk_bf16_f32 v64, v64, v65
	v_pk_fma_f32 v[66:67], v[66:67], v[70:71], v[74:75]
	s_nop 0
	v_cvt_pk_bf16_f32 v65, v66, v67
	global_store_dwordx2 v[78:79], v[64:65], off offset:288
	v_add_u32_e32 v64, 0x80, v136
	v_ashrrev_i32_e32 v65, 31, v64
	v_lshlrev_b64 v[66:67], 12, v[64:65]
	v_lshl_add_u64 v[66:67], s[0:1], 0, v[66:67]
	v_lshl_add_u64 v[66:67], v[66:67], 0, v[134:135]
	global_load_dwordx2 v[116:117], v[66:67], off offset:2048
	v_lshlrev_b64 v[114:115], 11, v[64:65]
	v_lshl_add_u64 v[64:65], s[4:5], 0, v[114:115]
	v_lshl_add_u64 v[64:65], v[64:65], 0, v[134:135]
	global_load_dwordx2 v[118:119], v[64:65], off
	global_load_dwordx2 v[120:121], v[66:67], off offset:2080
	global_load_dwordx2 v[122:123], v[64:65], off offset:32
	global_load_dwordx2 v[124:125], v[66:67], off offset:2304
	global_load_dwordx2 v[126:127], v[64:65], off offset:256
	global_load_dwordx2 v[138:139], v[66:67], off offset:2336
	global_load_dwordx2 v[140:141], v[64:65], off offset:288
	v_add_u32_e32 v64, 0x90, v136
	v_ashrrev_i32_e32 v65, 31, v64
	v_lshlrev_b64 v[66:67], 12, v[64:65]
	v_lshl_add_u64 v[66:67], s[0:1], 0, v[66:67]
	v_lshl_add_u64 v[66:67], v[66:67], 0, v[134:135]
	global_load_dwordx2 v[142:143], v[66:67], off offset:2048
	v_lshlrev_b64 v[108:109], 11, v[64:65]
	v_lshl_add_u64 v[64:65], s[4:5], 0, v[108:109]
	v_lshl_add_u64 v[64:65], v[64:65], 0, v[134:135]
	global_load_dwordx2 v[144:145], v[64:65], off
	global_load_dwordx2 v[112:113], v[66:67], off offset:2080
	global_load_dwordx2 v[110:111], v[64:65], off offset:32
	global_load_dwordx2 v[106:107], v[66:67], off offset:2304
	global_load_dwordx2 v[104:105], v[64:65], off offset:256
	global_load_dwordx2 v[100:101], v[66:67], off offset:2336
	global_load_dwordx2 v[102:103], v[64:65], off offset:288
	v_add_u32_e32 v64, 0xa0, v136
	v_ashrrev_i32_e32 v65, 31, v64
	v_lshlrev_b64 v[66:67], 12, v[64:65]
	v_lshl_add_u64 v[66:67], s[0:1], 0, v[66:67]
	v_lshl_add_u64 v[66:67], v[66:67], 0, v[134:135]
	global_load_dwordx2 v[96:97], v[66:67], off offset:2048
	v_lshlrev_b64 v[90:91], 11, v[64:65]
	v_lshl_add_u64 v[64:65], s[4:5], 0, v[90:91]
	v_lshl_add_u64 v[64:65], v[64:65], 0, v[134:135]
	global_load_dwordx2 v[98:99], v[64:65], off
	global_load_dwordx2 v[94:95], v[66:67], off offset:2080
	global_load_dwordx2 v[92:93], v[64:65], off offset:32
	global_load_dwordx2 v[88:89], v[66:67], off offset:2304
	global_load_dwordx2 v[86:87], v[64:65], off offset:256
	global_load_dwordx2 v[82:83], v[66:67], off offset:2336
	global_load_dwordx2 v[84:85], v[64:65], off offset:288
	v_add_u32_e32 v64, 0xb0, v136
	v_ashrrev_i32_e32 v65, 31, v64
	v_lshlrev_b64 v[66:67], 12, v[64:65]
	v_lshl_add_u64 v[66:67], s[0:1], 0, v[66:67]
	v_lshl_add_u64 v[66:67], v[66:67], 0, v[134:135]
	global_load_dwordx2 v[78:79], v[66:67], off offset:2048
	v_lshlrev_b64 v[72:73], 11, v[64:65]
	v_lshl_add_u64 v[64:65], s[4:5], 0, v[72:73]
	v_lshl_add_u64 v[136:137], v[64:65], 0, v[134:135]
	global_load_dwordx2 v[80:81], v[136:137], off
	global_load_dwordx2 v[76:77], v[66:67], off offset:2080
	global_load_dwordx2 v[74:75], v[136:137], off offset:32
	global_load_dwordx2 v[70:71], v[66:67], off offset:2304
	global_load_dwordx2 v[68:69], v[136:137], off offset:256
	global_load_dwordx2 v[64:65], v[66:67], off offset:2336
	s_nop 0
	global_load_dwordx2 v[66:67], v[136:137], off offset:288
	s_waitcnt vmcnt(0)
; __device__ __forceinline__ unsigned cvt_pk_bf16(float lo, float hi) { unsigned r; asm volatile("s_nop 0\n\tv_cvt_pk_bf16_f32 %0, %1, %2\n\ts_nop 1" : "=v"(r) : "v"(lo), "v"(hi)); return r; }
; __device__ __forceinline__ float bflo(unsigned w) { return __uint_as_float(w << 16); }
; __device__ __forceinline__ float bfhi(unsigned w) { return __uint_as_float(w & 0xffff0000u); }
;     __device__ __forceinline__ void operator()(f32x4 (&acc)[2][2][4][2], const Unit& u, int wr, int wc, int fr, int fq) const {
;     ...
;             for (int m = 0; m < 4; ++m) { const size_t row = row0 + ai * 128 + m * 16;
; #pragma unroll
;                 for (int bj = 0; bj < 2; ++bj)
; #pragma unroll
;                     for (int n = 0; n < 2; ++n) { const int col = col0 + bj * 128 + n * 16; const u32x2 g2 = gw[m][bj][n], t2 = tw[m][bj][n];
;                         const f32x4 gv = (f32x4){bflo(g2.x), bfhi(g2.x), bflo(g2.y), bfhi(g2.y)};
;                         const f32x4 o = (f32x4){bflo(t2.x), bfhi(t2.x), bflo(t2.y), bfhi(t2.y)} + gv * acc[ai][bj][m][n];
;                         u32x2 w; w.x = cvt_pk_bf16(o[0], o[1]); w.y = cvt_pk_bf16(o[2], o[3]); *(u32x2*)(merged + row * 1024 + col) = w; } }
	v_lshlrev_b32_e32 v146, 16, v118
	v_and_b32_e32 v147, 0xffff0000, v118
	v_lshlrev_b32_e32 v136, 16, v116
	v_and_b32_e32 v137, 0xffff0000, v116
	v_lshlrev_b32_e32 v116, 16, v117
	v_and_b32_e32 v117, 0xffff0000, v117
	v_lshlrev_b32_e32 v118, 16, v119
	v_and_b32_e32 v119, 0xffff0000, v119
	v_pk_fma_f32 v[62:63], v[62:63], v[116:117], v[118:119]
	v_pk_fma_f32 v[60:61], v[60:61], v[136:137], v[146:147]
	v_lshlrev_b32_e32 v116, 16, v122
	v_cvt_pk_bf16_f32 v60, v60, v61
	v_cvt_pk_bf16_f32 v61, v62, v63
	v_lshl_add_u64 v[62:63], s[6:7], 0, v[114:115]
	v_lshl_add_u64 v[62:63], v[62:63], 0, v[134:135]
	global_store_dwordx2 v[62:63], v[60:61], off
	v_lshlrev_b32_e32 v60, 16, v120
	v_and_b32_e32 v61, 0xffff0000, v120
	v_and_b32_e32 v117, 0xffff0000, v122
	v_lshlrev_b32_e32 v114, 16, v121
	v_and_b32_e32 v115, 0xffff0000, v121
	v_lshlrev_b32_e32 v118, 16, v123
	v_and_b32_e32 v119, 0xffff0000, v123
	v_pk_fma_f32 v[56:57], v[56:57], v[60:61], v[116:117]
	v_pk_fma_f32 v[58:59], v[58:59], v[114:115], v[118:119]
	v_cvt_pk_bf16_f32 v56, v56, v57
	v_lshlrev_b32_e32 v60, 16, v126
	v_cvt_pk_bf16_f32 v57, v58, v59
	global_store_dwordx2 v[62:63], v[56:57], off offset:32
	v_lshlrev_b32_e32 v56, 16, v124
	v_and_b32_e32 v57, 0xffff0000, v124
	v_and_b32_e32 v61, 0xffff0000, v126
	v_lshlrev_b32_e32 v58, 16, v125
	v_and_b32_e32 v59, 0xffff0000, v125
	v_lshlrev_b32_e32 v114, 16, v127
	v_and_b32_e32 v115, 0xffff0000, v127
	v_pk_fma_f32 v[52:53], v[52:53], v[56:57], v[60:61]
	v_pk_fma_f32 v[54:55], v[54:55], v[58:59], v[114:115]
	v_cvt_pk_bf16_f32 v52, v52, v53
	v_lshlrev_b32_e32 v56, 16, v140
	v_cvt_pk_bf16_f32 v53, v54, v55
	global_store_dwordx2 v[62:63], v[52:53], off offset:256
	v_lshlrev_b32_e32 v52, 16, v138
	v_and_b32_e32 v53, 0xffff0000, v138
	v_and_b32_e32 v57, 0xffff0000, v140
	v_lshlrev_b32_e32 v54, 16, v139
	v_and_b32_e32 v55, 0xffff0000, v139
	v_lshlrev_b32_e32 v58, 16, v141
	v_and_b32_e32 v59, 0xffff0000, v141
	v_pk_fma_f32 v[48:49], v[48:49], v[52:53], v[56:57]
	v_pk_fma_f32 v[50:51], v[50:51], v[54:55], v[58:59]
	v_cvt_pk_bf16_f32 v48, v48, v49
	v_lshlrev_b32_e32 v52, 16, v144
	v_cvt_pk_bf16_f32 v49, v50, v51
	global_store_dwordx2 v[62:63], v[48:49], off offset:288
	v_lshlrev_b32_e32 v48, 16, v142
	v_and_b32_e32 v49, 0xffff0000, v142
	v_lshlrev_b32_e32 v50, 16, v143
	v_and_b32_e32 v51, 0xffff0000, v143
	v_and_b32_e32 v53, 0xffff0000, v144
	v_lshlrev_b32_e32 v54, 16, v145
	v_and_b32_e32 v55, 0xffff0000, v145
	v_pk_fma_f32 v[46:47], v[46:47], v[50:51], v[54:55]
	v_pk_fma_f32 v[44:45], v[44:45], v[48:49], v[52:53]
	v_lshlrev_b32_e32 v50, 16, v110
	v_cvt_pk_bf16_f32 v44, v44, v45
	v_cvt_pk_bf16_f32 v45, v46, v47
	v_lshl_add_u64 v[46:47], s[6:7], 0, v[108:109]
	v_lshl_add_u64 v[46:47], v[46:47], 0, v[134:135]
	global_store_dwordx2 v[46:47], v[44:45], off
	v_lshlrev_b32_e32 v44, 16, v112
	v_and_b32_e32 v45, 0xffff0000, v112
	v_and_b32_e32 v51, 0xffff0000, v110
	v_lshlrev_b32_e32 v48, 16, v113
	v_and_b32_e32 v49, 0xffff0000, v113
	v_lshlrev_b32_e32 v52, 16, v111
	v_and_b32_e32 v53, 0xffff0000, v111
	v_pk_fma_f32 v[40:41], v[40:41], v[44:45], v[50:51]
	v_pk_fma_f32 v[42:43], v[42:43], v[48:49], v[52:53]
	v_cvt_pk_bf16_f32 v40, v40, v41
	v_lshlrev_b32_e32 v44, 16, v104
	v_cvt_pk_bf16_f32 v41, v42, v43
	global_store_dwordx2 v[46:47], v[40:41], off offset:32
	v_lshlrev_b32_e32 v40, 16, v106
	v_and_b32_e32 v41, 0xffff0000, v106
	v_and_b32_e32 v45, 0xffff0000, v104
	v_lshlrev_b32_e32 v42, 16, v107
	v_and_b32_e32 v43, 0xffff0000, v107
	v_lshlrev_b32_e32 v48, 16, v105
	v_and_b32_e32 v49, 0xffff0000, v105
	v_pk_fma_f32 v[36:37], v[36:37], v[40:41], v[44:45]
	v_pk_fma_f32 v[38:39], v[38:39], v[42:43], v[48:49]
	v_cvt_pk_bf16_f32 v36, v36, v37
	v_lshlrev_b32_e32 v40, 16, v102
	v_cvt_pk_bf16_f32 v37, v38, v39
	global_store_dwordx2 v[46:47], v[36:37], off offset:256
	v_lshlrev_b32_e32 v36, 16, v100
	v_and_b32_e32 v37, 0xffff0000, v100
	v_and_b32_e32 v41, 0xffff0000, v102
	v_lshlrev_b32_e32 v38, 16, v101
	v_and_b32_e32 v39, 0xffff0000, v101
	v_lshlrev_b32_e32 v42, 16, v103
	v_and_b32_e32 v43, 0xffff0000, v103
	v_pk_fma_f32 v[32:33], v[32:33], v[36:37], v[40:41]
	v_pk_fma_f32 v[34:35], v[34:35], v[38:39], v[42:43]
	v_cvt_pk_bf16_f32 v32, v32, v33
	v_lshlrev_b32_e32 v36, 16, v98
	v_cvt_pk_bf16_f32 v33, v34, v35
; __device__ __forceinline__ unsigned cvt_pk_bf16(float lo, float hi) { unsigned r; asm volatile("s_nop 0\n\tv_cvt_pk_bf16_f32 %0, %1, %2\n\ts_nop 1" : "=v"(r) : "v"(lo), "v"(hi)); return r; }
; #define PG8_WAIT_V(n) asm volatile("s_waitcnt vmcnt(" #n ")" ::: "memory")
; #define PG8_BAR __builtin_amdgcn_s_barrier()
; __device__ __forceinline__ float bflo(unsigned w) { return __uint_as_float(w << 16); }
; __device__ __forceinline__ float bfhi(unsigned w) { return __uint_as_float(w & 0xffff0000u); }
; template <class Epi, class Sched>
; __device__ __forceinline__ void gemm_phase(PG8_LAS unsigned char* lds, const Gemm g, const Sched& S, const Epi& E, int tid_in) {
;     ...
;         if (!has_next) break;
; #pragma unroll
;         for (int a = 0; a < 2; ++a)
; #pragma unroll
;             for (int b = 0; b < 2; ++b)
; #pragma unroll
;                 for (int m = 0; m < 4; ++m)
; #pragma unroll
;                     for (int n = 0; n < 2; ++n) acc[a][b][m][n] = (f32x4){0.f, 0.f, 0.f, 0.f};
;         cur = nxt; cA = nA; cB = nB; ++ui;
;     }
;     PG8_WAIT_V(0);
;     if (wr == 0) PG8_BAR;
;     PG8_BAR;
;     __device__ __forceinline__ void operator()(f32x4 (&acc)[2][2][4][2], const Unit& u, int wr, int wc, int fr, int fq) const {
;     ...
;             for (int m = 0; m < 4; ++m) { const size_t row = row0 + ai * 128 + m * 16;
; #pragma unroll
;                 for (int bj = 0; bj < 2; ++bj)
; #pragma unroll
;                     for (int n = 0; n < 2; ++n) { const int col = col0 + bj * 128 + n * 16; const u32x2 g2 = gw[m][bj][n], t2 = tw[m][bj][n];
;                         const f32x4 gv = (f32x4){bflo(g2.x), bfhi(g2.x), bflo(g2.y), bfhi(g2.y)};
;                         const f32x4 o = (f32x4){bflo(t2.x), bfhi(t2.x), bflo(t2.y), bfhi(t2.y)} + gv * acc[ai][bj][m][n];
;                         u32x2 w; w.x = cvt_pk_bf16(o[0], o[1]); w.y = cvt_pk_bf16(o[2], o[3]); *(u32x2*)(merged + row * 1024 + col) = w; } }
	global_store_dwordx2 v[46:47], v[32:33], off offset:288
	v_lshlrev_b32_e32 v32, 16, v96
	v_and_b32_e32 v33, 0xffff0000, v96
	v_lshlrev_b32_e32 v34, 16, v97
	v_and_b32_e32 v35, 0xffff0000, v97
	v_and_b32_e32 v37, 0xffff0000, v98
	v_lshlrev_b32_e32 v38, 16, v99
	v_and_b32_e32 v39, 0xffff0000, v99
	v_pk_fma_f32 v[30:31], v[30:31], v[34:35], v[38:39]
	v_pk_fma_f32 v[28:29], v[28:29], v[32:33], v[36:37]
	v_lshlrev_b32_e32 v34, 16, v92
	v_cvt_pk_bf16_f32 v28, v28, v29
	v_cvt_pk_bf16_f32 v29, v30, v31
	v_lshl_add_u64 v[30:31], s[6:7], 0, v[90:91]
	v_lshl_add_u64 v[30:31], v[30:31], 0, v[134:135]
	global_store_dwordx2 v[30:31], v[28:29], off
	v_lshlrev_b32_e32 v28, 16, v94
	v_and_b32_e32 v29, 0xffff0000, v94
	v_and_b32_e32 v35, 0xffff0000, v92
	v_lshlrev_b32_e32 v32, 16, v95
	v_and_b32_e32 v33, 0xffff0000, v95
	v_lshlrev_b32_e32 v36, 16, v93
	v_and_b32_e32 v37, 0xffff0000, v93
	v_pk_fma_f32 v[24:25], v[24:25], v[28:29], v[34:35]
	v_pk_fma_f32 v[26:27], v[26:27], v[32:33], v[36:37]
	v_cvt_pk_bf16_f32 v24, v24, v25
	v_lshlrev_b32_e32 v28, 16, v86
	v_cvt_pk_bf16_f32 v25, v26, v27
	global_store_dwordx2 v[30:31], v[24:25], off offset:32
	v_lshlrev_b32_e32 v24, 16, v88
	v_and_b32_e32 v25, 0xffff0000, v88
	v_and_b32_e32 v29, 0xffff0000, v86
	v_lshlrev_b32_e32 v26, 16, v89
	v_and_b32_e32 v27, 0xffff0000, v89
	v_lshlrev_b32_e32 v32, 16, v87
	v_and_b32_e32 v33, 0xffff0000, v87
	v_pk_fma_f32 v[20:21], v[20:21], v[24:25], v[28:29]
	v_pk_fma_f32 v[22:23], v[22:23], v[26:27], v[32:33]
	v_cvt_pk_bf16_f32 v20, v20, v21
	v_lshlrev_b32_e32 v24, 16, v84
	v_cvt_pk_bf16_f32 v21, v22, v23
	global_store_dwordx2 v[30:31], v[20:21], off offset:256
	v_lshlrev_b32_e32 v20, 16, v82
	v_and_b32_e32 v21, 0xffff0000, v82
	v_and_b32_e32 v25, 0xffff0000, v84
	v_lshlrev_b32_e32 v22, 16, v83
	v_and_b32_e32 v23, 0xffff0000, v83
	v_lshlrev_b32_e32 v26, 16, v85
	v_and_b32_e32 v27, 0xffff0000, v85
	v_pk_fma_f32 v[16:17], v[16:17], v[20:21], v[24:25]
	v_pk_fma_f32 v[18:19], v[18:19], v[22:23], v[26:27]
	v_cvt_pk_bf16_f32 v16, v16, v17
	v_lshlrev_b32_e32 v20, 16, v80
	v_cvt_pk_bf16_f32 v17, v18, v19
	global_store_dwordx2 v[30:31], v[16:17], off offset:288
	v_lshlrev_b32_e32 v16, 16, v78
	v_and_b32_e32 v17, 0xffff0000, v78
	v_lshlrev_b32_e32 v18, 16, v79
	v_and_b32_e32 v19, 0xffff0000, v79
	v_and_b32_e32 v21, 0xffff0000, v80
	v_lshlrev_b32_e32 v22, 16, v81
	v_and_b32_e32 v23, 0xffff0000, v81
	v_pk_fma_f32 v[14:15], v[14:15], v[18:19], v[22:23]
	v_pk_fma_f32 v[12:13], v[12:13], v[16:17], v[20:21]
	v_lshlrev_b32_e32 v18, 16, v74
	v_cvt_pk_bf16_f32 v12, v12, v13
	v_cvt_pk_bf16_f32 v13, v14, v15
	v_lshl_add_u64 v[14:15], s[6:7], 0, v[72:73]
	v_lshl_add_u64 v[14:15], v[14:15], 0, v[134:135]
	global_store_dwordx2 v[14:15], v[12:13], off
	v_lshlrev_b32_e32 v12, 16, v76
	v_and_b32_e32 v13, 0xffff0000, v76
	v_and_b32_e32 v19, 0xffff0000, v74
	v_lshlrev_b32_e32 v16, 16, v77
	v_and_b32_e32 v17, 0xffff0000, v77
	v_lshlrev_b32_e32 v20, 16, v75
	v_and_b32_e32 v21, 0xffff0000, v75
	v_pk_fma_f32 v[8:9], v[8:9], v[12:13], v[18:19]
	v_pk_fma_f32 v[10:11], v[10:11], v[16:17], v[20:21]
	v_cvt_pk_bf16_f32 v8, v8, v9
	v_lshlrev_b32_e32 v12, 16, v68
	v_cvt_pk_bf16_f32 v9, v10, v11
	global_store_dwordx2 v[14:15], v[8:9], off offset:32
	v_lshlrev_b32_e32 v8, 16, v70
	v_and_b32_e32 v9, 0xffff0000, v70
	v_and_b32_e32 v13, 0xffff0000, v68
	v_lshlrev_b32_e32 v10, 16, v71
	v_and_b32_e32 v11, 0xffff0000, v71
	v_lshlrev_b32_e32 v16, 16, v69
	v_and_b32_e32 v17, 0xffff0000, v69
	v_pk_fma_f32 v[4:5], v[4:5], v[8:9], v[12:13]
	v_pk_fma_f32 v[6:7], v[6:7], v[10:11], v[16:17]
	v_cvt_pk_bf16_f32 v4, v4, v5
	v_lshlrev_b32_e32 v8, 16, v66
	v_cvt_pk_bf16_f32 v5, v6, v7
	global_store_dwordx2 v[14:15], v[4:5], off offset:256
	v_lshlrev_b32_e32 v4, 16, v64
	v_and_b32_e32 v5, 0xffff0000, v64
	v_and_b32_e32 v9, 0xffff0000, v66
	v_lshlrev_b32_e32 v6, 16, v65
	v_and_b32_e32 v7, 0xffff0000, v65
	v_lshlrev_b32_e32 v10, 16, v67
	v_and_b32_e32 v11, 0xffff0000, v67
	v_pk_fma_f32 v[0:1], v[0:1], v[4:5], v[8:9]
	v_pk_fma_f32 v[2:3], v[2:3], v[6:7], v[10:11]
	v_cvt_pk_bf16_f32 v0, v0, v1
	s_nop 0
	v_cvt_pk_bf16_f32 v1, v2, v3
	s_nop 1
	global_store_dwordx2 v[14:15], v[0:1], off offset:288
	s_cbranch_vccz .LBB0_363
	s_waitcnt vmcnt(0)
	s_cmpk_gt_u32 s24, 0xff
	s_cbranch_scc1 .LBB0_374
	s_barrier

; #define PG8_STAGE(bufoff, gbase, voff) do { _Pragma("unroll") for (int _i = 0; _i < 2; ++_i) \
;         __builtin_amdgcn_global_load_lds((const unsigned*)((const char*)(gbase) + (voff)[_i]), (PG8_LAS unsigned*)(lds + (bufoff) + ldsw + _i * 8192), 16, 0, 0); } while (0)
; #define PG8_LDA(dst, b, h) do { _Pragma("unroll") for (int m = 0; m < 4; ++m) _Pragma("unroll") for (int k = 0; k < 2; ++k) dst[m][k] = *(const PG8_LAS bf16x8*)(lds + PG8_SA(b, h) + aoff + m * 2048 + k * 1024); } while (0)
; #define PG8_LDB(dst, b, h) do { _Pragma("unroll") for (int n = 0; n < 2; ++n) _Pragma("unroll") for (int k = 0; k < 2; ++k) dst[n][k] = *(const PG8_LAS bf16x8*)(lds + PG8_SB(b, h) + boff + n * 2048 + k * 1024); } while (0)
; #define PG8_MMA(ai, bj, At, Bt) do { __builtin_amdgcn_s_setprio(1); _Pragma("unroll") for (int m = 0; m < 4; ++m) _Pragma("unroll") for (int n = 0; n < 2; ++n) _Pragma("unroll") for (int k = 0; k < 2; ++k) \
;         acc[ai][bj][m][n] = __builtin_amdgcn_mfma_f32_16x16x32_bf16(Bt[n][k], At[m][k], acc[ai][bj][m][n], 0, 0, 0); __builtin_amdgcn_s_setprio(0); } while (0)
; #define PG8_WAIT_L(n) asm volatile("s_waitcnt lgkmcnt(" #n ")" ::: "memory")
; #define PG8_BAR __builtin_amdgcn_s_barrier()
; #define PG8_SCHED __builtin_amdgcn_sched_barrier(0)
; template <class Epi, class Sched>
; __device__ __forceinline__ void gemm_phase(PG8_LAS unsigned char* lds, const Gemm g, const Sched& S, const Epi& E, int tid_in) {
;     ...
;             PG8_LDB(B0, 0, 0); PG8_SCHED; PG8_LDA(At, 0, 0); PG8_STAGE(PG8_SA(1, 1), a1 + hstep, voffA);
;             PG8_WAIT_L(8); PG8_BAR; PG8_WAIT_L(0); PG8_MMA(0, 0, At, B0); PG8_BAR; PG8_SCHED;
;             PG8_LDB(B1, 0, 1); PG8_STAGE(PG8_SB(0, 0), b2, voffB);
;             PG8_BAR; PG8_WAIT_L(0); PG8_MMA(0, 1, At, B1); PG8_BAR;
;             PG8_LDA(At, 0, 1); PG8_STAGE(PG8_SA(0, 0), a2, voffA);
;             PG8_BAR; PG8_WAIT_L(0); PG8_MMA(1, 0, At, B0); PG8_BAR; PG8_SCHED;
.LBB0_388:
	s_add_u32 s28, s26, 0xfffc0080
	s_addc_u32 s29, s27, -1
	s_add_i32 s38, 0, 0x10000
	v_add_u32_e32 v140, s38, v246
	ds_read_b128 v[128:131], v140
	ds_read_b128 v[132:135], v140 offset:1024
	ds_read_b128 v[136:139], v140 offset:2048
	ds_read_b128 v[140:143], v140 offset:3072
	s_cmp_eq_u32 s37, 12
	s_cselect_b32 s31, s1, s29
	s_cselect_b32 s30, s19, s28
	s_cselect_b32 s29, s17, s36
	s_cselect_b32 s28, s25, s33
	v_lshl_add_u64 v[176:177], s[26:27], 0, v[210:211]
	s_add_i32 m0, s73, 0xc000
	ds_read_b128 v[144:147], v251
	ds_read_b128 v[148:151], v251 offset:1024
	ds_read_b128 v[152:155], v251 offset:2048
	ds_read_b128 v[156:159], v251 offset:3072
	ds_read_b128 v[160:163], v251 offset:4096
	ds_read_b128 v[164:167], v251 offset:5120
	ds_read_b128 v[168:171], v251 offset:6144
	ds_read_b128 v[172:175], v251 offset:7168
	global_load_lds_dwordx4 v[176:177], off
	s_add_i32 m0, s73, 0xe000
	v_lshl_add_u64 v[176:177], s[26:27], 0, v[212:213]
	global_load_lds_dwordx4 v[176:177], off
	s_waitcnt lgkmcnt(8)
	s_barrier
	s_waitcnt lgkmcnt(0)
	s_waitcnt lgkmcnt(0)
	v_mfma_f32_16x16x32_bf16 v[124:127], v[128:131], v[144:147], v[124:127]
	v_mfma_f32_16x16x32_bf16 v[120:123], v[136:139], v[144:147], v[120:123]
	v_mfma_f32_16x16x32_bf16 v[108:111], v[128:131], v[152:155], v[108:111]
	v_mfma_f32_16x16x32_bf16 v[104:107], v[136:139], v[152:155], v[104:107]
	v_mfma_f32_16x16x32_bf16 v[92:95], v[128:131], v[160:163], v[92:95]
	v_mfma_f32_16x16x32_bf16 v[88:91], v[136:139], v[160:163], v[88:91]
	v_mfma_f32_16x16x32_bf16 v[76:79], v[128:131], v[168:171], v[76:79]
	v_mfma_f32_16x16x32_bf16 v[72:75], v[136:139], v[168:171], v[72:75]
	v_mfma_f32_16x16x32_bf16 v[124:127], v[132:135], v[148:151], v[124:127]
	v_mfma_f32_16x16x32_bf16 v[120:123], v[140:143], v[148:151], v[120:123]
	v_mfma_f32_16x16x32_bf16 v[108:111], v[132:135], v[156:159], v[108:111]
	v_mfma_f32_16x16x32_bf16 v[104:107], v[140:143], v[156:159], v[104:107]
	v_mfma_f32_16x16x32_bf16 v[92:95], v[132:135], v[164:167], v[92:95]
	v_mfma_f32_16x16x32_bf16 v[88:91], v[140:143], v[164:167], v[88:91]
	v_mfma_f32_16x16x32_bf16 v[76:79], v[132:135], v[172:175], v[76:79]
	v_mfma_f32_16x16x32_bf16 v[72:75], v[140:143], v[172:175], v[72:75]
	s_barrier
	s_add_i32 s40, 0, 0x14000
	s_add_i32 s38, s38, s72
	v_add_u32_e32 v188, s40, v246
	v_lshl_add_u64 v[194:195], s[28:29], 0, v[202:203]
	s_mov_b32 m0, s38
	ds_read_b128 v[176:179], v188
	ds_read_b128 v[180:183], v188 offset:1024
	ds_read_b128 v[184:187], v188 offset:2048
	ds_read_b128 v[188:191], v188 offset:3072
	global_load_lds_dwordx4 v[194:195], off
	s_add_i32 m0, s38, 0x2000
	v_lshl_add_u64 v[196:197], s[28:29], 0, v[206:207]
	global_load_lds_dwordx4 v[196:197], off
	s_barrier
	s_waitcnt lgkmcnt(0)
	s_waitcnt lgkmcnt(0)
	v_mfma_f32_16x16x32_bf16 v[116:119], v[176:179], v[144:147], v[116:119]
	v_mfma_f32_16x16x32_bf16 v[112:115], v[184:187], v[144:147], v[112:115]
	v_mfma_f32_16x16x32_bf16 v[100:103], v[176:179], v[152:155], v[100:103]
	v_mfma_f32_16x16x32_bf16 v[96:99], v[184:187], v[152:155], v[96:99]
	v_mfma_f32_16x16x32_bf16 v[84:87], v[176:179], v[160:163], v[84:87]
	v_mfma_f32_16x16x32_bf16 v[80:83], v[184:187], v[160:163], v[80:83]
	v_mfma_f32_16x16x32_bf16 v[68:71], v[176:179], v[168:171], v[68:71]
	v_mfma_f32_16x16x32_bf16 v[64:67], v[184:187], v[168:171], v[64:67]
	v_mfma_f32_16x16x32_bf16 v[116:119], v[180:183], v[148:151], v[116:119]
	v_mfma_f32_16x16x32_bf16 v[112:115], v[188:191], v[148:151], v[112:115]
	v_mfma_f32_16x16x32_bf16 v[100:103], v[180:183], v[156:159], v[100:103]
	v_mfma_f32_16x16x32_bf16 v[96:99], v[188:191], v[156:159], v[96:99]
	v_mfma_f32_16x16x32_bf16 v[84:87], v[180:183], v[164:167], v[84:87]
	v_mfma_f32_16x16x32_bf16 v[80:83], v[188:191], v[164:167], v[80:83]
	v_mfma_f32_16x16x32_bf16 v[68:71], v[180:183], v[172:175], v[68:71]
	v_mfma_f32_16x16x32_bf16 v[64:67], v[188:191], v[172:175], v[64:67]
	s_mov_b32 m0, s73
	v_lshl_add_u64 v[214:215], s[30:31], 0, v[200:201]
	s_barrier
	ds_read_b128 v[144:147], v251 offset:16384
	ds_read_b128 v[148:151], v251 offset:17408
	ds_read_b128 v[152:155], v251 offset:18432
	ds_read_b128 v[156:159], v251 offset:19456
	ds_read_b128 v[160:163], v251 offset:20480
	ds_read_b128 v[164:167], v251 offset:21504
	ds_read_b128 v[168:171], v251 offset:22528
	ds_read_b128 v[172:175], v251 offset:23552
	global_load_lds_dwordx4 v[214:215], off
	s_mov_b32 m0, s76
	v_lshl_add_u64 v[216:217], s[30:31], 0, v[204:205]
	global_load_lds_dwordx4 v[216:217], off
	s_barrier
	s_waitcnt lgkmcnt(0)
	s_waitcnt lgkmcnt(0)
	v_mfma_f32_16x16x32_bf16 v[60:63], v[128:131], v[144:147], v[60:63]
	v_mfma_f32_16x16x32_bf16 v[56:59], v[136:139], v[144:147], v[56:59]
	v_mfma_f32_16x16x32_bf16 v[44:47], v[128:131], v[152:155], v[44:47]
	v_mfma_f32_16x16x32_bf16 v[40:43], v[136:139], v[152:155], v[40:43]
	v_mfma_f32_16x16x32_bf16 v[28:31], v[128:131], v[160:163], v[28:31]
	v_mfma_f32_16x16x32_bf16 v[24:27], v[136:139], v[160:163], v[24:27]
	v_mfma_f32_16x16x32_bf16 v[12:15], v[128:131], v[168:171], v[12:15]
	v_mfma_f32_16x16x32_bf16 v[8:11], v[136:139], v[168:171], v[8:11]
	v_mfma_f32_16x16x32_bf16 v[60:63], v[132:135], v[148:151], v[60:63]
	v_mfma_f32_16x16x32_bf16 v[56:59], v[140:143], v[148:151], v[56:59]
	v_mfma_f32_16x16x32_bf16 v[44:47], v[132:135], v[156:159], v[44:47]
	v_mfma_f32_16x16x32_bf16 v[40:43], v[140:143], v[156:159], v[40:43]
	v_mfma_f32_16x16x32_bf16 v[28:31], v[132:135], v[164:167], v[28:31]
	v_mfma_f32_16x16x32_bf16 v[24:27], v[140:143], v[164:167], v[24:27]
	v_mfma_f32_16x16x32_bf16 v[12:15], v[132:135], v[172:175], v[12:15]
	v_mfma_f32_16x16x32_bf16 v[8:11], v[140:143], v[172:175], v[8:11]
	s_barrier
; #define PG8_STAGE(bufoff, gbase, voff) do { _Pragma("unroll") for (int _i = 0; _i < 2; ++_i) \
;         __builtin_amdgcn_global_load_lds((const unsigned*)((const char*)(gbase) + (voff)[_i]), (PG8_LAS unsigned*)(lds + (bufoff) + ldsw + _i * 8192), 16, 0, 0); } while (0)
; #define PG8_LDA(dst, b, h) do { _Pragma("unroll") for (int m = 0; m < 4; ++m) _Pragma("unroll") for (int k = 0; k < 2; ++k) dst[m][k] = *(const PG8_LAS bf16x8*)(lds + PG8_SA(b, h) + aoff + m * 2048 + k * 1024); } while (0)
; #define PG8_LDB(dst, b, h) do { _Pragma("unroll") for (int n = 0; n < 2; ++n) _Pragma("unroll") for (int k = 0; k < 2; ++k) dst[n][k] = *(const PG8_LAS bf16x8*)(lds + PG8_SB(b, h) + boff + n * 2048 + k * 1024); } while (0)
; #define PG8_MMA(ai, bj, At, Bt) do { __builtin_amdgcn_s_setprio(1); _Pragma("unroll") for (int m = 0; m < 4; ++m) _Pragma("unroll") for (int n = 0; n < 2; ++n) _Pragma("unroll") for (int k = 0; k < 2; ++k) \
;         acc[ai][bj][m][n] = __builtin_amdgcn_mfma_f32_16x16x32_bf16(Bt[n][k], At[m][k], acc[ai][bj][m][n], 0, 0, 0); __builtin_amdgcn_s_setprio(0); } while (0)
; #define PG8_WAIT_V(n) asm volatile("s_waitcnt vmcnt(" #n ")" ::: "memory")
; #define PG8_WAIT_L(n) asm volatile("s_waitcnt lgkmcnt(" #n ")" ::: "memory")
; #define PG8_BAR __builtin_amdgcn_s_barrier()
; #define PG8_SCHED __builtin_amdgcn_sched_barrier(0)
; template <class Epi, class Sched>
; __device__ __forceinline__ void gemm_phase(PG8_LAS unsigned char* lds, const Gemm g, const Sched& S, const Epi& E, int tid_in) {
;     ...
;             PG8_STAGE(PG8_SB(0, 1), b2 + hstep, voffB);
;             PG8_WAIT_V(6); PG8_BAR; PG8_MMA(1, 1, At, B1); PG8_BAR;
;             PG8_LDB(B0, 1, 0); PG8_SCHED; PG8_LDA(At, 1, 0); PG8_STAGE(PG8_SA(0, 1), a2 + hstep, voffA);
;             PG8_WAIT_L(8); PG8_BAR; PG8_WAIT_L(0); PG8_MMA(0, 0, At, B0); PG8_BAR; PG8_SCHED;
;             PG8_LDB(B1, 1, 1); PG8_STAGE(PG8_SB(1, 0), b3, voffB);
;             PG8_BAR; PG8_WAIT_L(0); PG8_MMA(0, 1, At, B1); PG8_BAR;
;             PG8_LDA(At, 1, 1); PG8_STAGE(PG8_SA(1, 0), a3, voffA);
	s_add_u32 s38, s28, 0x40000
	s_addc_u32 s39, s29, 0
	s_add_i32 s40, s40, s72
	s_mov_b32 m0, s40
	v_lshl_add_u64 v[128:129], s[38:39], 0, v[202:203]
	global_load_lds_dwordx4 v[128:129], off
	s_add_i32 m0, s40, 0x2000
	v_lshl_add_u64 v[128:129], s[38:39], 0, v[206:207]
	global_load_lds_dwordx4 v[128:129], off
	s_waitcnt vmcnt(6)
	s_barrier
	v_mfma_f32_16x16x32_bf16 v[52:55], v[176:179], v[144:147], v[52:55]
	v_mfma_f32_16x16x32_bf16 v[48:51], v[184:187], v[144:147], v[48:51]
	v_mfma_f32_16x16x32_bf16 v[36:39], v[176:179], v[152:155], v[36:39]
	v_mfma_f32_16x16x32_bf16 v[32:35], v[184:187], v[152:155], v[32:35]
	v_mfma_f32_16x16x32_bf16 v[20:23], v[176:179], v[160:163], v[20:23]
	v_mfma_f32_16x16x32_bf16 v[16:19], v[184:187], v[160:163], v[16:19]
	v_mfma_f32_16x16x32_bf16 v[4:7], v[176:179], v[168:171], v[4:7]
	v_mfma_f32_16x16x32_bf16 v[0:3], v[184:187], v[168:171], v[0:3]
	v_mfma_f32_16x16x32_bf16 v[52:55], v[180:183], v[148:151], v[52:55]
	v_mfma_f32_16x16x32_bf16 v[48:51], v[188:191], v[148:151], v[48:51]
	v_mfma_f32_16x16x32_bf16 v[36:39], v[180:183], v[156:159], v[36:39]
	v_mfma_f32_16x16x32_bf16 v[32:35], v[188:191], v[156:159], v[32:35]
	v_mfma_f32_16x16x32_bf16 v[20:23], v[180:183], v[164:167], v[20:23]
	v_mfma_f32_16x16x32_bf16 v[16:19], v[188:191], v[164:167], v[16:19]
	v_mfma_f32_16x16x32_bf16 v[4:7], v[180:183], v[172:175], v[4:7]
	v_mfma_f32_16x16x32_bf16 v[0:3], v[188:191], v[172:175], v[0:3]
	s_add_i32 s38, 0, 0x18000
	v_add_u32_e32 v140, s38, v246
	s_barrier
	ds_read_b128 v[128:131], v140
	ds_read_b128 v[132:135], v140 offset:1024
	ds_read_b128 v[136:139], v140 offset:2048
	ds_read_b128 v[140:143], v140 offset:3072
	s_add_u32 s30, s30, 0x40000
	s_addc_u32 s31, s31, 0
	s_mov_b32 m0, s77
	v_lshl_add_u64 v[176:177], s[30:31], 0, v[200:201]
	ds_read_b128 v[144:147], v251 offset:32768
	ds_read_b128 v[148:151], v251 offset:33792
	ds_read_b128 v[152:155], v251 offset:34816
	ds_read_b128 v[156:159], v251 offset:35840
	ds_read_b128 v[160:163], v251 offset:36864
	ds_read_b128 v[164:167], v251 offset:37888
	ds_read_b128 v[168:171], v251 offset:38912
	ds_read_b128 v[172:175], v251 offset:39936
	global_load_lds_dwordx4 v[176:177], off
	s_mov_b32 m0, s78
	v_lshl_add_u64 v[176:177], s[30:31], 0, v[204:205]
	global_load_lds_dwordx4 v[176:177], off
	s_waitcnt lgkmcnt(8)
	s_barrier
	s_waitcnt lgkmcnt(0)
	s_waitcnt lgkmcnt(0)
	v_mfma_f32_16x16x32_bf16 v[124:127], v[128:131], v[144:147], v[124:127]
	v_mfma_f32_16x16x32_bf16 v[120:123], v[136:139], v[144:147], v[120:123]
	v_mfma_f32_16x16x32_bf16 v[108:111], v[128:131], v[152:155], v[108:111]
	v_mfma_f32_16x16x32_bf16 v[104:107], v[136:139], v[152:155], v[104:107]
	v_mfma_f32_16x16x32_bf16 v[92:95], v[128:131], v[160:163], v[92:95]
	v_mfma_f32_16x16x32_bf16 v[88:91], v[136:139], v[160:163], v[88:91]
	v_mfma_f32_16x16x32_bf16 v[76:79], v[128:131], v[168:171], v[76:79]
	v_mfma_f32_16x16x32_bf16 v[72:75], v[136:139], v[168:171], v[72:75]
	v_mfma_f32_16x16x32_bf16 v[124:127], v[132:135], v[148:151], v[124:127]
	v_mfma_f32_16x16x32_bf16 v[120:123], v[140:143], v[148:151], v[120:123]
	v_mfma_f32_16x16x32_bf16 v[108:111], v[132:135], v[156:159], v[108:111]
	v_mfma_f32_16x16x32_bf16 v[104:107], v[140:143], v[156:159], v[104:107]
	v_mfma_f32_16x16x32_bf16 v[92:95], v[132:135], v[164:167], v[92:95]
	v_mfma_f32_16x16x32_bf16 v[88:91], v[140:143], v[164:167], v[88:91]
	v_mfma_f32_16x16x32_bf16 v[76:79], v[132:135], v[172:175], v[76:79]
	v_mfma_f32_16x16x32_bf16 v[72:75], v[140:143], v[172:175], v[72:75]
	s_barrier
	s_add_i32 s30, 0, 0x1c000
	s_add_i32 s31, s38, s72
	v_add_u32_e32 v188, s30, v246
	v_lshl_add_u64 v[194:195], v[194:195], 0, s[74:75]
	s_mov_b32 m0, s31
	ds_read_b128 v[176:179], v188
	ds_read_b128 v[180:183], v188 offset:1024
	ds_read_b128 v[184:187], v188 offset:2048
	ds_read_b128 v[188:191], v188 offset:3072
	global_load_lds_dwordx4 v[194:195], off
	s_add_i32 m0, s31, 0x2000
	v_lshl_add_u64 v[194:195], v[196:197], 0, s[74:75]
	global_load_lds_dwordx4 v[194:195], off
	s_barrier
	s_waitcnt lgkmcnt(0)
	s_waitcnt lgkmcnt(0)
	v_mfma_f32_16x16x32_bf16 v[116:119], v[176:179], v[144:147], v[116:119]
	v_mfma_f32_16x16x32_bf16 v[112:115], v[184:187], v[144:147], v[112:115]
	v_mfma_f32_16x16x32_bf16 v[100:103], v[176:179], v[152:155], v[100:103]
	v_mfma_f32_16x16x32_bf16 v[96:99], v[184:187], v[152:155], v[96:99]
	v_mfma_f32_16x16x32_bf16 v[84:87], v[176:179], v[160:163], v[84:87]
	v_mfma_f32_16x16x32_bf16 v[80:83], v[184:187], v[160:163], v[80:83]
	v_mfma_f32_16x16x32_bf16 v[68:71], v[176:179], v[168:171], v[68:71]
	v_mfma_f32_16x16x32_bf16 v[64:67], v[184:187], v[168:171], v[64:67]
	v_mfma_f32_16x16x32_bf16 v[116:119], v[180:183], v[148:151], v[116:119]
	v_mfma_f32_16x16x32_bf16 v[112:115], v[188:191], v[148:151], v[112:115]
	v_mfma_f32_16x16x32_bf16 v[100:103], v[180:183], v[156:159], v[100:103]
	v_mfma_f32_16x16x32_bf16 v[96:99], v[188:191], v[156:159], v[96:99]
	v_mfma_f32_16x16x32_bf16 v[84:87], v[180:183], v[164:167], v[84:87]
	v_mfma_f32_16x16x32_bf16 v[80:83], v[188:191], v[164:167], v[80:83]
	v_mfma_f32_16x16x32_bf16 v[68:71], v[180:183], v[172:175], v[68:71]
	v_mfma_f32_16x16x32_bf16 v[64:67], v[188:191], v[172:175], v[64:67]
	s_mov_b32 m0, s80
	v_lshl_add_u64 v[194:195], v[214:215], 0, s[74:75]
	s_barrier
	ds_read_b128 v[144:147], v251 offset:49152
	ds_read_b128 v[148:151], v251 offset:50176
	ds_read_b128 v[152:155], v251 offset:51200
	ds_read_b128 v[156:159], v251 offset:52224
	ds_read_b128 v[160:163], v251 offset:53248
	ds_read_b128 v[164:167], v251 offset:54272
	ds_read_b128 v[168:171], v251 offset:55296
	ds_read_b128 v[172:175], v251 offset:56320
	global_load_lds_dwordx4 v[194:195], off
	s_mov_b32 m0, s81
	v_lshl_add_u64 v[194:195], v[216:217], 0, s[74:75]
	global_load_lds_dwordx4 v[194:195], off
	s_barrier
; __device__ __forceinline__ unsigned cvt_pk_bf16(float lo, float hi) { unsigned r; asm volatile("s_nop 0\n\tv_cvt_pk_bf16_f32 %0, %1, %2\n\ts_nop 1" : "=v"(r) : "v"(lo), "v"(hi)); return r; }
; #define PG8_STAGE(bufoff, gbase, voff) do { _Pragma("unroll") for (int _i = 0; _i < 2; ++_i) \
;         __builtin_amdgcn_global_load_lds((const unsigned*)((const char*)(gbase) + (voff)[_i]), (PG8_LAS unsigned*)(lds + (bufoff) + ldsw + _i * 8192), 16, 0, 0); } while (0)
; #define PG8_MMA(ai, bj, At, Bt) do { __builtin_amdgcn_s_setprio(1); _Pragma("unroll") for (int m = 0; m < 4; ++m) _Pragma("unroll") for (int n = 0; n < 2; ++n) _Pragma("unroll") for (int k = 0; k < 2; ++k) \
;         acc[ai][bj][m][n] = __builtin_amdgcn_mfma_f32_16x16x32_bf16(Bt[n][k], At[m][k], acc[ai][bj][m][n], 0, 0, 0); __builtin_amdgcn_s_setprio(0); } while (0)
; #define PG8_WAIT_V(n) asm volatile("s_waitcnt vmcnt(" #n ")" ::: "memory")
; #define PG8_WAIT_L(n) asm volatile("s_waitcnt lgkmcnt(" #n ")" ::: "memory")
; #define PG8_BAR __builtin_amdgcn_s_barrier()
; template <class Epi, class Sched>
; __device__ __forceinline__ void gemm_phase(PG8_LAS unsigned char* lds, const Gemm g, const Sched& S, const Epi& E, int tid_in) {
;     ...
;             PG8_BAR; PG8_WAIT_L(0); PG8_MMA(1, 0, At, B0); PG8_BAR; PG8_SCHED;
;             PG8_STAGE(PG8_SB(1, 1), b3 + hstep, voffB);
;             PG8_WAIT_V(6); PG8_BAR; PG8_MMA(1, 1, At, B1); PG8_BAR;
;         }
;     __device__ __forceinline__ void operator()(f32x4 (&acc)[2][2][4][2], const Unit& u, int wr, int wc, int fr, int fq) const {
;     ...
;         } else {
; #pragma unroll
;             for (int bj = 0; bj < 2; ++bj) { const int col = (u.pn - 12) * 256 + bj * 128 + c8;
;                 const f32x4 b0 = *(const f32x4*)(b_gate + col), b1 = *(const f32x4*)(b_gate + col + 4);
; #pragma unroll
;                 for (int ai = 0; ai < 2; ++ai)
; #pragma unroll
;                     for (int m = 0; m < 4; ++m) { const f32x4 v0 = acc[ai][bj][m][0] + b0, v1 = acc[ai][bj][m][1] + b1;
;                         u32x4 w; w.x = cvt_pk_bf16(sigmoidf_(v0[0]), sigmoidf_(v0[1])); w.y = cvt_pk_bf16(sigmoidf_(v0[2]), sigmoidf_(v0[3]));
;                         w.z = cvt_pk_bf16(sigmoidf_(v1[0]), sigmoidf_(v1[1])); w.w = cvt_pk_bf16(sigmoidf_(v1[2]), sigmoidf_(v1[3]));
;                         *(u32x4*)(gates + (size_t)(row0 + ai * 128 + m * 16) * 2048 + col) = w; } }
	s_waitcnt lgkmcnt(0)
	s_waitcnt lgkmcnt(0)
	v_mfma_f32_16x16x32_bf16 v[60:63], v[128:131], v[144:147], v[60:63]
	v_mfma_f32_16x16x32_bf16 v[56:59], v[136:139], v[144:147], v[56:59]
	v_mfma_f32_16x16x32_bf16 v[44:47], v[128:131], v[152:155], v[44:47]
	v_mfma_f32_16x16x32_bf16 v[40:43], v[136:139], v[152:155], v[40:43]
	v_mfma_f32_16x16x32_bf16 v[28:31], v[128:131], v[160:163], v[28:31]
	v_mfma_f32_16x16x32_bf16 v[24:27], v[136:139], v[160:163], v[24:27]
	v_mfma_f32_16x16x32_bf16 v[12:15], v[128:131], v[168:171], v[12:15]
	v_mfma_f32_16x16x32_bf16 v[8:11], v[136:139], v[168:171], v[8:11]
	v_mfma_f32_16x16x32_bf16 v[60:63], v[132:135], v[148:151], v[60:63]
	v_mfma_f32_16x16x32_bf16 v[56:59], v[140:143], v[148:151], v[56:59]
	v_mfma_f32_16x16x32_bf16 v[44:47], v[132:135], v[156:159], v[44:47]
	v_mfma_f32_16x16x32_bf16 v[40:43], v[140:143], v[156:159], v[40:43]
	v_mfma_f32_16x16x32_bf16 v[28:31], v[132:135], v[164:167], v[28:31]
	v_mfma_f32_16x16x32_bf16 v[24:27], v[140:143], v[164:167], v[24:27]
	v_mfma_f32_16x16x32_bf16 v[12:15], v[132:135], v[172:175], v[12:15]
	v_mfma_f32_16x16x32_bf16 v[8:11], v[140:143], v[172:175], v[8:11]
	s_barrier
	s_add_u32 s28, s28, 0x40080
	s_addc_u32 s29, s29, 0
	s_add_i32 s30, s30, s72
	s_mov_b32 m0, s30
	v_lshl_add_u64 v[128:129], s[28:29], 0, v[202:203]
	global_load_lds_dwordx4 v[128:129], off
	s_add_i32 m0, s30, 0x2000
	v_lshl_add_u64 v[128:129], s[28:29], 0, v[206:207]
	global_load_lds_dwordx4 v[128:129], off
	s_waitcnt vmcnt(6)
	s_barrier
	v_mfma_f32_16x16x32_bf16 v[52:55], v[176:179], v[144:147], v[52:55]
	v_mfma_f32_16x16x32_bf16 v[48:51], v[184:187], v[144:147], v[48:51]
	v_mfma_f32_16x16x32_bf16 v[36:39], v[176:179], v[152:155], v[36:39]
	v_mfma_f32_16x16x32_bf16 v[32:35], v[184:187], v[152:155], v[32:35]
	v_mfma_f32_16x16x32_bf16 v[20:23], v[176:179], v[160:163], v[20:23]
	v_mfma_f32_16x16x32_bf16 v[16:19], v[184:187], v[160:163], v[16:19]
	v_mfma_f32_16x16x32_bf16 v[4:7], v[176:179], v[168:171], v[4:7]
	v_mfma_f32_16x16x32_bf16 v[0:3], v[184:187], v[168:171], v[0:3]
	v_mfma_f32_16x16x32_bf16 v[52:55], v[180:183], v[148:151], v[52:55]
	v_mfma_f32_16x16x32_bf16 v[48:51], v[188:191], v[148:151], v[48:51]
	v_mfma_f32_16x16x32_bf16 v[36:39], v[180:183], v[156:159], v[36:39]
	v_mfma_f32_16x16x32_bf16 v[32:35], v[188:191], v[156:159], v[32:35]
	v_mfma_f32_16x16x32_bf16 v[20:23], v[180:183], v[164:167], v[20:23]
	v_mfma_f32_16x16x32_bf16 v[16:19], v[188:191], v[164:167], v[16:19]
	v_mfma_f32_16x16x32_bf16 v[4:7], v[180:183], v[172:175], v[4:7]
	v_mfma_f32_16x16x32_bf16 v[0:3], v[188:191], v[172:175], v[0:3]
	s_add_i32 s37, s37, 2
	s_add_u32 s26, s26, 0x100
	s_addc_u32 s27, s27, 0
	s_add_u32 s33, s33, 0x100
	s_addc_u32 s36, s36, 0
	s_cmp_gt_u32 s37, 13
	s_barrier
	s_cbranch_scc0 .LBB0_388
	v_lshl_add_u32 v214, s0, 8, v209
	s_cmp_gt_i32 s24, 7
	s_mov_b64 s[0:1], -1
	s_cbranch_scc0 .LBB0_395
	s_lshl_b32 s17, s24, 8
	s_cmp_lt_u32 s24, 12
	s_cbranch_scc1 .LBB0_392
	v_or_b32_e32 v128, 0xfffff400, v208
	v_add_u32_e32 v140, s17, v128
	v_readlane_b32 s48, v255, 19
	v_ashrrev_i32_e32 v141, 31, v140
	v_readlane_b32 s49, v255, 20
	v_ashrrev_i32_e32 v215, 31, v214
	v_lshlrev_b64 v[146:147], 1, v[140:141]
	v_lshl_add_u64 v[132:133], v[140:141], 2, s[48:49]
	global_load_dwordx4 v[128:131], v[132:133], off offset:16
	s_nop 0
	global_load_dwordx4 v[132:135], v[132:133], off
	s_mov_b64 s[0:1], 0x80000
	v_or_b32_e32 v140, 0x80, v140
	v_readlane_b32 s50, v255, 21
	v_readlane_b32 s51, v255, 22
	v_readlane_b32 s52, v255, 23
	v_readlane_b32 s53, v255, 24
	v_readlane_b32 s54, v255, 25
	v_readlane_b32 s55, v255, 26
	s_waitcnt vmcnt(0)
	v_pk_add_f32 v[144:145], v[120:121], v[128:129]
	v_pk_add_f32 v[136:137], v[124:125], v[132:133]
	v_pk_add_f32 v[138:139], v[126:127], v[134:135]
	v_mul_f32_e32 v136, 0xbfb8aa3b, v136
	v_mul_f32_e32 v137, 0xbfb8aa3b, v137
	v_exp_f32_e32 v136, v136
	v_exp_f32_e32 v137, v137
	v_pk_add_f32 v[142:143], v[122:123], v[130:131]
	v_pk_add_f32 v[148:149], v[104:105], v[128:129]
	v_add_f32_e32 v136, 1.0, v136
	v_add_f32_e32 v137, 1.0, v137
	v_rcp_f32_e32 v136, v136
	v_rcp_f32_e32 v137, v137
	s_nop 0
	v_cvt_pk_bf16_f32 v136, v136, v137
	v_mul_f32_e32 v137, 0xbfb8aa3b, v138
	v_mul_f32_e32 v138, 0xbfb8aa3b, v139
	v_exp_f32_e32 v137, v137
	v_exp_f32_e32 v138, v138
	v_mul_f32_e32 v139, 0xbfb8aa3b, v145
	v_exp_f32_e32 v139, v139
	v_add_f32_e32 v137, 1.0, v137
	v_add_f32_e32 v138, 1.0, v138
	v_rcp_f32_e32 v137, v137
	v_rcp_f32_e32 v138, v138
	s_nop 0
	v_cvt_pk_bf16_f32 v137, v137, v138
	v_mul_f32_e32 v138, 0xbfb8aa3b, v144
	v_exp_f32_e32 v138, v138
	v_add_f32_e32 v139, 1.0, v139
	v_rcp_f32_e32 v139, v139
	v_pk_add_f32 v[150:151], v[88:89], v[128:129]
	v_add_f32_e32 v138, 1.0, v138
	v_rcp_f32_e32 v138, v138
	s_nop 0
	v_cvt_pk_bf16_f32 v138, v138, v139
	v_mul_f32_e32 v139, 0xbfb8aa3b, v142
	v_mul_f32_e32 v142, 0xbfb8aa3b, v143
	v_exp_f32_e32 v139, v139
	v_exp_f32_e32 v142, v142
	v_pk_add_f32 v[152:153], v[90:91], v[130:131]
	v_pk_add_f32 v[154:155], v[58:59], v[130:131]
	v_add_f32_e32 v139, 1.0, v139
	v_add_f32_e32 v142, 1.0, v142
	v_rcp_f32_e32 v139, v139
	v_rcp_f32_e32 v142, v142
	s_nop 0
	v_cvt_pk_bf16_f32 v139, v139, v142
	v_lshlrev_b64 v[142:143], 12, v[214:215]
	v_lshl_add_u64 v[142:143], s[14:15], 0, v[142:143]
	v_lshl_add_u64 v[144:145], v[142:143], 0, v[146:147]
	global_store_dwordx4 v[144:145], v[136:139], off
	v_pk_add_f32 v[144:145], v[106:107], v[130:131]
	v_pk_add_f32 v[156:157], v[42:43], v[130:131]
	v_pk_add_f32 v[136:137], v[108:109], v[132:133]
	v_pk_add_f32 v[138:139], v[110:111], v[134:135]
	v_mul_f32_e32 v136, 0xbfb8aa3b, v136
	v_mul_f32_e32 v137, 0xbfb8aa3b, v137
	v_exp_f32_e32 v136, v136
; __device__ __forceinline__ unsigned cvt_pk_bf16(float lo, float hi) { unsigned r; asm volatile("s_nop 0\n\tv_cvt_pk_bf16_f32 %0, %1, %2\n\ts_nop 1" : "=v"(r) : "v"(lo), "v"(hi)); return r; }
; __device__ __forceinline__ float sigmoidf_(float x) { return __builtin_amdgcn_rcpf(1.f + __expf(-x)); }
;     __device__ __forceinline__ void operator()(f32x4 (&acc)[2][2][4][2], const Unit& u, int wr, int wc, int fr, int fq) const {
;     ...
; #pragma unroll
;             for (int bj = 0; bj < 2; ++bj) { const int col = (u.pn - 12) * 256 + bj * 128 + c8;
;                 const f32x4 b0 = *(const f32x4*)(b_gate + col), b1 = *(const f32x4*)(b_gate + col + 4);
; #pragma unroll
;                 for (int ai = 0; ai < 2; ++ai)
; #pragma unroll
;                     for (int m = 0; m < 4; ++m) { const f32x4 v0 = acc[ai][bj][m][0] + b0, v1 = acc[ai][bj][m][1] + b1;
;                         u32x4 w; w.x = cvt_pk_bf16(sigmoidf_(v0[0]), sigmoidf_(v0[1])); w.y = cvt_pk_bf16(sigmoidf_(v0[2]), sigmoidf_(v0[3]));
;                         w.z = cvt_pk_bf16(sigmoidf_(v1[0]), sigmoidf_(v1[1])); w.w = cvt_pk_bf16(sigmoidf_(v1[2]), sigmoidf_(v1[3]));
;                         *(u32x4*)(gates + (size_t)(row0 + ai * 128 + m * 16) * 2048 + col) = w; } }
	v_exp_f32_e32 v137, v137
	v_mul_f32_e32 v141, 0xbfb8aa3b, v145
	v_exp_f32_e32 v141, v141
	v_add_f32_e32 v136, 1.0, v136
	v_add_f32_e32 v137, 1.0, v137
	v_rcp_f32_e32 v136, v136
	v_rcp_f32_e32 v137, v137
	s_nop 0
	v_cvt_pk_bf16_f32 v136, v136, v137
	v_mul_f32_e32 v137, 0xbfb8aa3b, v138
	v_mul_f32_e32 v138, 0xbfb8aa3b, v139
	v_exp_f32_e32 v137, v137
	v_exp_f32_e32 v138, v138
	v_mul_f32_e32 v139, 0xbfb8aa3b, v149
	v_exp_f32_e32 v139, v139
	v_add_f32_e32 v137, 1.0, v137
	v_add_f32_e32 v138, 1.0, v138
	v_rcp_f32_e32 v137, v137
	v_rcp_f32_e32 v138, v138
	s_nop 0
	v_cvt_pk_bf16_f32 v137, v137, v138
	v_mul_f32_e32 v138, 0xbfb8aa3b, v148
	v_exp_f32_e32 v138, v138
	v_add_f32_e32 v139, 1.0, v139
	v_rcp_f32_e32 v139, v139
	v_add_f32_e32 v141, 1.0, v141
	v_add_f32_e32 v138, 1.0, v138
	v_rcp_f32_e32 v138, v138
	s_nop 0
	v_cvt_pk_bf16_f32 v138, v138, v139
	v_mul_f32_e32 v139, 0xbfb8aa3b, v144
	v_exp_f32_e32 v139, v139
	v_or_b32_e32 v144, 16, v214
	v_ashrrev_i32_e32 v145, 31, v144
	v_lshlrev_b64 v[144:145], 12, v[144:145]
	v_add_f32_e32 v139, 1.0, v139
	v_lshl_add_u64 v[144:145], s[14:15], 0, v[144:145]
	v_rcp_f32_e32 v139, v139
	v_lshl_add_u64 v[148:149], v[144:145], 0, v[146:147]
	v_rcp_f32_e32 v141, v141
	s_nop 0
	v_cvt_pk_bf16_f32 v139, v139, v141
	global_store_dwordx4 v[148:149], v[136:139], off
	v_pk_add_f32 v[158:159], v[26:27], v[130:131]
	s_nop 0
	v_pk_add_f32 v[136:137], v[94:95], v[134:135]
	v_pk_add_f32 v[138:139], v[92:93], v[132:133]
	v_mul_f32_e32 v136, 0xbfb8aa3b, v136
	v_mul_f32_e32 v138, 0xbfb8aa3b, v138
	v_mul_f32_e32 v139, 0xbfb8aa3b, v139
	v_exp_f32_e32 v136, v136
	v_mul_f32_e32 v137, 0xbfb8aa3b, v137
	v_exp_f32_e32 v138, v138
	v_exp_f32_e32 v139, v139
	v_exp_f32_e32 v137, v137
	v_add_f32_e32 v136, 1.0, v136
	v_add_f32_e32 v138, 1.0, v138
	v_add_f32_e32 v139, 1.0, v139
	v_rcp_f32_e32 v136, v136
	v_add_f32_e32 v137, 1.0, v137
	v_rcp_f32_e32 v138, v138
	v_rcp_f32_e32 v139, v139
	s_nop 0
	v_cvt_pk_bf16_f32 v148, v138, v139
	v_rcp_f32_e32 v137, v137
	s_nop 0
	v_cvt_pk_bf16_f32 v149, v136, v137
	v_mul_f32_e32 v136, 0xbfb8aa3b, v150
	v_exp_f32_e32 v136, v136
	v_mul_f32_e32 v137, 0xbfb8aa3b, v151
	v_exp_f32_e32 v137, v137
	v_add_f32_e32 v136, 1.0, v136
	v_rcp_f32_e32 v136, v136
	v_add_f32_e32 v137, 1.0, v137
	v_rcp_f32_e32 v137, v137
	s_nop 0
	v_cvt_pk_bf16_f32 v150, v136, v137
	v_mul_f32_e32 v136, 0xbfb8aa3b, v152
	v_exp_f32_e32 v136, v136
	v_mul_f32_e32 v137, 0xbfb8aa3b, v153
	v_exp_f32_e32 v137, v137
	v_pk_add_f32 v[152:153], v[74:75], v[130:131]
	v_add_f32_e32 v136, 1.0, v136
	v_rcp_f32_e32 v136, v136
	v_add_f32_e32 v137, 1.0, v137
	v_rcp_f32_e32 v137, v137
	s_nop 0
	v_cvt_pk_bf16_f32 v151, v136, v137
	v_or_b32_e32 v136, 32, v214
	v_ashrrev_i32_e32 v137, 31, v136
	v_lshlrev_b64 v[136:137], 12, v[136:137]
	v_lshl_add_u64 v[136:137], s[14:15], 0, v[136:137]
	v_lshl_add_u64 v[138:139], v[136:137], 0, v[146:147]
	global_store_dwordx4 v[138:139], v[148:151], off
	v_pk_add_f32 v[138:139], v[78:79], v[134:135]
	s_nop 0
	v_pk_add_f32 v[148:149], v[76:77], v[132:133]
	v_mul_f32_e32 v138, 0xbfb8aa3b, v138
	v_mul_f32_e32 v141, 0xbfb8aa3b, v148
	v_mul_f32_e32 v148, 0xbfb8aa3b, v149
	v_exp_f32_e32 v148, v148
	v_exp_f32_e32 v138, v138
	v_mul_f32_e32 v139, 0xbfb8aa3b, v139
	v_exp_f32_e32 v141, v141
	v_exp_f32_e32 v139, v139
	v_add_f32_e32 v148, 1.0, v148
	v_add_f32_e32 v138, 1.0, v138
	v_pk_add_f32 v[150:151], v[72:73], v[128:129]
	v_add_f32_e32 v141, 1.0, v141
	v_rcp_f32_e32 v148, v148
	v_rcp_f32_e32 v138, v138
	v_add_f32_e32 v139, 1.0, v139
	v_rcp_f32_e32 v141, v141
	s_nop 0
	v_cvt_pk_bf16_f32 v148, v141, v148
	v_rcp_f32_e32 v139, v139
	s_nop 0
	v_cvt_pk_bf16_f32 v149, v138, v139
	v_mul_f32_e32 v138, 0xbfb8aa3b, v150
	v_exp_f32_e32 v138, v138
	v_mul_f32_e32 v139, 0xbfb8aa3b, v151
	v_exp_f32_e32 v139, v139
	v_add_f32_e32 v138, 1.0, v138
	v_rcp_f32_e32 v138, v138
	v_add_f32_e32 v139, 1.0, v139
	v_rcp_f32_e32 v139, v139
	s_nop 0
	v_cvt_pk_bf16_f32 v150, v138, v139
	v_mul_f32_e32 v138, 0xbfb8aa3b, v152
	v_exp_f32_e32 v138, v138
	v_mul_f32_e32 v139, 0xbfb8aa3b, v153
	v_exp_f32_e32 v139, v139
	v_add_f32_e32 v138, 1.0, v138
	v_rcp_f32_e32 v138, v138
	v_add_f32_e32 v139, 1.0, v139
	v_rcp_f32_e32 v139, v139
	s_nop 0
	v_cvt_pk_bf16_f32 v151, v138, v139
	v_or_b32_e32 v138, 48, v214
	v_ashrrev_i32_e32 v139, 31, v138
	v_lshlrev_b64 v[138:139], 12, v[138:139]
	v_lshl_add_u64 v[138:139], s[14:15], 0, v[138:139]
	v_lshl_add_u64 v[152:153], v[138:139], 0, v[146:147]
	global_store_dwordx4 v[152:153], v[148:151], off
	v_pk_add_f32 v[152:153], v[56:57], v[128:129]
	s_nop 0
	v_pk_add_f32 v[150:151], v[60:61], v[132:133]
	v_pk_add_f32 v[148:149], v[62:63], v[134:135]
	v_mul_f32_e32 v141, 0xbfb8aa3b, v150
	v_mul_f32_e32 v150, 0xbfb8aa3b, v151
	v_exp_f32_e32 v141, v141
	v_exp_f32_e32 v150, v150
	v_add_f32_e32 v141, 1.0, v141
	v_add_f32_e32 v150, 1.0, v150
	v_rcp_f32_e32 v141, v141
	v_rcp_f32_e32 v150, v150
	s_nop 0
	v_cvt_pk_bf16_f32 v150, v141, v150
	v_mul_f32_e32 v141, 0xbfb8aa3b, v148
	v_mul_f32_e32 v148, 0xbfb8aa3b, v149
	v_exp_f32_e32 v148, v148
	v_exp_f32_e32 v141, v141
	v_add_f32_e32 v148, 1.0, v148
	v_add_f32_e32 v141, 1.0, v141
	v_rcp_f32_e32 v148, v148
	v_rcp_f32_e32 v141, v141
	s_nop 0
	v_cvt_pk_bf16_f32 v151, v141, v148
	v_mul_f32_e32 v148, 0xbfb8aa3b, v153
	v_mul_f32_e32 v141, 0xbfb8aa3b, v152
	v_exp_f32_e32 v148, v148
	v_exp_f32_e32 v141, v141
	v_add_f32_e32 v148, 1.0, v148
	v_add_f32_e32 v141, 1.0, v141
	v_rcp_f32_e32 v148, v148
	v_rcp_f32_e32 v141, v141
	s_nop 0
	v_cvt_pk_bf16_f32 v152, v141, v148
	v_mul_f32_e32 v148, 0xbfb8aa3b, v155
	v_mul_f32_e32 v141, 0xbfb8aa3b, v154
	v_exp_f32_e32 v148, v148
	v_exp_f32_e32 v141, v141
	v_add_f32_e32 v148, 1.0, v148
; __device__ __forceinline__ unsigned cvt_pk_bf16(float lo, float hi) { unsigned r; asm volatile("s_nop 0\n\tv_cvt_pk_bf16_f32 %0, %1, %2\n\ts_nop 1" : "=v"(r) : "v"(lo), "v"(hi)); return r; }
; __device__ __forceinline__ float sigmoidf_(float x) { return __builtin_amdgcn_rcpf(1.f + __expf(-x)); }
;     __device__ __forceinline__ void operator()(f32x4 (&acc)[2][2][4][2], const Unit& u, int wr, int wc, int fr, int fq) const {
;     ...
; #pragma unroll
;             for (int bj = 0; bj < 2; ++bj) { const int col = (u.pn - 12) * 256 + bj * 128 + c8;
;                 const f32x4 b0 = *(const f32x4*)(b_gate + col), b1 = *(const f32x4*)(b_gate + col + 4);
; #pragma unroll
;                 for (int ai = 0; ai < 2; ++ai)
; #pragma unroll
;                     for (int m = 0; m < 4; ++m) { const f32x4 v0 = acc[ai][bj][m][0] + b0, v1 = acc[ai][bj][m][1] + b1;
;                         u32x4 w; w.x = cvt_pk_bf16(sigmoidf_(v0[0]), sigmoidf_(v0[1])); w.y = cvt_pk_bf16(sigmoidf_(v0[2]), sigmoidf_(v0[3]));
;                         w.z = cvt_pk_bf16(sigmoidf_(v1[0]), sigmoidf_(v1[1])); w.w = cvt_pk_bf16(sigmoidf_(v1[2]), sigmoidf_(v1[3]));
;                         *(u32x4*)(gates + (size_t)(row0 + ai * 128 + m * 16) * 2048 + col) = w; } }
	v_add_f32_e32 v141, 1.0, v141
	v_rcp_f32_e32 v148, v148
	v_rcp_f32_e32 v141, v141
	s_nop 0
	v_cvt_pk_bf16_f32 v153, v141, v148
	v_lshl_add_u64 v[148:149], v[142:143], 0, s[0:1]
	v_lshl_add_u64 v[154:155], v[148:149], 0, v[146:147]
	global_store_dwordx4 v[154:155], v[150:153], off
	v_pk_add_f32 v[154:155], v[40:41], v[128:129]
	s_mov_b64 s[0:1], 0x90000
	v_pk_add_f32 v[152:153], v[44:45], v[132:133]
	v_pk_add_f32 v[150:151], v[46:47], v[134:135]
	v_mul_f32_e32 v141, 0xbfb8aa3b, v152
	v_mul_f32_e32 v152, 0xbfb8aa3b, v153
	v_exp_f32_e32 v141, v141
	v_exp_f32_e32 v152, v152
	v_add_f32_e32 v141, 1.0, v141
	v_add_f32_e32 v152, 1.0, v152
	v_rcp_f32_e32 v141, v141
	v_rcp_f32_e32 v152, v152
	s_nop 0
	v_cvt_pk_bf16_f32 v152, v141, v152
	v_mul_f32_e32 v141, 0xbfb8aa3b, v150
	v_mul_f32_e32 v150, 0xbfb8aa3b, v151
	v_exp_f32_e32 v150, v150
	v_exp_f32_e32 v141, v141
	v_add_f32_e32 v150, 1.0, v150
	v_add_f32_e32 v141, 1.0, v141
	v_rcp_f32_e32 v150, v150
	v_rcp_f32_e32 v141, v141
	s_nop 0
	v_cvt_pk_bf16_f32 v153, v141, v150
	v_mul_f32_e32 v150, 0xbfb8aa3b, v155
	v_mul_f32_e32 v141, 0xbfb8aa3b, v154
	v_exp_f32_e32 v150, v150
	v_exp_f32_e32 v141, v141
	v_add_f32_e32 v150, 1.0, v150
	v_add_f32_e32 v141, 1.0, v141
	v_rcp_f32_e32 v150, v150
	v_rcp_f32_e32 v141, v141
	s_nop 0
	v_cvt_pk_bf16_f32 v154, v141, v150
	v_mul_f32_e32 v150, 0xbfb8aa3b, v157
	v_mul_f32_e32 v141, 0xbfb8aa3b, v156
	v_exp_f32_e32 v150, v150
	v_exp_f32_e32 v141, v141
	v_add_f32_e32 v150, 1.0, v150
	v_add_f32_e32 v141, 1.0, v141
	v_rcp_f32_e32 v150, v150
	v_rcp_f32_e32 v141, v141
	s_nop 0
	v_cvt_pk_bf16_f32 v155, v141, v150
	v_lshl_add_u64 v[150:151], v[142:143], 0, s[0:1]
	v_lshl_add_u64 v[156:157], v[150:151], 0, v[146:147]
	global_store_dwordx4 v[156:157], v[152:155], off
	v_pk_add_f32 v[156:157], v[24:25], v[128:129]
	s_mov_b64 s[0:1], 0xa0000
	v_pk_add_f32 v[154:155], v[28:29], v[132:133]
	v_pk_add_f32 v[152:153], v[30:31], v[134:135]
	v_mul_f32_e32 v141, 0xbfb8aa3b, v154
	v_mul_f32_e32 v154, 0xbfb8aa3b, v155
	v_exp_f32_e32 v141, v141
	v_exp_f32_e32 v154, v154
	v_pk_add_f32 v[132:133], v[12:13], v[132:133]
	v_pk_add_f32 v[134:135], v[14:15], v[134:135]
	v_add_f32_e32 v141, 1.0, v141
	v_add_f32_e32 v154, 1.0, v154
	v_rcp_f32_e32 v141, v141
	v_rcp_f32_e32 v154, v154
	s_nop 0
	v_cvt_pk_bf16_f32 v154, v141, v154
	v_mul_f32_e32 v141, 0xbfb8aa3b, v152
	v_mul_f32_e32 v152, 0xbfb8aa3b, v153
	v_exp_f32_e32 v152, v152
	v_exp_f32_e32 v141, v141
	v_add_f32_e32 v152, 1.0, v152
	v_add_f32_e32 v141, 1.0, v141
	v_rcp_f32_e32 v152, v152
	v_rcp_f32_e32 v141, v141
	s_nop 0
	v_cvt_pk_bf16_f32 v155, v141, v152
	v_mul_f32_e32 v152, 0xbfb8aa3b, v157
	v_mul_f32_e32 v141, 0xbfb8aa3b, v156
	v_exp_f32_e32 v152, v152
	v_exp_f32_e32 v141, v141
	v_add_f32_e32 v152, 1.0, v152
	v_add_f32_e32 v141, 1.0, v141
	v_rcp_f32_e32 v152, v152
	v_rcp_f32_e32 v141, v141
	s_nop 0
	v_cvt_pk_bf16_f32 v156, v141, v152
	v_mul_f32_e32 v152, 0xbfb8aa3b, v159
	v_mul_f32_e32 v141, 0xbfb8aa3b, v158
	v_exp_f32_e32 v152, v152
	v_exp_f32_e32 v141, v141
	v_add_f32_e32 v152, 1.0, v152
	v_add_f32_e32 v141, 1.0, v141
	v_rcp_f32_e32 v152, v152
	v_rcp_f32_e32 v141, v141
	s_nop 0
	v_cvt_pk_bf16_f32 v157, v141, v152
	v_lshl_add_u64 v[152:153], v[142:143], 0, s[0:1]
	v_lshl_add_u64 v[158:159], v[152:153], 0, v[146:147]
	global_store_dwordx4 v[158:159], v[154:157], off
	s_mov_b64 s[0:1], 0xb0000
	v_ashrrev_i32_e32 v141, 31, v140
	v_pk_add_f32 v[154:155], v[10:11], v[130:131]
	v_pk_add_f32 v[130:131], v[8:9], v[128:129]
	v_mul_f32_e32 v128, 0xbfb8aa3b, v132
	v_mul_f32_e32 v129, 0xbfb8aa3b, v133
	v_exp_f32_e32 v128, v128
	v_exp_f32_e32 v129, v129
	v_mul_f32_e32 v132, 0xbfb8aa3b, v135
	v_mul_f32_e32 v130, 0xbfb8aa3b, v130
	v_add_f32_e32 v128, 1.0, v128
	v_add_f32_e32 v129, 1.0, v129
	v_rcp_f32_e32 v128, v128
	v_rcp_f32_e32 v129, v129
	s_nop 0
	v_cvt_pk_bf16_f32 v128, v128, v129
	v_mul_f32_e32 v129, 0xbfb8aa3b, v134
	v_mul_f32_e32 v131, 0xbfb8aa3b, v131
	v_exp_f32_e32 v129, v129
	v_exp_f32_e32 v132, v132
	v_exp_f32_e32 v130, v130
	v_exp_f32_e32 v131, v131
	v_add_f32_e32 v129, 1.0, v129
	v_add_f32_e32 v132, 1.0, v132
	v_add_f32_e32 v130, 1.0, v130
	v_add_f32_e32 v131, 1.0, v131
	v_rcp_f32_e32 v129, v129
	v_rcp_f32_e32 v132, v132
	v_rcp_f32_e32 v130, v130
	v_rcp_f32_e32 v131, v131
	s_nop 0
	v_cvt_pk_bf16_f32 v129, v129, v132
	v_cvt_pk_bf16_f32 v130, v130, v131
	v_mul_f32_e32 v131, 0xbfb8aa3b, v154
	v_mul_f32_e32 v132, 0xbfb8aa3b, v155
	v_exp_f32_e32 v131, v131
	v_exp_f32_e32 v132, v132
	v_lshl_add_u64 v[154:155], v[142:143], 0, s[0:1]
	s_mov_b64 s[0:1], 0
	v_add_f32_e32 v131, 1.0, v131
	v_add_f32_e32 v132, 1.0, v132
	v_rcp_f32_e32 v131, v131
	v_rcp_f32_e32 v132, v132
	s_nop 0
	v_cvt_pk_bf16_f32 v131, v131, v132
	v_lshl_add_u64 v[132:133], v[154:155], 0, v[146:147]
	global_store_dwordx4 v[132:133], v[128:131], off
	v_lshl_add_u64 v[132:133], v[140:141], 2, s[48:49]
	global_load_dwordx4 v[128:131], v[132:133], off offset:16
	s_nop 0
	global_load_dwordx4 v[132:135], v[132:133], off
	v_lshlrev_b64 v[140:141], 1, v[140:141]
	v_lshl_add_u64 v[142:143], v[142:143], 0, v[140:141]
	v_lshl_add_u64 v[136:137], v[136:137], 0, v[140:141]
	s_waitcnt vmcnt(0)
; __device__ __forceinline__ unsigned cvt_pk_bf16(float lo, float hi) { unsigned r; asm volatile("s_nop 0\n\tv_cvt_pk_bf16_f32 %0, %1, %2\n\ts_nop 1" : "=v"(r) : "v"(lo), "v"(hi)); return r; }
; __device__ __forceinline__ float sigmoidf_(float x) { return __builtin_amdgcn_rcpf(1.f + __expf(-x)); }
;     __device__ __forceinline__ void operator()(f32x4 (&acc)[2][2][4][2], const Unit& u, int wr, int wc, int fr, int fq) const {
;     ...
; #pragma unroll
;             for (int bj = 0; bj < 2; ++bj) { const int col = (u.pn - 12) * 256 + bj * 128 + c8;
;                 const f32x4 b0 = *(const f32x4*)(b_gate + col), b1 = *(const f32x4*)(b_gate + col + 4);
; #pragma unroll
;                 for (int ai = 0; ai < 2; ++ai)
; #pragma unroll
;                     for (int m = 0; m < 4; ++m) { const f32x4 v0 = acc[ai][bj][m][0] + b0, v1 = acc[ai][bj][m][1] + b1;
;                         u32x4 w; w.x = cvt_pk_bf16(sigmoidf_(v0[0]), sigmoidf_(v0[1])); w.y = cvt_pk_bf16(sigmoidf_(v0[2]), sigmoidf_(v0[3]));
;                         w.z = cvt_pk_bf16(sigmoidf_(v1[0]), sigmoidf_(v1[1])); w.w = cvt_pk_bf16(sigmoidf_(v1[2]), sigmoidf_(v1[3]));
;                         *(u32x4*)(gates + (size_t)(row0 + ai * 128 + m * 16) * 2048 + col) = w; } }
	v_pk_add_f32 v[158:159], v[112:113], v[128:129]
	v_pk_add_f32 v[146:147], v[118:119], v[134:135]
	v_pk_add_f32 v[156:157], v[116:117], v[132:133]
	v_mul_f32_e32 v146, 0xbfb8aa3b, v146
	v_mul_f32_e32 v156, 0xbfb8aa3b, v156
	v_mul_f32_e32 v157, 0xbfb8aa3b, v157
	v_mul_f32_e32 v147, 0xbfb8aa3b, v147
	v_exp_f32_e32 v156, v156
	v_exp_f32_e32 v157, v157
	v_exp_f32_e32 v146, v146
	v_exp_f32_e32 v147, v147
	v_add_f32_e32 v156, 1.0, v156
	v_add_f32_e32 v157, 1.0, v157
	v_add_f32_e32 v146, 1.0, v146
	v_add_f32_e32 v147, 1.0, v147
	v_rcp_f32_e32 v156, v156
	v_rcp_f32_e32 v157, v157
	v_rcp_f32_e32 v146, v146
	v_rcp_f32_e32 v147, v147
	s_nop 0
	v_cvt_pk_bf16_f32 v156, v156, v157
	v_cvt_pk_bf16_f32 v157, v146, v147
	v_mul_f32_e32 v146, 0xbfb8aa3b, v158
	v_mul_f32_e32 v147, 0xbfb8aa3b, v159
	v_exp_f32_e32 v146, v146
	v_exp_f32_e32 v147, v147
	v_pk_add_f32 v[160:161], v[114:115], v[130:131]
	v_add_f32_e32 v146, 1.0, v146
	v_add_f32_e32 v147, 1.0, v147
	v_rcp_f32_e32 v146, v146
	v_rcp_f32_e32 v147, v147
	s_nop 0
	v_cvt_pk_bf16_f32 v158, v146, v147
	v_mul_f32_e32 v146, 0xbfb8aa3b, v160
	v_mul_f32_e32 v147, 0xbfb8aa3b, v161
	v_exp_f32_e32 v146, v146
	v_exp_f32_e32 v147, v147
	v_pk_add_f32 v[160:161], v[98:99], v[130:131]
	v_add_f32_e32 v146, 1.0, v146
	v_add_f32_e32 v147, 1.0, v147
	v_rcp_f32_e32 v146, v146
	v_rcp_f32_e32 v147, v147
	s_nop 0
	v_cvt_pk_bf16_f32 v159, v146, v147
	global_store_dwordx4 v[142:143], v[156:159], off
	v_pk_add_f32 v[142:143], v[102:103], v[134:135]
	v_pk_add_f32 v[146:147], v[100:101], v[132:133]
	v_mul_f32_e32 v142, 0xbfb8aa3b, v142
	v_mul_f32_e32 v143, 0xbfb8aa3b, v143
	v_mul_f32_e32 v146, 0xbfb8aa3b, v146
	v_mul_f32_e32 v147, 0xbfb8aa3b, v147
	v_exp_f32_e32 v142, v142
	v_exp_f32_e32 v143, v143
	v_exp_f32_e32 v146, v146
	v_exp_f32_e32 v147, v147
	v_add_f32_e32 v142, 1.0, v142
	v_add_f32_e32 v143, 1.0, v143
	v_pk_add_f32 v[158:159], v[96:97], v[128:129]
	v_add_f32_e32 v146, 1.0, v146
	v_add_f32_e32 v147, 1.0, v147
	v_rcp_f32_e32 v142, v142
	v_rcp_f32_e32 v143, v143
	v_rcp_f32_e32 v146, v146
	v_rcp_f32_e32 v147, v147
	s_nop 0
	v_cvt_pk_bf16_f32 v156, v146, v147
	v_cvt_pk_bf16_f32 v157, v142, v143
	v_mul_f32_e32 v142, 0xbfb8aa3b, v158
	v_mul_f32_e32 v143, 0xbfb8aa3b, v159
	v_exp_f32_e32 v142, v142
	v_exp_f32_e32 v143, v143
	v_pk_add_f32 v[146:147], v[82:83], v[130:131]
	v_add_f32_e32 v142, 1.0, v142
	v_add_f32_e32 v143, 1.0, v143
	v_rcp_f32_e32 v142, v142
	v_rcp_f32_e32 v143, v143
	s_nop 0
	v_cvt_pk_bf16_f32 v158, v142, v143
	v_mul_f32_e32 v142, 0xbfb8aa3b, v160
	v_mul_f32_e32 v143, 0xbfb8aa3b, v161
	v_exp_f32_e32 v142, v142
	v_exp_f32_e32 v143, v143
	v_add_f32_e32 v142, 1.0, v142
	v_add_f32_e32 v143, 1.0, v143
	v_rcp_f32_e32 v142, v142
	v_rcp_f32_e32 v143, v143
	s_nop 0
	v_cvt_pk_bf16_f32 v159, v142, v143
	v_lshl_add_u64 v[142:143], v[144:145], 0, v[140:141]
	global_store_dwordx4 v[142:143], v[156:159], off
	v_pk_add_f32 v[142:143], v[84:85], v[132:133]
	v_pk_add_f32 v[144:145], v[86:87], v[134:135]
	v_mul_f32_e32 v142, 0xbfb8aa3b, v142
	v_mul_f32_e32 v143, 0xbfb8aa3b, v143
	v_exp_f32_e32 v142, v142
	v_exp_f32_e32 v143, v143
	v_pk_add_f32 v[156:157], v[80:81], v[128:129]
	v_add_f32_e32 v142, 1.0, v142
	v_add_f32_e32 v143, 1.0, v143
	v_rcp_f32_e32 v142, v142
	v_rcp_f32_e32 v143, v143
	s_nop 0
	v_cvt_pk_bf16_f32 v142, v142, v143
	v_mul_f32_e32 v143, 0xbfb8aa3b, v144
	v_mul_f32_e32 v144, 0xbfb8aa3b, v145
	v_exp_f32_e32 v143, v143
	v_exp_f32_e32 v144, v144
	v_mul_f32_e32 v145, 0xbfb8aa3b, v157
	v_exp_f32_e32 v145, v145
	v_add_f32_e32 v143, 1.0, v143
	v_add_f32_e32 v144, 1.0, v144
	v_rcp_f32_e32 v143, v143
	v_rcp_f32_e32 v144, v144
	s_nop 0
	v_cvt_pk_bf16_f32 v143, v143, v144
	v_mul_f32_e32 v144, 0xbfb8aa3b, v156
	v_exp_f32_e32 v144, v144
	v_add_f32_e32 v145, 1.0, v145
	v_rcp_f32_e32 v145, v145
	v_add_f32_e32 v144, 1.0, v144
	v_rcp_f32_e32 v144, v144
	s_nop 0
	v_cvt_pk_bf16_f32 v144, v144, v145
	v_mul_f32_e32 v145, 0xbfb8aa3b, v146
	v_exp_f32_e32 v145, v145
	v_mul_f32_e32 v146, 0xbfb8aa3b, v147
	v_exp_f32_e32 v146, v146
	v_add_f32_e32 v145, 1.0, v145
	v_rcp_f32_e32 v145, v145
	v_add_f32_e32 v146, 1.0, v146
	v_rcp_f32_e32 v146, v146
	s_nop 0
	v_cvt_pk_bf16_f32 v145, v145, v146
	global_store_dwordx4 v[136:137], v[142:145], off
	v_pk_add_f32 v[136:137], v[70:71], v[134:135]
	v_pk_add_f32 v[146:147], v[66:67], v[130:131]
	v_pk_add_f32 v[142:143], v[68:69], v[132:133]
	v_mul_f32_e32 v136, 0xbfb8aa3b, v136
	v_mul_f32_e32 v142, 0xbfb8aa3b, v142
	v_mul_f32_e32 v143, 0xbfb8aa3b, v143
	v_mul_f32_e32 v137, 0xbfb8aa3b, v137
	v_exp_f32_e32 v142, v142
	v_exp_f32_e32 v143, v143
	v_exp_f32_e32 v136, v136
	v_exp_f32_e32 v137, v137
	v_add_f32_e32 v142, 1.0, v142
	v_add_f32_e32 v143, 1.0, v143
	v_add_f32_e32 v136, 1.0, v136
	v_add_f32_e32 v137, 1.0, v137
	v_pk_add_f32 v[144:145], v[64:65], v[128:129]
	v_rcp_f32_e32 v142, v142
	v_rcp_f32_e32 v143, v143
	v_rcp_f32_e32 v136, v136
	v_rcp_f32_e32 v137, v137
	s_nop 0
	v_cvt_pk_bf16_f32 v142, v142, v143
	v_cvt_pk_bf16_f32 v143, v136, v137
	v_mul_f32_e32 v136, 0xbfb8aa3b, v144
	v_mul_f32_e32 v137, 0xbfb8aa3b, v145
	v_exp_f32_e32 v136, v136
	v_exp_f32_e32 v137, v137
	v_add_f32_e32 v136, 1.0, v136
	v_add_f32_e32 v137, 1.0, v137
	v_rcp_f32_e32 v136, v136
	v_rcp_f32_e32 v137, v137
	s_nop 0
	v_cvt_pk_bf16_f32 v144, v136, v137
	v_mul_f32_e32 v136, 0xbfb8aa3b, v146
	v_mul_f32_e32 v137, 0xbfb8aa3b, v147
	v_exp_f32_e32 v136, v136
	v_exp_f32_e32 v137, v137
	v_add_f32_e32 v136, 1.0, v136
	v_add_f32_e32 v137, 1.0, v137
	v_rcp_f32_e32 v136, v136
	v_rcp_f32_e32 v137, v137
	s_nop 0
	v_cvt_pk_bf16_f32 v145, v136, v137
	v_lshl_add_u64 v[136:137], v[138:139], 0, v[140:141]
	global_store_dwordx4 v[136:137], v[142:145], off
; __device__ __forceinline__ unsigned cvt_pk_bf16(float lo, float hi) { unsigned r; asm volatile("s_nop 0\n\tv_cvt_pk_bf16_f32 %0, %1, %2\n\ts_nop 1" : "=v"(r) : "v"(lo), "v"(hi)); return r; }
; __device__ __forceinline__ float sigmoidf_(float x) { return __builtin_amdgcn_rcpf(1.f + __expf(-x)); }
;     __device__ __forceinline__ void operator()(f32x4 (&acc)[2][2][4][2], const Unit& u, int wr, int wc, int fr, int fq) const {
;     ...
; #pragma unroll
;             for (int bj = 0; bj < 2; ++bj) { const int col = (u.pn - 12) * 256 + bj * 128 + c8;
;                 const f32x4 b0 = *(const f32x4*)(b_gate + col), b1 = *(const f32x4*)(b_gate + col + 4);
; #pragma unroll
;                 for (int ai = 0; ai < 2; ++ai)
; #pragma unroll
;                     for (int m = 0; m < 4; ++m) { const f32x4 v0 = acc[ai][bj][m][0] + b0, v1 = acc[ai][bj][m][1] + b1;
;                         u32x4 w; w.x = cvt_pk_bf16(sigmoidf_(v0[0]), sigmoidf_(v0[1])); w.y = cvt_pk_bf16(sigmoidf_(v0[2]), sigmoidf_(v0[3]));
;                         w.z = cvt_pk_bf16(sigmoidf_(v1[0]), sigmoidf_(v1[1])); w.w = cvt_pk_bf16(sigmoidf_(v1[2]), sigmoidf_(v1[3]));
;                         *(u32x4*)(gates + (size_t)(row0 + ai * 128 + m * 16) * 2048 + col) = w; } }
	v_pk_add_f32 v[136:137], v[52:53], v[132:133]
	v_pk_add_f32 v[138:139], v[54:55], v[134:135]
	v_mul_f32_e32 v136, 0xbfb8aa3b, v136
	v_mul_f32_e32 v137, 0xbfb8aa3b, v137
	v_exp_f32_e32 v136, v136
	v_exp_f32_e32 v137, v137
	v_pk_add_f32 v[144:145], v[48:49], v[128:129]
	v_pk_add_f32 v[142:143], v[50:51], v[130:131]
	v_add_f32_e32 v136, 1.0, v136
	v_add_f32_e32 v137, 1.0, v137
	v_rcp_f32_e32 v136, v136
	v_rcp_f32_e32 v137, v137
	s_nop 0
	v_cvt_pk_bf16_f32 v136, v136, v137
	v_mul_f32_e32 v137, 0xbfb8aa3b, v138
	v_mul_f32_e32 v138, 0xbfb8aa3b, v139
	v_exp_f32_e32 v137, v137
	v_exp_f32_e32 v138, v138
	v_mul_f32_e32 v139, 0xbfb8aa3b, v145
	v_exp_f32_e32 v139, v139
	v_add_f32_e32 v137, 1.0, v137
	v_add_f32_e32 v138, 1.0, v138
	v_rcp_f32_e32 v137, v137
	v_rcp_f32_e32 v138, v138
	s_nop 0
	v_cvt_pk_bf16_f32 v137, v137, v138
	v_mul_f32_e32 v138, 0xbfb8aa3b, v144
	v_exp_f32_e32 v138, v138
	v_add_f32_e32 v139, 1.0, v139
	v_rcp_f32_e32 v139, v139
	v_pk_add_f32 v[144:145], v[32:33], v[128:129]
	v_add_f32_e32 v138, 1.0, v138
	v_rcp_f32_e32 v138, v138
	s_nop 0
	v_cvt_pk_bf16_f32 v138, v138, v139
	v_mul_f32_e32 v139, 0xbfb8aa3b, v142
	v_mul_f32_e32 v142, 0xbfb8aa3b, v143
	v_exp_f32_e32 v139, v139
	v_exp_f32_e32 v142, v142
	v_add_f32_e32 v139, 1.0, v139
	v_add_f32_e32 v142, 1.0, v142
	v_rcp_f32_e32 v139, v139
	v_rcp_f32_e32 v142, v142
	s_nop 0
	v_cvt_pk_bf16_f32 v139, v139, v142
	v_lshl_add_u64 v[142:143], v[148:149], 0, v[140:141]
	global_store_dwordx4 v[142:143], v[136:139], off
	v_pk_add_f32 v[142:143], v[34:35], v[130:131]
	s_nop 0
	v_pk_add_f32 v[136:137], v[36:37], v[132:133]
	v_pk_add_f32 v[138:139], v[38:39], v[134:135]
	v_mul_f32_e32 v136, 0xbfb8aa3b, v136
	v_mul_f32_e32 v137, 0xbfb8aa3b, v137
	v_exp_f32_e32 v136, v136
	v_exp_f32_e32 v137, v137
	v_add_f32_e32 v136, 1.0, v136
	v_add_f32_e32 v137, 1.0, v137
	v_rcp_f32_e32 v136, v136
	v_rcp_f32_e32 v137, v137
	s_nop 0
	v_cvt_pk_bf16_f32 v136, v136, v137
	v_mul_f32_e32 v137, 0xbfb8aa3b, v138
	v_mul_f32_e32 v138, 0xbfb8aa3b, v139
	v_exp_f32_e32 v137, v137
	v_exp_f32_e32 v138, v138
	v_mul_f32_e32 v139, 0xbfb8aa3b, v145
	v_exp_f32_e32 v139, v139
	v_add_f32_e32 v137, 1.0, v137
	v_add_f32_e32 v138, 1.0, v138
	v_rcp_f32_e32 v137, v137
	v_rcp_f32_e32 v138, v138
	s_nop 0
	v_cvt_pk_bf16_f32 v137, v137, v138
	v_mul_f32_e32 v138, 0xbfb8aa3b, v144
	v_exp_f32_e32 v138, v138
	v_add_f32_e32 v139, 1.0, v139
	v_rcp_f32_e32 v139, v139
	v_pk_add_f32 v[144:145], v[16:17], v[128:129]
	v_add_f32_e32 v138, 1.0, v138
	v_rcp_f32_e32 v138, v138
	s_nop 0
	v_cvt_pk_bf16_f32 v138, v138, v139
	v_mul_f32_e32 v139, 0xbfb8aa3b, v142
	v_mul_f32_e32 v142, 0xbfb8aa3b, v143
	v_exp_f32_e32 v139, v139
	v_exp_f32_e32 v142, v142
	v_add_f32_e32 v139, 1.0, v139
	v_add_f32_e32 v142, 1.0, v142
	v_rcp_f32_e32 v139, v139
	v_rcp_f32_e32 v142, v142
	s_nop 0
	v_cvt_pk_bf16_f32 v139, v139, v142
	v_lshl_add_u64 v[142:143], v[150:151], 0, v[140:141]
	global_store_dwordx4 v[142:143], v[136:139], off
	v_pk_add_f32 v[142:143], v[18:19], v[130:131]
	s_nop 0
	v_pk_add_f32 v[136:137], v[20:21], v[132:133]
	v_pk_add_f32 v[138:139], v[22:23], v[134:135]
	v_mul_f32_e32 v136, 0xbfb8aa3b, v136
	v_mul_f32_e32 v137, 0xbfb8aa3b, v137
	v_exp_f32_e32 v136, v136
	v_exp_f32_e32 v137, v137
	v_pk_add_f32 v[132:133], v[4:5], v[132:133]
	v_pk_add_f32 v[134:135], v[6:7], v[134:135]
	v_add_f32_e32 v136, 1.0, v136
	v_add_f32_e32 v137, 1.0, v137
	v_rcp_f32_e32 v136, v136
	v_rcp_f32_e32 v137, v137
	s_nop 0
	v_cvt_pk_bf16_f32 v136, v136, v137
	v_mul_f32_e32 v137, 0xbfb8aa3b, v138
	v_mul_f32_e32 v138, 0xbfb8aa3b, v139
	v_exp_f32_e32 v137, v137
	v_exp_f32_e32 v138, v138
	v_mul_f32_e32 v139, 0xbfb8aa3b, v145
	v_exp_f32_e32 v139, v139
	v_add_f32_e32 v137, 1.0, v137
	v_add_f32_e32 v138, 1.0, v138
	v_rcp_f32_e32 v137, v137
	v_rcp_f32_e32 v138, v138
	s_nop 0
	v_cvt_pk_bf16_f32 v137, v137, v138
	v_mul_f32_e32 v138, 0xbfb8aa3b, v144
	v_exp_f32_e32 v138, v138
	v_add_f32_e32 v139, 1.0, v139
	v_rcp_f32_e32 v139, v139
	v_add_f32_e32 v138, 1.0, v138
	v_rcp_f32_e32 v138, v138
	s_nop 0
	v_cvt_pk_bf16_f32 v138, v138, v139
	v_mul_f32_e32 v139, 0xbfb8aa3b, v142
	v_mul_f32_e32 v142, 0xbfb8aa3b, v143
	v_exp_f32_e32 v139, v139
	v_exp_f32_e32 v142, v142
	v_add_f32_e32 v139, 1.0, v139
	v_add_f32_e32 v142, 1.0, v142
	v_rcp_f32_e32 v139, v139
	v_rcp_f32_e32 v142, v142
	s_nop 0
	v_cvt_pk_bf16_f32 v139, v139, v142
	v_lshl_add_u64 v[142:143], v[152:153], 0, v[140:141]
	global_store_dwordx4 v[142:143], v[136:139], off
	s_nop 1
	v_pk_add_f32 v[136:137], v[2:3], v[130:131]
	v_pk_add_f32 v[130:131], v[0:1], v[128:129]
	v_mul_f32_e32 v128, 0xbfb8aa3b, v132
	v_mul_f32_e32 v129, 0xbfb8aa3b, v133
	v_exp_f32_e32 v128, v128
	v_exp_f32_e32 v129, v129
	v_mul_f32_e32 v132, 0xbfb8aa3b, v135
	v_mul_f32_e32 v130, 0xbfb8aa3b, v130
	v_add_f32_e32 v128, 1.0, v128
	v_add_f32_e32 v129, 1.0, v129
	v_rcp_f32_e32 v128, v128
	v_rcp_f32_e32 v129, v129
	s_nop 0
	v_cvt_pk_bf16_f32 v128, v128, v129
	v_mul_f32_e32 v129, 0xbfb8aa3b, v134
	v_mul_f32_e32 v131, 0xbfb8aa3b, v131
	v_exp_f32_e32 v129, v129
	v_exp_f32_e32 v132, v132
	v_exp_f32_e32 v130, v130
	v_exp_f32_e32 v131, v131
	v_add_f32_e32 v129, 1.0, v129
	v_add_f32_e32 v132, 1.0, v132
	v_add_f32_e32 v130, 1.0, v130
	v_add_f32_e32 v131, 1.0, v131
	v_rcp_f32_e32 v129, v129
	v_rcp_f32_e32 v132, v132
	v_rcp_f32_e32 v130, v130
	v_rcp_f32_e32 v131, v131
	s_nop 0
	v_cvt_pk_bf16_f32 v129, v129, v132
	v_cvt_pk_bf16_f32 v130, v130, v131
	v_mul_f32_e32 v131, 0xbfb8aa3b, v136
	v_mul_f32_e32 v132, 0xbfb8aa3b, v137
	v_exp_f32_e32 v131, v131
	v_exp_f32_e32 v132, v132
	v_add_f32_e32 v131, 1.0, v131
	v_add_f32_e32 v132, 1.0, v132
	v_rcp_f32_e32 v131, v131
	v_rcp_f32_e32 v132, v132
	s_nop 0
	v_cvt_pk_bf16_f32 v131, v131, v132
	v_lshl_add_u64 v[132:133], v[154:155], 0, v[140:141]
	global_store_dwordx4 v[132:133], v[128:131], off

; #define PG8_STAGE(bufoff, gbase, voff) do { _Pragma("unroll") for (int _i = 0; _i < 2; ++_i) \
;         __builtin_amdgcn_global_load_lds((const unsigned*)((const char*)(gbase) + (voff)[_i]), (PG8_LAS unsigned*)(lds + (bufoff) + ldsw + _i * 8192), 16, 0, 0); } while (0)
; #define PG8_LDA(dst, b, h) do { _Pragma("unroll") for (int m = 0; m < 4; ++m) _Pragma("unroll") for (int k = 0; k < 2; ++k) dst[m][k] = *(const PG8_LAS bf16x8*)(lds + PG8_SA(b, h) + aoff + m * 2048 + k * 1024); } while (0)
; #define PG8_LDB(dst, b, h) do { _Pragma("unroll") for (int n = 0; n < 2; ++n) _Pragma("unroll") for (int k = 0; k < 2; ++k) dst[n][k] = *(const PG8_LAS bf16x8*)(lds + PG8_SB(b, h) + boff + n * 2048 + k * 1024); } while (0)
; #define PG8_MMA(ai, bj, At, Bt) do { __builtin_amdgcn_s_setprio(1); _Pragma("unroll") for (int m = 0; m < 4; ++m) _Pragma("unroll") for (int n = 0; n < 2; ++n) _Pragma("unroll") for (int k = 0; k < 2; ++k) \
;         acc[ai][bj][m][n] = __builtin_amdgcn_mfma_f32_16x16x32_bf16(Bt[n][k], At[m][k], acc[ai][bj][m][n], 0, 0, 0); __builtin_amdgcn_s_setprio(0); } while (0)
; #define PG8_WAIT_L(n) asm volatile("s_waitcnt lgkmcnt(" #n ")" ::: "memory")
; #define PG8_BAR __builtin_amdgcn_s_barrier()
; #define PG8_SCHED __builtin_amdgcn_sched_barrier(0)
; template <class Epi, class Sched>
; __device__ __forceinline__ void gemm_phase(PG8_LAS unsigned char* lds, const Gemm g, const Sched& S, const Epi& E, int tid_in) {
;     ...
;             PG8_LDB(B0, 0, 0); PG8_SCHED; PG8_LDA(At, 0, 0); PG8_STAGE(PG8_SA(1, 1), a1 + hstep, voffA);
;             PG8_WAIT_L(8); PG8_BAR; PG8_WAIT_L(0); PG8_MMA(0, 0, At, B0); PG8_BAR; PG8_SCHED;
;             PG8_LDB(B1, 0, 1); PG8_STAGE(PG8_SB(0, 0), b2, voffB);
;             PG8_BAR; PG8_WAIT_L(0); PG8_MMA(0, 1, At, B1); PG8_BAR;
;             PG8_LDA(At, 0, 1); PG8_STAGE(PG8_SA(0, 0), a2, voffA);
;             PG8_BAR; PG8_WAIT_L(0); PG8_MMA(1, 0, At, B0); PG8_BAR; PG8_SCHED;
.LBB0_696:
	s_add_u32 s18, s16, 0xfffc0080
	s_addc_u32 s19, s17, -1
	s_add_i32 s43, 0, 0x10000
	v_add_u32_e32 v154, s43, v143
	ds_read_b128 v[138:141], v154
	ds_read_b128 v[146:149], v154 offset:1024
	ds_read_b128 v[150:153], v154 offset:2048
	ds_read_b128 v[154:157], v154 offset:3072
	s_cmp_eq_u32 s42, 12
	s_cselect_b32 s21, s5, s19
	s_cselect_b32 s20, s7, s18
	s_cselect_b32 s19, s9, s41
	s_cselect_b32 s18, s11, s40
	v_lshl_add_u64 v[190:191], s[16:17], 0, v[134:135]
	s_add_i32 m0, s28, 0xc000
	ds_read_b128 v[158:161], v145
	ds_read_b128 v[162:165], v145 offset:1024
	ds_read_b128 v[166:169], v145 offset:2048
	ds_read_b128 v[170:173], v145 offset:3072
	ds_read_b128 v[174:177], v145 offset:4096
	ds_read_b128 v[178:181], v145 offset:5120
	ds_read_b128 v[182:185], v145 offset:6144
	ds_read_b128 v[186:189], v145 offset:7168
	global_load_lds_dwordx4 v[190:191], off
	s_add_i32 m0, s28, 0xe000
	v_lshl_add_u64 v[190:191], s[16:17], 0, v[136:137]
	global_load_lds_dwordx4 v[190:191], off
	s_waitcnt lgkmcnt(8)
	s_barrier
	s_waitcnt lgkmcnt(0)
	s_waitcnt lgkmcnt(0)
	v_mfma_f32_16x16x32_bf16 v[124:127], v[138:141], v[158:161], v[124:127]
	v_mfma_f32_16x16x32_bf16 v[120:123], v[150:153], v[158:161], v[120:123]
	v_mfma_f32_16x16x32_bf16 v[112:115], v[138:141], v[166:169], v[112:115]
	v_mfma_f32_16x16x32_bf16 v[104:107], v[150:153], v[166:169], v[104:107]
	v_mfma_f32_16x16x32_bf16 v[96:99], v[138:141], v[174:177], v[96:99]
	v_mfma_f32_16x16x32_bf16 v[88:91], v[150:153], v[174:177], v[88:91]
	v_mfma_f32_16x16x32_bf16 v[80:83], v[138:141], v[182:185], v[80:83]
	v_mfma_f32_16x16x32_bf16 v[72:75], v[150:153], v[182:185], v[72:75]
	v_mfma_f32_16x16x32_bf16 v[124:127], v[146:149], v[162:165], v[124:127]
	v_mfma_f32_16x16x32_bf16 v[120:123], v[154:157], v[162:165], v[120:123]
	v_mfma_f32_16x16x32_bf16 v[112:115], v[146:149], v[170:173], v[112:115]
	v_mfma_f32_16x16x32_bf16 v[104:107], v[154:157], v[170:173], v[104:107]
	v_mfma_f32_16x16x32_bf16 v[96:99], v[146:149], v[178:181], v[96:99]
	v_mfma_f32_16x16x32_bf16 v[88:91], v[154:157], v[178:181], v[88:91]
	v_mfma_f32_16x16x32_bf16 v[80:83], v[146:149], v[186:189], v[80:83]
	v_mfma_f32_16x16x32_bf16 v[72:75], v[154:157], v[186:189], v[72:75]
	s_barrier
	s_add_i32 s46, 0, 0x14000
	v_add_u32_e32 v190, s46, v143
	s_add_i32 s43, s43, s27
	ds_read_b128 v[200:203], v190
	ds_read_b128 v[204:207], v190 offset:1024
	ds_read_b128 v[208:211], v190 offset:2048
	ds_read_b128 v[212:215], v190 offset:3072
	v_lshl_add_u64 v[190:191], s[18:19], 0, v[192:193]
	s_mov_b32 m0, s43
	v_lshl_add_u64 v[194:195], s[18:19], 0, v[132:133]
	global_load_lds_dwordx4 v[190:191], off
	s_add_i32 m0, s43, 0x2000
	s_nop 0
	global_load_lds_dwordx4 v[194:195], off
	s_barrier
	s_waitcnt lgkmcnt(0)
	s_waitcnt lgkmcnt(0)
	v_mfma_f32_16x16x32_bf16 v[116:119], v[200:203], v[158:161], v[116:119]
	v_mfma_f32_16x16x32_bf16 v[108:111], v[208:211], v[158:161], v[108:111]
	v_mfma_f32_16x16x32_bf16 v[100:103], v[200:203], v[166:169], v[100:103]
	v_mfma_f32_16x16x32_bf16 v[92:95], v[208:211], v[166:169], v[92:95]
	v_mfma_f32_16x16x32_bf16 v[84:87], v[200:203], v[174:177], v[84:87]
	v_mfma_f32_16x16x32_bf16 v[76:79], v[208:211], v[174:177], v[76:79]
	v_mfma_f32_16x16x32_bf16 v[68:71], v[200:203], v[182:185], v[68:71]
	v_mfma_f32_16x16x32_bf16 v[64:67], v[208:211], v[182:185], v[64:67]
	v_mfma_f32_16x16x32_bf16 v[116:119], v[204:207], v[162:165], v[116:119]
	v_mfma_f32_16x16x32_bf16 v[108:111], v[212:215], v[162:165], v[108:111]
	v_mfma_f32_16x16x32_bf16 v[100:103], v[204:207], v[170:173], v[100:103]
	v_mfma_f32_16x16x32_bf16 v[92:95], v[212:215], v[170:173], v[92:95]
	v_mfma_f32_16x16x32_bf16 v[84:87], v[204:207], v[178:181], v[84:87]
	v_mfma_f32_16x16x32_bf16 v[76:79], v[212:215], v[178:181], v[76:79]
	v_mfma_f32_16x16x32_bf16 v[68:71], v[204:207], v[186:189], v[68:71]
	v_mfma_f32_16x16x32_bf16 v[64:67], v[212:215], v[186:189], v[64:67]
	s_mov_b32 m0, s28
	v_lshl_add_u64 v[196:197], s[20:21], 0, v[128:129]
	s_barrier
	ds_read_b128 v[158:161], v145 offset:16384
	ds_read_b128 v[162:165], v145 offset:17408
	ds_read_b128 v[166:169], v145 offset:18432
	ds_read_b128 v[170:173], v145 offset:19456
	ds_read_b128 v[174:177], v145 offset:20480
	ds_read_b128 v[178:181], v145 offset:21504
	ds_read_b128 v[182:185], v145 offset:22528
	ds_read_b128 v[186:189], v145 offset:23552
	global_load_lds_dwordx4 v[196:197], off
	s_mov_b32 m0, s29
	v_lshl_add_u64 v[216:217], s[20:21], 0, v[130:131]
	global_load_lds_dwordx4 v[216:217], off
	s_barrier
	s_waitcnt lgkmcnt(0)
	s_waitcnt lgkmcnt(0)
	v_mfma_f32_16x16x32_bf16 v[60:63], v[138:141], v[158:161], v[60:63]
	v_mfma_f32_16x16x32_bf16 v[56:59], v[150:153], v[158:161], v[56:59]
	v_mfma_f32_16x16x32_bf16 v[48:51], v[138:141], v[166:169], v[48:51]
	v_mfma_f32_16x16x32_bf16 v[40:43], v[150:153], v[166:169], v[40:43]
	v_mfma_f32_16x16x32_bf16 v[32:35], v[138:141], v[174:177], v[32:35]
	v_mfma_f32_16x16x32_bf16 v[24:27], v[150:153], v[174:177], v[24:27]
	v_mfma_f32_16x16x32_bf16 v[16:19], v[138:141], v[182:185], v[16:19]
	v_mfma_f32_16x16x32_bf16 v[8:11], v[150:153], v[182:185], v[8:11]
	v_mfma_f32_16x16x32_bf16 v[60:63], v[146:149], v[162:165], v[60:63]
	v_mfma_f32_16x16x32_bf16 v[56:59], v[154:157], v[162:165], v[56:59]
	v_mfma_f32_16x16x32_bf16 v[48:51], v[146:149], v[170:173], v[48:51]
	v_mfma_f32_16x16x32_bf16 v[40:43], v[154:157], v[170:173], v[40:43]
	v_mfma_f32_16x16x32_bf16 v[32:35], v[146:149], v[178:181], v[32:35]
	v_mfma_f32_16x16x32_bf16 v[24:27], v[154:157], v[178:181], v[24:27]
	v_mfma_f32_16x16x32_bf16 v[16:19], v[146:149], v[186:189], v[16:19]
	v_mfma_f32_16x16x32_bf16 v[8:11], v[154:157], v[186:189], v[8:11]
	s_barrier
; #define PG8_STAGE(bufoff, gbase, voff) do { _Pragma("unroll") for (int _i = 0; _i < 2; ++_i) \
;         __builtin_amdgcn_global_load_lds((const unsigned*)((const char*)(gbase) + (voff)[_i]), (PG8_LAS unsigned*)(lds + (bufoff) + ldsw + _i * 8192), 16, 0, 0); } while (0)
; #define PG8_LDA(dst, b, h) do { _Pragma("unroll") for (int m = 0; m < 4; ++m) _Pragma("unroll") for (int k = 0; k < 2; ++k) dst[m][k] = *(const PG8_LAS bf16x8*)(lds + PG8_SA(b, h) + aoff + m * 2048 + k * 1024); } while (0)
; #define PG8_LDB(dst, b, h) do { _Pragma("unroll") for (int n = 0; n < 2; ++n) _Pragma("unroll") for (int k = 0; k < 2; ++k) dst[n][k] = *(const PG8_LAS bf16x8*)(lds + PG8_SB(b, h) + boff + n * 2048 + k * 1024); } while (0)
; #define PG8_MMA(ai, bj, At, Bt) do { __builtin_amdgcn_s_setprio(1); _Pragma("unroll") for (int m = 0; m < 4; ++m) _Pragma("unroll") for (int n = 0; n < 2; ++n) _Pragma("unroll") for (int k = 0; k < 2; ++k) \
;         acc[ai][bj][m][n] = __builtin_amdgcn_mfma_f32_16x16x32_bf16(Bt[n][k], At[m][k], acc[ai][bj][m][n], 0, 0, 0); __builtin_amdgcn_s_setprio(0); } while (0)
; #define PG8_WAIT_V(n) asm volatile("s_waitcnt vmcnt(" #n ")" ::: "memory")
; #define PG8_WAIT_L(n) asm volatile("s_waitcnt lgkmcnt(" #n ")" ::: "memory")
; #define PG8_BAR __builtin_amdgcn_s_barrier()
; #define PG8_SCHED __builtin_amdgcn_sched_barrier(0)
; template <class Epi, class Sched>
; __device__ __forceinline__ void gemm_phase(PG8_LAS unsigned char* lds, const Gemm g, const Sched& S, const Epi& E, int tid_in) {
;     ...
;             PG8_STAGE(PG8_SB(0, 1), b2 + hstep, voffB);
;             PG8_WAIT_V(6); PG8_BAR; PG8_MMA(1, 1, At, B1); PG8_BAR;
;             PG8_LDB(B0, 1, 0); PG8_SCHED; PG8_LDA(At, 1, 0); PG8_STAGE(PG8_SA(0, 1), a2 + hstep, voffA);
;             PG8_WAIT_L(8); PG8_BAR; PG8_WAIT_L(0); PG8_MMA(0, 0, At, B0); PG8_BAR; PG8_SCHED;
;             PG8_LDB(B1, 1, 1); PG8_STAGE(PG8_SB(1, 0), b3, voffB);
;             PG8_BAR; PG8_WAIT_L(0); PG8_MMA(0, 1, At, B1); PG8_BAR;
	s_add_u32 s44, s18, 0x40000
	s_addc_u32 s45, s19, 0
	s_add_i32 s43, s46, s27
	s_mov_b32 m0, s43
	v_lshl_add_u64 v[138:139], s[44:45], 0, v[192:193]
	global_load_lds_dwordx4 v[138:139], off
	s_add_i32 m0, s43, 0x2000
	v_lshl_add_u64 v[138:139], s[44:45], 0, v[132:133]
	global_load_lds_dwordx4 v[138:139], off
	s_waitcnt vmcnt(6)
	s_barrier
	v_mfma_f32_16x16x32_bf16 v[52:55], v[200:203], v[158:161], v[52:55]
	v_mfma_f32_16x16x32_bf16 v[44:47], v[208:211], v[158:161], v[44:47]
	v_mfma_f32_16x16x32_bf16 v[36:39], v[200:203], v[166:169], v[36:39]
	v_mfma_f32_16x16x32_bf16 v[28:31], v[208:211], v[166:169], v[28:31]
	v_mfma_f32_16x16x32_bf16 v[20:23], v[200:203], v[174:177], v[20:23]
	v_mfma_f32_16x16x32_bf16 v[12:15], v[208:211], v[174:177], v[12:15]
	v_mfma_f32_16x16x32_bf16 v[4:7], v[200:203], v[182:185], v[4:7]
	v_mfma_f32_16x16x32_bf16 v[0:3], v[208:211], v[182:185], v[0:3]
	v_mfma_f32_16x16x32_bf16 v[52:55], v[204:207], v[162:165], v[52:55]
	v_mfma_f32_16x16x32_bf16 v[44:47], v[212:215], v[162:165], v[44:47]
	v_mfma_f32_16x16x32_bf16 v[36:39], v[204:207], v[170:173], v[36:39]
	v_mfma_f32_16x16x32_bf16 v[28:31], v[212:215], v[170:173], v[28:31]
	v_mfma_f32_16x16x32_bf16 v[20:23], v[204:207], v[178:181], v[20:23]
	v_mfma_f32_16x16x32_bf16 v[12:15], v[212:215], v[178:181], v[12:15]
	v_mfma_f32_16x16x32_bf16 v[4:7], v[204:207], v[186:189], v[4:7]
	v_mfma_f32_16x16x32_bf16 v[0:3], v[212:215], v[186:189], v[0:3]
	s_add_i32 s43, 0, 0x18000
	v_add_u32_e32 v154, s43, v143
	s_barrier
	ds_read_b128 v[138:141], v154
	ds_read_b128 v[146:149], v154 offset:1024
	ds_read_b128 v[150:153], v154 offset:2048
	ds_read_b128 v[154:157], v154 offset:3072
	s_add_u32 s20, s20, 0x40000
	s_addc_u32 s21, s21, 0
	s_mov_b32 m0, s30
	v_lshl_add_u64 v[200:201], s[20:21], 0, v[128:129]
	ds_read_b128 v[158:161], v145 offset:32768
	ds_read_b128 v[162:165], v145 offset:33792
	ds_read_b128 v[166:169], v145 offset:34816
	ds_read_b128 v[170:173], v145 offset:35840
	ds_read_b128 v[174:177], v145 offset:36864
	ds_read_b128 v[178:181], v145 offset:37888
	ds_read_b128 v[182:185], v145 offset:38912
	ds_read_b128 v[186:189], v145 offset:39936
	global_load_lds_dwordx4 v[200:201], off
	s_mov_b32 m0, s31
	v_lshl_add_u64 v[200:201], s[20:21], 0, v[130:131]
	global_load_lds_dwordx4 v[200:201], off
	s_waitcnt lgkmcnt(8)
	s_barrier
	s_waitcnt lgkmcnt(0)
	s_waitcnt lgkmcnt(0)
	v_mfma_f32_16x16x32_bf16 v[124:127], v[138:141], v[158:161], v[124:127]
	v_mfma_f32_16x16x32_bf16 v[120:123], v[150:153], v[158:161], v[120:123]
	v_mfma_f32_16x16x32_bf16 v[112:115], v[138:141], v[166:169], v[112:115]
	v_mfma_f32_16x16x32_bf16 v[104:107], v[150:153], v[166:169], v[104:107]
	v_mfma_f32_16x16x32_bf16 v[96:99], v[138:141], v[174:177], v[96:99]
	v_mfma_f32_16x16x32_bf16 v[88:91], v[150:153], v[174:177], v[88:91]
	v_mfma_f32_16x16x32_bf16 v[80:83], v[138:141], v[182:185], v[80:83]
	v_mfma_f32_16x16x32_bf16 v[72:75], v[150:153], v[182:185], v[72:75]
	v_mfma_f32_16x16x32_bf16 v[124:127], v[146:149], v[162:165], v[124:127]
	v_mfma_f32_16x16x32_bf16 v[120:123], v[154:157], v[162:165], v[120:123]
	v_mfma_f32_16x16x32_bf16 v[112:115], v[146:149], v[170:173], v[112:115]
	v_mfma_f32_16x16x32_bf16 v[104:107], v[154:157], v[170:173], v[104:107]
	v_mfma_f32_16x16x32_bf16 v[96:99], v[146:149], v[178:181], v[96:99]
	v_mfma_f32_16x16x32_bf16 v[88:91], v[154:157], v[178:181], v[88:91]
	v_mfma_f32_16x16x32_bf16 v[80:83], v[146:149], v[186:189], v[80:83]
	v_mfma_f32_16x16x32_bf16 v[72:75], v[154:157], v[186:189], v[72:75]
	s_barrier
	s_add_i32 s20, 0, 0x1c000
	s_add_i32 s21, s43, s27
	v_add_u32_e32 v199, s20, v143
	v_lshl_add_u64 v[190:191], v[190:191], 0, s[74:75]
	s_mov_b32 m0, s21
	ds_read_b128 v[200:203], v199
	ds_read_b128 v[204:207], v199 offset:1024
	ds_read_b128 v[208:211], v199 offset:2048
	ds_read_b128 v[212:215], v199 offset:3072
	global_load_lds_dwordx4 v[190:191], off
	s_add_i32 m0, s21, 0x2000
	v_lshl_add_u64 v[190:191], v[194:195], 0, s[74:75]
	global_load_lds_dwordx4 v[190:191], off
	s_barrier
; __device__ __forceinline__ unsigned cvt_pk_bf16(float lo, float hi) { unsigned r; asm volatile("s_nop 0\n\tv_cvt_pk_bf16_f32 %0, %1, %2\n\ts_nop 1" : "=v"(r) : "v"(lo), "v"(hi)); return r; }
; #define PG8_STAGE(bufoff, gbase, voff) do { _Pragma("unroll") for (int _i = 0; _i < 2; ++_i) \
;         __builtin_amdgcn_global_load_lds((const unsigned*)((const char*)(gbase) + (voff)[_i]), (PG8_LAS unsigned*)(lds + (bufoff) + ldsw + _i * 8192), 16, 0, 0); } while (0)
; #define PG8_LDA(dst, b, h) do { _Pragma("unroll") for (int m = 0; m < 4; ++m) _Pragma("unroll") for (int k = 0; k < 2; ++k) dst[m][k] = *(const PG8_LAS bf16x8*)(lds + PG8_SA(b, h) + aoff + m * 2048 + k * 1024); } while (0)
; #define PG8_WAIT_V(n) asm volatile("s_waitcnt vmcnt(" #n ")" ::: "memory")
; #define PG8_WAIT_L(n) asm volatile("s_waitcnt lgkmcnt(" #n ")" ::: "memory")
; template <class Epi, class Sched>
; __device__ __forceinline__ void gemm_phase(PG8_LAS unsigned char* lds, const Gemm g, const Sched& S, const Epi& E, int tid_in) {
;     ...
;             PG8_WAIT_L(8); PG8_BAR; PG8_WAIT_L(0); PG8_MMA(0, 0, At, B0); PG8_BAR; PG8_SCHED;
;             PG8_LDB(B1, 1, 1); PG8_STAGE(PG8_SB(1, 0), b3, voffB);
;             PG8_BAR; PG8_WAIT_L(0); PG8_MMA(0, 1, At, B1); PG8_BAR;
;             PG8_LDA(At, 1, 1); PG8_STAGE(PG8_SA(1, 0), a3, voffA);
;             PG8_BAR; PG8_WAIT_L(0); PG8_MMA(1, 0, At, B0); PG8_BAR; PG8_SCHED;
;             PG8_STAGE(PG8_SB(1, 1), b3 + hstep, voffB);
;             PG8_WAIT_V(6); PG8_BAR; PG8_MMA(1, 1, At, B1); PG8_BAR;
;     __device__ __forceinline__ void operator()(f32x4 (&acc)[2][2][4][2], const Unit& u, int wr, int wc, int fr, int fq) const {
;         const int row0 = u.pm * 256 + wr * 64 + fr, col0 = u.pn * 256 + wc * 32 + 8 * fq;
; #pragma unroll
;         for (int ai = 0; ai < 2; ++ai)
; #pragma unroll
;             for (int m = 0; m < 4; ++m) { bf16_t* rowp = O + (size_t)(row0 + ai * 128 + m * 16) * ldc + col0;
; #pragma unroll
;                 for (int bj = 0; bj < 2; ++bj) { if (u.pn * 256 + bj * 128 + wc * 32 >= 5184) continue;
;                     const f32x4 v0 = acc[ai][bj][m][0], v1 = acc[ai][bj][m][1];
;                     u32x4 w; w.x = cvt_pk_bf16(v0[0], v0[1]); w.y = cvt_pk_bf16(v0[2], v0[3]); w.z = cvt_pk_bf16(v1[0], v1[1]); w.w = cvt_pk_bf16(v1[2], v1[3]);
;                     *(u32x4*)(rowp + bj * 128) = w; } }
	s_waitcnt lgkmcnt(0)
	s_waitcnt lgkmcnt(0)
	v_mfma_f32_16x16x32_bf16 v[116:119], v[200:203], v[158:161], v[116:119]
	v_mfma_f32_16x16x32_bf16 v[108:111], v[208:211], v[158:161], v[108:111]
	v_mfma_f32_16x16x32_bf16 v[100:103], v[200:203], v[166:169], v[100:103]
	v_mfma_f32_16x16x32_bf16 v[92:95], v[208:211], v[166:169], v[92:95]
	v_mfma_f32_16x16x32_bf16 v[84:87], v[200:203], v[174:177], v[84:87]
	v_mfma_f32_16x16x32_bf16 v[76:79], v[208:211], v[174:177], v[76:79]
	v_mfma_f32_16x16x32_bf16 v[68:71], v[200:203], v[182:185], v[68:71]
	v_mfma_f32_16x16x32_bf16 v[64:67], v[208:211], v[182:185], v[64:67]
	v_mfma_f32_16x16x32_bf16 v[116:119], v[204:207], v[162:165], v[116:119]
	v_mfma_f32_16x16x32_bf16 v[108:111], v[212:215], v[162:165], v[108:111]
	v_mfma_f32_16x16x32_bf16 v[100:103], v[204:207], v[170:173], v[100:103]
	v_mfma_f32_16x16x32_bf16 v[92:95], v[212:215], v[170:173], v[92:95]
	v_mfma_f32_16x16x32_bf16 v[84:87], v[204:207], v[178:181], v[84:87]
	v_mfma_f32_16x16x32_bf16 v[76:79], v[212:215], v[178:181], v[76:79]
	v_mfma_f32_16x16x32_bf16 v[68:71], v[204:207], v[186:189], v[68:71]
	v_mfma_f32_16x16x32_bf16 v[64:67], v[212:215], v[186:189], v[64:67]
	s_mov_b32 m0, s36
	v_lshl_add_u64 v[190:191], v[196:197], 0, s[74:75]
	s_barrier
	ds_read_b128 v[158:161], v145 offset:49152
	ds_read_b128 v[162:165], v145 offset:50176
	ds_read_b128 v[166:169], v145 offset:51200
	ds_read_b128 v[170:173], v145 offset:52224
	ds_read_b128 v[174:177], v145 offset:53248
	ds_read_b128 v[178:181], v145 offset:54272
	ds_read_b128 v[182:185], v145 offset:55296
	ds_read_b128 v[186:189], v145 offset:56320
	global_load_lds_dwordx4 v[190:191], off
	s_mov_b32 m0, s37
	v_lshl_add_u64 v[190:191], v[216:217], 0, s[74:75]
	global_load_lds_dwordx4 v[190:191], off
	s_barrier
	s_waitcnt lgkmcnt(0)
	s_waitcnt lgkmcnt(0)
	v_mfma_f32_16x16x32_bf16 v[60:63], v[138:141], v[158:161], v[60:63]
	v_mfma_f32_16x16x32_bf16 v[56:59], v[150:153], v[158:161], v[56:59]
	v_mfma_f32_16x16x32_bf16 v[48:51], v[138:141], v[166:169], v[48:51]
	v_mfma_f32_16x16x32_bf16 v[40:43], v[150:153], v[166:169], v[40:43]
	v_mfma_f32_16x16x32_bf16 v[32:35], v[138:141], v[174:177], v[32:35]
	v_mfma_f32_16x16x32_bf16 v[24:27], v[150:153], v[174:177], v[24:27]
	v_mfma_f32_16x16x32_bf16 v[16:19], v[138:141], v[182:185], v[16:19]
	v_mfma_f32_16x16x32_bf16 v[8:11], v[150:153], v[182:185], v[8:11]
	v_mfma_f32_16x16x32_bf16 v[60:63], v[146:149], v[162:165], v[60:63]
	v_mfma_f32_16x16x32_bf16 v[56:59], v[154:157], v[162:165], v[56:59]
	v_mfma_f32_16x16x32_bf16 v[48:51], v[146:149], v[170:173], v[48:51]
	v_mfma_f32_16x16x32_bf16 v[40:43], v[154:157], v[170:173], v[40:43]
	v_mfma_f32_16x16x32_bf16 v[32:35], v[146:149], v[178:181], v[32:35]
	v_mfma_f32_16x16x32_bf16 v[24:27], v[154:157], v[178:181], v[24:27]
	v_mfma_f32_16x16x32_bf16 v[16:19], v[146:149], v[186:189], v[16:19]
	v_mfma_f32_16x16x32_bf16 v[8:11], v[154:157], v[186:189], v[8:11]
	s_barrier
	s_add_u32 s18, s18, 0x40080
	s_addc_u32 s19, s19, 0
	s_add_i32 s20, s20, s27
	s_mov_b32 m0, s20
	v_lshl_add_u64 v[138:139], s[18:19], 0, v[192:193]
	global_load_lds_dwordx4 v[138:139], off
	s_add_i32 m0, s20, 0x2000
	v_lshl_add_u64 v[138:139], s[18:19], 0, v[132:133]
	global_load_lds_dwordx4 v[138:139], off
	s_waitcnt vmcnt(6)
	s_barrier
	v_mfma_f32_16x16x32_bf16 v[52:55], v[200:203], v[158:161], v[52:55]
	v_mfma_f32_16x16x32_bf16 v[44:47], v[208:211], v[158:161], v[44:47]
	v_mfma_f32_16x16x32_bf16 v[36:39], v[200:203], v[166:169], v[36:39]
	v_mfma_f32_16x16x32_bf16 v[28:31], v[208:211], v[166:169], v[28:31]
	v_mfma_f32_16x16x32_bf16 v[20:23], v[200:203], v[174:177], v[20:23]
	v_mfma_f32_16x16x32_bf16 v[12:15], v[208:211], v[174:177], v[12:15]
	v_mfma_f32_16x16x32_bf16 v[4:7], v[200:203], v[182:185], v[4:7]
	v_mfma_f32_16x16x32_bf16 v[0:3], v[208:211], v[182:185], v[0:3]
	v_mfma_f32_16x16x32_bf16 v[52:55], v[204:207], v[162:165], v[52:55]
	v_mfma_f32_16x16x32_bf16 v[44:47], v[212:215], v[162:165], v[44:47]
	v_mfma_f32_16x16x32_bf16 v[36:39], v[204:207], v[170:173], v[36:39]
	v_mfma_f32_16x16x32_bf16 v[28:31], v[212:215], v[170:173], v[28:31]
	v_mfma_f32_16x16x32_bf16 v[20:23], v[204:207], v[178:181], v[20:23]
	v_mfma_f32_16x16x32_bf16 v[12:15], v[212:215], v[178:181], v[12:15]
	v_mfma_f32_16x16x32_bf16 v[4:7], v[204:207], v[186:189], v[4:7]
	v_mfma_f32_16x16x32_bf16 v[0:3], v[212:215], v[186:189], v[0:3]
	s_add_i32 s42, s42, 2
	s_add_u32 s16, s16, 0x100
	s_addc_u32 s17, s17, 0
	s_add_u32 s40, s40, 0x100
	s_addc_u32 s41, s41, 0
	s_cmp_gt_u32 s42, 13
	s_barrier
	s_cbranch_scc0 .LBB0_696
	s_lshl_b32 s4, s4, 8
	v_lshl_add_u32 v146, s6, 8, v142
	v_or_b32_e32 v138, s4, v144
	s_or_b32 s4, s4, s33
	v_mov_b64_e32 v[140:141], s[0:1]
	v_ashrrev_i32_e32 v139, 31, v138
	v_mad_i64_i32 v[140:141], s[6:7], v146, s78, v[140:141]
	s_cmpk_lt_i32 s4, 0x1440
	s_cselect_b64 s[6:7], -1, 0
	s_cmpk_gt_i32 s4, 0x143f
	v_lshl_add_u64 v[140:141], v[138:139], 1, v[140:141]
	s_cbranch_scc1 .LBB0_699
	v_cvt_pk_bf16_f32 v124, v124, v125
	v_cvt_pk_bf16_f32 v125, v126, v127
	v_cvt_pk_bf16_f32 v126, v120, v121
	v_cvt_pk_bf16_f32 v127, v122, v123
	s_nop 1
	global_store_dwordx4 v[140:141], v[124:127], off
